# de-serialized latency-bound load chains: HGRN pass3 and pass1 (all ushort gathers hoisted, counted waits), sample-DSA V gather batched 8 loads in flight; arithmetic unchanged
# speedup vs baseline: 1.0753x; 1.0327x over previous
;     template <class F> __device__ __forceinline__ void run(const F& f, long n) { gs(*c, f, n); xcd_barrier(c->bar); }
; __device__ __forceinline__ void pass1(const bf16* ZB, const float* lbl, const Bufs& B, LAS unsigned char* shm, int G, int tid) {
;     ...
;     for (int u = (int)blockIdx.x; u < NUNIT; u += G) { const int n = u % NCH, bh = u / NCH, h = bh % HGH, b = bh / HGH; const size_t row0 = (size_t)b * SEQ + 64 * n;
;         const bf16* zr = ZB + (row0 + 8 * seg) * ZLD + 64 * h + k; const float lbk = lbl[64 * h + k];
;         float bl[8], kkv[8]; float run = 0.f;
; #pragma unroll
;         for (int i = 0; i < 8; ++i) { const float gf = bf2f(zr[(size_t)i * ZLD + O_F]); const float sg = 1.0f / (1.0f + __expf(-gf)); const float f = lbk + (1.f - lbk) * sg; kkv[i] = (1.f - lbk) * (1.f - sg); run += __logf(f); bl[i] = run; }
.LBB0_541:
	s_ashr_i32 s47, s46, 31
	s_lshr_b32 s0, s47, 26
	s_add_i32 s0, s46, s0
	s_ashr_i32 s2, s0, 6
	s_lshr_b32 s0, s2, 30
	s_add_i32 s0, s2, s0
	s_and_b32 s0, s0, 0x3fffffc
	s_sub_i32 s3, s2, s0
	s_lshr_b32 s0, s47, 24
	s_add_i32 s0, s46, s0
	s_ashr_i32 s0, s0, 8
	s_lshl_b32 s2, s2, 12
	s_ashr_i32 s1, s0, 31
	s_sub_i32 s2, s17, s2
	s_lshl_b64 s[0:1], s[0:1], 12
	s_ashr_i32 s19, s2, 31
	s_add_u32 s18, s0, s2
	s_addc_u32 s19, s1, s19
	s_add_u32 s62, s18, s76
	s_addc_u32 s63, s19, s77
	s_lshl_b64 s[0:1], s[62:63], 11
	s_add_u32 s0, s64, s0
	s_addc_u32 s1, s65, s1
	s_lshl_b32 s72, s3, 6
	s_ashr_i32 s73, s72, 31
	s_lshl_b64 s[2:3], s[72:73], 1
	v_or_b32_e32 v2, s72, v18
	s_add_u32 s74, s0, s2
	v_ashrrev_i32_e32 v3, 31, v2
	s_addc_u32 s75, s1, s3
	v_lshl_add_u64 v[2:3], v[2:3], 2, s[44:45]
	global_load_dword v14, v[2:3], off
	v_add_u32_e32 v66, 0x1000, v214
	v_add_u32_e32 v67, 0x2000, v214
	v_add_u32_e32 v68, 0x3000, v214
	global_load_ushort v84, v214, s[74:75] offset:512
	global_load_ushort v85, v214, s[74:75] offset:2560
	global_load_ushort v86, v66, s[74:75] offset:512
	global_load_ushort v87, v66, s[74:75] offset:2560
	global_load_ushort v88, v67, s[74:75] offset:512
	global_load_ushort v89, v67, s[74:75] offset:2560
	global_load_ushort v90, v68, s[74:75] offset:512
	global_load_ushort v91, v68, s[74:75] offset:2560
	global_load_ushort v92, v214, s[74:75]
	global_load_ushort v100, v214, s[74:75] offset:1024
	global_load_ushort v93, v214, s[74:75] offset:2048
	global_load_ushort v101, v214, s[74:75] offset:3072
	global_load_ushort v94, v66, s[74:75]
	global_load_ushort v102, v66, s[74:75] offset:1024
	global_load_ushort v95, v66, s[74:75] offset:2048
	global_load_ushort v103, v66, s[74:75] offset:3072
	global_load_ushort v96, v67, s[74:75]
	global_load_ushort v104, v67, s[74:75] offset:1024
	global_load_ushort v97, v67, s[74:75] offset:2048
	global_load_ushort v105, v67, s[74:75] offset:3072
	global_load_ushort v98, v68, s[74:75]
	global_load_ushort v106, v68, s[74:75] offset:1024
	global_load_ushort v99, v68, s[74:75] offset:2048
	global_load_ushort v107, v68, s[74:75] offset:3072
	s_mov_b32 s78, 0x800000
	s_mov_b32 s79, 0x3f317217
	s_mov_b32 s82, 0x7f800000
	v_lshl_add_u64 v[8:9], s[74:75], 0, v[214:215]
	v_mov_b32_e32 v13, 0
	s_waitcnt vmcnt(24)
	v_sub_f32_e32 v2, 1.0, v14
	s_waitcnt vmcnt(23)
	v_mov_b32_e32 v3, v84
	v_lshlrev_b32_e32 v3, 16, v3
	v_mul_f32_e32 v3, 0xbfb8aa3b, v3
	v_exp_f32_e32 v3, v3
	s_nop 0
	v_add_f32_e32 v3, 1.0, v3
	v_div_scale_f32 v4, s[0:1], v3, v3, 1.0
	v_rcp_f32_e32 v5, v4
	s_nop 0
	v_fma_f32 v6, -v4, v5, 1.0
	v_fmac_f32_e32 v5, v6, v5
	v_div_scale_f32 v6, vcc, 1.0, v3, 1.0
	v_mul_f32_e32 v7, v6, v5
	v_fma_f32 v10, -v4, v7, v6
	v_fmac_f32_e32 v7, v10, v5
	v_fma_f32 v4, -v4, v7, v6
	v_div_fmas_f32 v4, v4, v5, v7
	v_div_fixup_f32 v3, v4, v3, 1.0
	v_fma_f32 v4, v2, v3, v14
	v_cmp_gt_f32_e32 vcc, s78, v4
	s_nop 1
	v_cndmask_b32_e64 v5, 0, 32, vcc
	v_ldexp_f32 v4, v4, v5
	v_log_f32_e32 v4, v4
	s_nop 0
	v_mul_f32_e32 v5, 0x3f317217, v4
	v_fma_f32 v5, v4, s79, -v5
	v_fmac_f32_e32 v5, 0x3377d1cf, v4
	v_fmac_f32_e32 v5, 0x3f317217, v4
	v_cmp_lt_f32_e64 s[0:1], |v4|, s82
	s_nop 1
	v_cndmask_b32_e64 v4, v4, v5, s[0:1]
	v_cndmask_b32_e32 v5, 0, v241, vcc
	v_sub_f32_e32 v4, v4, v5
	v_add_f32_e32 v12, 0, v4
	s_waitcnt vmcnt(22)
	v_mov_b32_e32 v4, v85
	v_lshlrev_b32_e32 v4, 16, v4
	v_mul_f32_e32 v4, 0xbfb8aa3b, v4
	v_exp_f32_e32 v4, v4
	s_nop 0
	v_add_f32_e32 v4, 1.0, v4
	v_div_scale_f32 v5, s[0:1], v4, v4, 1.0
	v_rcp_f32_e32 v6, v5
	s_nop 0
	v_fma_f32 v7, -v5, v6, 1.0
	v_fmac_f32_e32 v6, v7, v6
	v_div_scale_f32 v7, vcc, 1.0, v4, 1.0
	v_mul_f32_e32 v10, v7, v6
	v_fma_f32 v11, -v5, v10, v7
	v_fmac_f32_e32 v10, v11, v6
	v_fma_f32 v5, -v5, v10, v7
	v_div_fmas_f32 v5, v5, v6, v10
	v_div_fixup_f32 v15, v5, v4, 1.0
	v_fma_f32 v4, v2, v15, v14
	v_cmp_gt_f32_e32 vcc, s78, v4
	s_nop 1
	v_cndmask_b32_e64 v5, 0, 32, vcc
	v_ldexp_f32 v4, v4, v5
	v_log_f32_e32 v4, v4
	s_nop 0
	v_mul_f32_e32 v5, 0x3f317217, v4
	v_fma_f32 v5, v4, s79, -v5
	v_fmac_f32_e32 v5, 0x3377d1cf, v4
	v_fmac_f32_e32 v5, 0x3f317217, v4
	v_cmp_lt_f32_e64 s[0:1], |v4|, s82
	s_nop 1
	v_cndmask_b32_e64 v4, v4, v5, s[0:1]
	v_cndmask_b32_e32 v5, 0, v241, vcc
	v_add_co_u32_e32 v6, vcc, s83, v8
	v_sub_f32_e32 v4, v4, v5
	s_nop 0
	v_addc_co_u32_e32 v7, vcc, 0, v9, vcc
	v_add_f32_e32 v16, v12, v4
	s_waitcnt vmcnt(21)
	v_mov_b32_e32 v4, v86
	v_lshlrev_b32_e32 v4, 16, v4
	v_mul_f32_e32 v4, 0xbfb8aa3b, v4
	v_exp_f32_e32 v4, v4
	s_nop 0
	v_add_f32_e32 v4, 1.0, v4
	v_div_scale_f32 v5, s[0:1], v4, v4, 1.0
	v_rcp_f32_e32 v10, v5
	s_nop 0
	v_fma_f32 v11, -v5, v10, 1.0
	v_fmac_f32_e32 v10, v11, v10
	v_div_scale_f32 v11, vcc, 1.0, v4, 1.0
	v_mul_f32_e32 v17, v11, v10
	v_fma_f32 v29, -v5, v17, v11
	v_fmac_f32_e32 v17, v29, v10
	v_fma_f32 v5, -v5, v17, v11
	v_div_fmas_f32 v5, v5, v10, v17
	v_div_fixup_f32 v17, v5, v4, 1.0
	v_fma_f32 v4, v2, v17, v14
	v_cmp_gt_f32_e32 vcc, s78, v4
	s_nop 1
	v_cndmask_b32_e64 v5, 0, 32, vcc
	v_ldexp_f32 v4, v4, v5
	v_log_f32_e32 v4, v4
	s_nop 0
	v_mul_f32_e32 v5, 0x3f317217, v4
	v_fma_f32 v5, v4, s79, -v5
	v_fmac_f32_e32 v5, 0x3377d1cf, v4
	v_fmac_f32_e32 v5, 0x3f317217, v4
	v_cmp_lt_f32_e64 s[0:1], |v4|, s82
	s_nop 1
	v_cndmask_b32_e64 v4, v4, v5, s[0:1]
	v_cndmask_b32_e32 v5, 0, v241, vcc
	v_sub_f32_e32 v4, v4, v5
	v_add_f32_e32 v29, v16, v4
	s_waitcnt vmcnt(20)
;     template <class F> __device__ __forceinline__ void run(const F& f, long n) { gs(*c, f, n); xcd_barrier(c->bar); }
; __device__ __forceinline__ void pass1(const bf16* ZB, const float* lbl, const Bufs& B, LAS unsigned char* shm, int G, int tid) {
;     ...
;         for (int i = 0; i < 8; ++i) { const float gf = bf2f(zr[(size_t)i * ZLD + O_F]); const float sg = 1.0f / (1.0f + __expf(-gf)); const float f = lbk + (1.f - lbk) * sg; kkv[i] = (1.f - lbk) * (1.f - sg); run += __logf(f); bl[i] = run; }
;         SEGT[seg * 64 + k] = run;
;         __syncthreads();
;         { float off = 0.f;
; #pragma unroll
;           for (int s = 0; s < 7; ++s) off += (s < seg) ? SEGT[s * 64 + k] : 0.f;
	v_mov_b32_e32 v4, v87
	v_lshlrev_b32_e32 v4, 16, v4
	v_mul_f32_e32 v4, 0xbfb8aa3b, v4
	v_exp_f32_e32 v4, v4
	s_nop 0
	v_add_f32_e32 v4, 1.0, v4
	v_div_scale_f32 v5, s[0:1], v4, v4, 1.0
	v_rcp_f32_e32 v10, v5
	s_nop 0
	v_fma_f32 v11, -v5, v10, 1.0
	v_fmac_f32_e32 v10, v11, v10
	v_div_scale_f32 v11, vcc, 1.0, v4, 1.0
	v_mul_f32_e32 v47, v11, v10
	v_fma_f32 v48, -v5, v47, v11
	v_fmac_f32_e32 v47, v48, v10
	v_fma_f32 v5, -v5, v47, v11
	v_div_fmas_f32 v5, v5, v10, v47
	v_div_fixup_f32 v47, v5, v4, 1.0
	v_fma_f32 v4, v2, v47, v14
	v_cmp_gt_f32_e32 vcc, s78, v4
	s_nop 1
	v_cndmask_b32_e64 v5, 0, 32, vcc
	v_ldexp_f32 v4, v4, v5
	v_log_f32_e32 v4, v4
	s_nop 0
	v_mul_f32_e32 v5, 0x3f317217, v4
	v_fma_f32 v5, v4, s79, -v5
	v_fmac_f32_e32 v5, 0x3377d1cf, v4
	v_fmac_f32_e32 v5, 0x3f317217, v4
	v_cmp_lt_f32_e64 s[0:1], |v4|, s82
	s_nop 1
	v_cndmask_b32_e64 v4, v4, v5, s[0:1]
	v_cndmask_b32_e32 v5, 0, v241, vcc
	v_sub_f32_e32 v4, v4, v5
	s_movk_i32 s0, 0x2000
	v_add_f32_e32 v48, v29, v4
	v_add_co_u32_e32 v4, vcc, s0, v8
	s_nop 1
	v_addc_co_u32_e32 v5, vcc, 0, v9, vcc
	s_waitcnt vmcnt(19)
	v_mov_b32_e32 v10, v88
	v_lshlrev_b32_e32 v10, 16, v10
	v_mul_f32_e32 v10, 0xbfb8aa3b, v10
	v_exp_f32_e32 v10, v10
	s_nop 0
	v_add_f32_e32 v10, 1.0, v10
	v_div_scale_f32 v11, s[0:1], v10, v10, 1.0
	v_rcp_f32_e32 v49, v11
	s_nop 0
	v_fma_f32 v50, -v11, v49, 1.0
	v_fmac_f32_e32 v49, v50, v49
	v_div_scale_f32 v50, vcc, 1.0, v10, 1.0
	v_mul_f32_e32 v51, v50, v49
	v_fma_f32 v52, -v11, v51, v50
	v_fmac_f32_e32 v51, v52, v49
	v_fma_f32 v11, -v11, v51, v50
	v_div_fmas_f32 v11, v11, v49, v51
	v_div_fixup_f32 v49, v11, v10, 1.0
	v_fma_f32 v10, v2, v49, v14
	v_cmp_gt_f32_e32 vcc, s78, v10
	s_nop 1
	v_cndmask_b32_e64 v11, 0, 32, vcc
	v_ldexp_f32 v10, v10, v11
	v_log_f32_e32 v10, v10
	s_nop 0
	v_mul_f32_e32 v11, 0x3f317217, v10
	v_fma_f32 v11, v10, s79, -v11
	v_fmac_f32_e32 v11, 0x3377d1cf, v10
	v_fmac_f32_e32 v11, 0x3f317217, v10
	v_cmp_lt_f32_e64 s[0:1], |v10|, s82
	s_nop 1
	v_cndmask_b32_e64 v10, v10, v11, s[0:1]
	v_cndmask_b32_e32 v11, 0, v241, vcc
	v_sub_f32_e32 v10, v10, v11
	v_add_f32_e32 v50, v48, v10
	s_waitcnt vmcnt(18)
	v_mov_b32_e32 v10, v89
	v_lshlrev_b32_e32 v10, 16, v10
	v_mul_f32_e32 v10, 0xbfb8aa3b, v10
	v_exp_f32_e32 v10, v10
	s_nop 0
	v_add_f32_e32 v10, 1.0, v10
	v_div_scale_f32 v11, s[0:1], v10, v10, 1.0
	v_rcp_f32_e32 v51, v11
	s_nop 0
	v_fma_f32 v52, -v11, v51, 1.0
	v_fmac_f32_e32 v51, v52, v51
	v_div_scale_f32 v52, vcc, 1.0, v10, 1.0
	v_mul_f32_e32 v53, v52, v51
	v_fma_f32 v54, -v11, v53, v52
	v_fmac_f32_e32 v53, v54, v51
	v_fma_f32 v11, -v11, v53, v52
	v_div_fmas_f32 v11, v11, v51, v53
	v_div_fixup_f32 v51, v11, v10, 1.0
	v_fma_f32 v10, v2, v51, v14
	v_cmp_gt_f32_e32 vcc, s78, v10
	s_nop 1
	v_cndmask_b32_e64 v11, 0, 32, vcc
	v_ldexp_f32 v10, v10, v11
	v_log_f32_e32 v10, v10
	s_nop 0
	v_mul_f32_e32 v11, 0x3f317217, v10
	v_fma_f32 v11, v10, s79, -v11
	v_fmac_f32_e32 v11, 0x3377d1cf, v10
	v_fmac_f32_e32 v11, 0x3f317217, v10
	v_cmp_lt_f32_e64 s[0:1], |v10|, s82
	s_nop 1
	v_cndmask_b32_e64 v10, v10, v11, s[0:1]
	v_cndmask_b32_e32 v11, 0, v241, vcc
	v_sub_f32_e32 v10, v10, v11
	s_movk_i32 s0, 0x3000
	v_add_f32_e32 v52, v50, v10
	v_add_co_u32_e32 v10, vcc, s0, v8
	s_nop 1
	v_addc_co_u32_e32 v11, vcc, 0, v9, vcc
	s_waitcnt vmcnt(17)
	v_mov_b32_e32 v53, v90
	v_lshlrev_b32_e32 v53, 16, v53
	v_mul_f32_e32 v53, 0xbfb8aa3b, v53
	v_exp_f32_e32 v53, v53
	s_nop 0
	v_add_f32_e32 v53, 1.0, v53
	v_div_scale_f32 v54, s[0:1], v53, v53, 1.0
	v_rcp_f32_e32 v55, v54
	s_nop 0
	v_fma_f32 v56, -v54, v55, 1.0
	v_fmac_f32_e32 v55, v56, v55
	v_div_scale_f32 v56, vcc, 1.0, v53, 1.0
	v_mul_f32_e32 v57, v56, v55
	v_fma_f32 v58, -v54, v57, v56
	v_fmac_f32_e32 v57, v58, v55
	v_fma_f32 v54, -v54, v57, v56
	v_div_fmas_f32 v54, v54, v55, v57
	v_div_fixup_f32 v53, v54, v53, 1.0
	v_fma_f32 v54, v2, v53, v14
	v_cmp_gt_f32_e32 vcc, s78, v54
	s_nop 1
	v_cndmask_b32_e64 v55, 0, 32, vcc
	v_ldexp_f32 v54, v54, v55
	v_log_f32_e32 v54, v54
	s_nop 0
	v_mul_f32_e32 v55, 0x3f317217, v54
	v_fma_f32 v55, v54, s79, -v55
	v_fmac_f32_e32 v55, 0x3377d1cf, v54
	v_fmac_f32_e32 v55, 0x3f317217, v54
	v_cmp_lt_f32_e64 s[0:1], |v54|, s82
	s_nop 1
	v_cndmask_b32_e64 v54, v54, v55, s[0:1]
	v_cndmask_b32_e32 v55, 0, v241, vcc
	v_sub_f32_e32 v54, v54, v55
	v_add_f32_e32 v54, v52, v54
	s_waitcnt vmcnt(16)
	v_mov_b32_e32 v55, v91
	v_lshlrev_b32_e32 v55, 16, v55
	v_mul_f32_e32 v55, 0xbfb8aa3b, v55
	v_exp_f32_e32 v55, v55
	s_nop 0
	v_add_f32_e32 v55, 1.0, v55
	v_div_scale_f32 v56, s[0:1], v55, v55, 1.0
	v_rcp_f32_e32 v57, v56
	s_nop 0
	v_fma_f32 v58, -v56, v57, 1.0
	v_fmac_f32_e32 v57, v58, v57
	v_div_scale_f32 v58, vcc, 1.0, v55, 1.0
	v_mul_f32_e32 v59, v58, v57
	v_fma_f32 v60, -v56, v59, v58
	v_fmac_f32_e32 v59, v60, v57
	v_fma_f32 v56, -v56, v59, v58
	v_div_fmas_f32 v56, v56, v57, v59
	v_div_fixup_f32 v57, v56, v55, 1.0
	v_fmac_f32_e32 v14, v2, v57
	v_cmp_gt_f32_e32 vcc, s78, v14
	s_nop 1
	v_cndmask_b32_e64 v55, 0, 32, vcc
	v_ldexp_f32 v14, v14, v55
	v_log_f32_e32 v14, v14
	s_nop 0
	v_mul_f32_e32 v55, 0x3f317217, v14
	v_fma_f32 v55, v14, s79, -v55
	v_fmac_f32_e32 v55, 0x3377d1cf, v14
	v_fmac_f32_e32 v55, 0x3f317217, v14
	v_cmp_lt_f32_e64 s[0:1], |v14|, s82
	s_nop 1
	v_cndmask_b32_e64 v14, v14, v55, s[0:1]
	v_cndmask_b32_e32 v55, 0, v241, vcc
	v_sub_f32_e32 v14, v14, v55
	v_add_f32_e32 v14, v54, v14
	s_andn2_b64 vcc, exec, s[58:59]
	v_mov_b32_e32 v55, 0
	ds_write_b32 v30, v14
	s_waitcnt lgkmcnt(0)
	s_barrier
	s_cbranch_vccnz .LBB0_543
	ds_read_b32 v55, v19
	s_waitcnt lgkmcnt(0)
	v_add_f32_e32 v55, 0, v55

; __device__ __forceinline__ unsigned f2bf(float f) { unsigned u = __builtin_bit_cast(unsigned, f); return (u + 0x7fffu + ((u >> 16) & 1u)) >> 16; }
; __device__ __forceinline__ float cexp(float x) { return __expf(fminf(x, 80.f)); }
; __device__ __forceinline__ void pass1(const bf16* ZB, const float* lbl, const Bufs& B, LAS unsigned char* shm, int G, int tid) {
;     ...
;         { const float rr = RB[k], b63 = B63[k];
; #pragma unroll
;           for (int i = 0; i < 8; ++i) { const int t = 8 * seg + i; const float q = bf2f(zr[(size_t)i * ZLD + O_Q]); const bf16 vraw = zr[(size_t)i * ZLD + O_I];
;               QT[t * RS + k] = (bf16)f2bf(q * cexp(bl[i] - rr)); KT[t * RS + k] = (bf16)f2bf(kkv[i] * cexp(rr - bl[i])); K2T[k * RS + t] = (bf16)f2bf(kkv[i] * cexp(b63 - bl[i])); VT[k * RS + t] = vraw;
;               B.QE[(row0 + t) * 256 + 64 * h + k] = (bf16)f2bf(q * cexp(bl[i])); }
;           if (seg == 0) B.DEC[(size_t)u * 64 + k] = cexp(b63); }
.LBB0_554:
	v_sub_f32_e32 v3, 1.0, v3
	v_add_f32_e32 v60, v16, v13
	v_add_f32_e32 v16, v54, v13
	v_mul_f32_e32 v54, v2, v3
	v_sub_f32_e32 v3, 1.0, v15
	v_mul_f32_e32 v61, v2, v3
	v_sub_f32_e32 v3, 1.0, v17
	v_add_f32_e32 v56, v29, v13
	v_add_f32_e32 v29, v52, v13
	v_mul_f32_e32 v52, v2, v3
	v_sub_f32_e32 v3, 1.0, v47
	v_add_f32_e32 v55, v48, v13
	v_add_f32_e32 v48, v50, v13
	v_mul_f32_e32 v50, v2, v3
	v_sub_f32_e32 v3, 1.0, v49
	v_mul_f32_e32 v49, v2, v3
	v_sub_f32_e32 v3, 1.0, v51
	s_waitcnt lgkmcnt(0)
	s_barrier
	s_waitcnt vmcnt(0)
	v_mov_b32_e32 v51, v92
	v_mul_f32_e32 v47, v2, v3
	v_sub_f32_e32 v3, 1.0, v53
	v_mov_b32_e32 v53, v100
	v_mul_f32_e32 v17, v2, v3
	v_sub_f32_e32 v3, 1.0, v57
	v_mul_f32_e32 v15, v2, v3
	ds_read2st64_b32 v[2:3], v19 offset0:8 offset1:9
	v_add_f32_e32 v58, v12, v13
	v_lshl_add_u64 v[12:13], s[72:73], 1, v[22:23]
	s_lshl_b64 s[0:1], s[62:63], 9
	s_waitcnt lgkmcnt(0)
	v_sub_f32_e32 v57, v58, v2
	v_min_f32_e32 v57, 0x42a00000, v57
	v_mul_f32_e32 v57, 0x3fb8aa3b, v57
	v_exp_f32_e32 v57, v57
	s_nop 0
	v_lshlrev_b32_e32 v51, 16, v51
	v_mul_f32_e32 v57, v57, v51
	v_bfe_u32 v59, v57, 16, 1
	v_add3_u32 v57, v57, v59, s66
	ds_write_b16_d16_hi v36, v57 offset:2560
	v_sub_f32_e32 v57, v2, v58
	v_min_f32_e32 v57, 0x42a00000, v57
	v_mul_f32_e32 v57, 0x3fb8aa3b, v57
	v_exp_f32_e32 v57, v57
	s_nop 0
	v_mul_f32_e32 v57, v54, v57
	v_bfe_u32 v59, v57, 16, 1
	v_add3_u32 v57, v57, v59, s66
	ds_write_b16_d16_hi v36, v57 offset:11776
	v_sub_f32_e32 v57, v3, v58
	v_min_f32_e32 v57, 0x42a00000, v57
	v_mul_f32_e32 v57, 0x3fb8aa3b, v57
	v_exp_f32_e32 v57, v57
	s_nop 0
	v_mul_f32_e32 v54, v54, v57
	v_bfe_u32 v57, v54, 16, 1
	v_add3_u32 v54, v54, v57, s66
	ds_write_b16_d16_hi v37, v54 offset:20992
	s_nop 0
	ds_write_b16 v37, v53 offset:30208
	v_min_f32_e32 v53, 0x42a00000, v58
	v_mul_f32_e32 v53, 0x3fb8aa3b, v53
	v_exp_f32_e32 v53, v53
	v_lshl_add_u64 v[58:59], v[12:13], 0, s[0:1]
	s_add_u32 s0, s18, s84
	s_addc_u32 s1, s19, s85
	v_mul_f32_e32 v51, v53, v51
	v_bfe_u32 v53, v51, 16, 1
	v_add3_u32 v51, v51, v53, s66
	global_store_short_d16_hi v[58:59], v51, off
	v_mov_b32_e32 v51, v93
	s_lshl_b64 s[0:1], s[0:1], 9
	v_mov_b32_e32 v8, v101
	v_sub_f32_e32 v9, v60, v2
	v_min_f32_e32 v9, 0x42a00000, v9
	v_mul_f32_e32 v9, 0x3fb8aa3b, v9
	v_exp_f32_e32 v9, v9
	s_nop 0
	v_lshlrev_b32_e32 v51, 16, v51
	v_mul_f32_e32 v9, v9, v51
	v_bfe_u32 v53, v9, 16, 1
	v_add3_u32 v9, v9, v53, s66
	ds_write_b16_d16_hi v38, v9 offset:2560
	v_sub_f32_e32 v9, v2, v60
	v_min_f32_e32 v9, 0x42a00000, v9
	v_mul_f32_e32 v9, 0x3fb8aa3b, v9
	v_exp_f32_e32 v9, v9
	s_nop 0
	v_mul_f32_e32 v9, v61, v9
	v_bfe_u32 v53, v9, 16, 1
	v_add3_u32 v9, v9, v53, s66
	ds_write_b16_d16_hi v38, v9 offset:11776
	v_sub_f32_e32 v9, v3, v60
	v_min_f32_e32 v9, 0x42a00000, v9
	v_mul_f32_e32 v9, 0x3fb8aa3b, v9
	v_exp_f32_e32 v9, v9
	s_nop 0
	v_mul_f32_e32 v9, v61, v9
	v_bfe_u32 v53, v9, 16, 1
	v_add3_u32 v9, v9, v53, s66
	ds_write_b16_d16_hi v37, v9 offset:20994
	s_nop 0
	ds_write_b16 v37, v8 offset:30210
	v_min_f32_e32 v8, 0x42a00000, v60
	v_mul_f32_e32 v8, 0x3fb8aa3b, v8
	v_exp_f32_e32 v8, v8
	s_nop 0
	v_mul_f32_e32 v8, v8, v51
	v_bfe_u32 v9, v8, 16, 1
	v_add3_u32 v51, v8, v9, s66
	v_lshl_add_u64 v[8:9], v[12:13], 0, s[0:1]
	global_store_short_d16_hi v[8:9], v51, off
	v_mov_b32_e32 v8, v94
	v_sub_f32_e32 v51, v56, v2
	v_mov_b32_e32 v9, v102
	v_min_f32_e32 v51, 0x42a00000, v51
	v_mul_f32_e32 v51, 0x3fb8aa3b, v51
	v_exp_f32_e32 v51, v51
	s_add_u32 s0, s18, s88
	s_addc_u32 s1, s19, s60
	s_lshl_b64 s[0:1], s[0:1], 9
	s_nop 0
	v_lshlrev_b32_e32 v8, 16, v8
	v_mul_f32_e32 v51, v51, v8
	v_bfe_u32 v53, v51, 16, 1
	v_add3_u32 v51, v51, v53, s66
	ds_write_b16_d16_hi v39, v51 offset:2560
	v_sub_f32_e32 v51, v2, v56
	v_min_f32_e32 v51, 0x42a00000, v51
	v_mul_f32_e32 v51, 0x3fb8aa3b, v51
	v_exp_f32_e32 v51, v51
	s_nop 0
	v_mul_f32_e32 v51, v52, v51
	v_bfe_u32 v53, v51, 16, 1
	v_add3_u32 v51, v51, v53, s66
	ds_write_b16_d16_hi v39, v51 offset:11776
	v_sub_f32_e32 v51, v3, v56
	v_min_f32_e32 v51, 0x42a00000, v51
	v_mul_f32_e32 v51, 0x3fb8aa3b, v51
	v_exp_f32_e32 v51, v51
	s_nop 0
	v_mul_f32_e32 v51, v52, v51
	v_bfe_u32 v52, v51, 16, 1
	v_add3_u32 v51, v51, v52, s66
	ds_write_b16_d16_hi v37, v51 offset:20996
	s_nop 0
	ds_write_b16 v37, v9 offset:30212
	v_min_f32_e32 v9, 0x42a00000, v56
	v_mul_f32_e32 v9, 0x3fb8aa3b, v9
	v_exp_f32_e32 v9, v9
	s_nop 0
	v_mul_f32_e32 v8, v9, v8
	v_bfe_u32 v9, v8, 16, 1
	v_add3_u32 v51, v8, v9, s66
	v_lshl_add_u64 v[8:9], v[12:13], 0, s[0:1]
	global_store_short_d16_hi v[8:9], v51, off
	v_mov_b32_e32 v8, v95
	s_add_u32 s0, s18, s48
	v_mov_b32_e32 v6, v103
	v_sub_f32_e32 v7, v55, v2
	v_min_f32_e32 v7, 0x42a00000, v7
	v_mul_f32_e32 v7, 0x3fb8aa3b, v7
	v_exp_f32_e32 v7, v7
	s_addc_u32 s1, s19, s49
	s_lshl_b64 s[0:1], s[0:1], 9
	s_nop 0
	v_lshlrev_b32_e32 v8, 16, v8
	v_mul_f32_e32 v7, v7, v8
	v_bfe_u32 v9, v7, 16, 1
	v_add3_u32 v7, v7, v9, s66
	ds_write_b16_d16_hi v40, v7 offset:2560
	v_sub_f32_e32 v7, v2, v55
	v_min_f32_e32 v7, 0x42a00000, v7
	v_mul_f32_e32 v7, 0x3fb8aa3b, v7
	v_exp_f32_e32 v7, v7
	s_nop 0
	v_mul_f32_e32 v7, v50, v7
	v_bfe_u32 v9, v7, 16, 1
	v_add3_u32 v7, v7, v9, s66
	ds_write_b16_d16_hi v40, v7 offset:11776
	v_sub_f32_e32 v7, v3, v55
	v_min_f32_e32 v7, 0x42a00000, v7
	v_mul_f32_e32 v7, 0x3fb8aa3b, v7
	v_exp_f32_e32 v7, v7
	s_nop 0
	v_mul_f32_e32 v7, v50, v7
	v_bfe_u32 v9, v7, 16, 1
	v_add3_u32 v7, v7, v9, s66
	ds_write_b16_d16_hi v37, v7 offset:20998
	s_nop 0
; __device__ __forceinline__ unsigned f2bf(float f) { unsigned u = __builtin_bit_cast(unsigned, f); return (u + 0x7fffu + ((u >> 16) & 1u)) >> 16; }
; __device__ __forceinline__ float cexp(float x) { return __expf(fminf(x, 80.f)); }
; __device__ __forceinline__ void pass1(const bf16* ZB, const float* lbl, const Bufs& B, LAS unsigned char* shm, int G, int tid) {
;     ...
;         { const float rr = RB[k], b63 = B63[k];
; #pragma unroll
;           for (int i = 0; i < 8; ++i) { const int t = 8 * seg + i; const float q = bf2f(zr[(size_t)i * ZLD + O_Q]); const bf16 vraw = zr[(size_t)i * ZLD + O_I];
;               QT[t * RS + k] = (bf16)f2bf(q * cexp(bl[i] - rr)); KT[t * RS + k] = (bf16)f2bf(kkv[i] * cexp(rr - bl[i])); K2T[k * RS + t] = (bf16)f2bf(kkv[i] * cexp(b63 - bl[i])); VT[k * RS + t] = vraw;
;               B.QE[(row0 + t) * 256 + 64 * h + k] = (bf16)f2bf(q * cexp(bl[i])); }
;           if (seg == 0) B.DEC[(size_t)u * 64 + k] = cexp(b63); }
	ds_write_b16 v37, v6 offset:30214
	v_min_f32_e32 v6, 0x42a00000, v55
	v_mul_f32_e32 v6, 0x3fb8aa3b, v6
	v_exp_f32_e32 v6, v6
	s_nop 0
	v_mul_f32_e32 v6, v6, v8
	v_bfe_u32 v7, v6, 16, 1
	v_add3_u32 v8, v6, v7, s66
	v_lshl_add_u64 v[6:7], v[12:13], 0, s[0:1]
	global_store_short_d16_hi v[6:7], v8, off
	v_mov_b32_e32 v6, v96
	v_sub_f32_e32 v8, v48, v2
	v_mov_b32_e32 v7, v104
	v_min_f32_e32 v8, 0x42a00000, v8
	v_mul_f32_e32 v8, 0x3fb8aa3b, v8
	v_exp_f32_e32 v8, v8
	s_add_u32 s0, s18, s81
	s_addc_u32 s1, s19, s8
	s_lshl_b64 s[0:1], s[0:1], 9
	s_nop 0
	v_lshlrev_b32_e32 v6, 16, v6
	v_mul_f32_e32 v8, v8, v6
	v_bfe_u32 v9, v8, 16, 1
	v_add3_u32 v8, v8, v9, s66
	ds_write_b16_d16_hi v41, v8 offset:2560
	v_sub_f32_e32 v8, v2, v48
	v_min_f32_e32 v8, 0x42a00000, v8
	v_mul_f32_e32 v8, 0x3fb8aa3b, v8
	v_exp_f32_e32 v8, v8
	s_nop 0
	v_mul_f32_e32 v8, v49, v8
	v_bfe_u32 v9, v8, 16, 1
	v_add3_u32 v8, v8, v9, s66
	ds_write_b16_d16_hi v41, v8 offset:11776
	v_sub_f32_e32 v8, v3, v48
	v_min_f32_e32 v8, 0x42a00000, v8
	v_mul_f32_e32 v8, 0x3fb8aa3b, v8
	v_exp_f32_e32 v8, v8
	s_nop 0
	v_mul_f32_e32 v8, v49, v8
	v_bfe_u32 v9, v8, 16, 1
	v_add3_u32 v8, v8, v9, s66
	ds_write_b16_d16_hi v37, v8 offset:21000
	s_nop 0
	ds_write_b16 v37, v7 offset:30216
	v_min_f32_e32 v7, 0x42a00000, v48
	v_mul_f32_e32 v7, 0x3fb8aa3b, v7
	v_exp_f32_e32 v7, v7
	s_nop 0
	v_mul_f32_e32 v6, v7, v6
	v_bfe_u32 v7, v6, 16, 1
	v_add3_u32 v8, v6, v7, s66
	v_lshl_add_u64 v[6:7], v[12:13], 0, s[0:1]
	global_store_short_d16_hi v[6:7], v8, off
	v_mov_b32_e32 v6, v97
	s_add_u32 s0, s18, s9
	v_mov_b32_e32 v4, v105
	v_sub_f32_e32 v5, v29, v2
	v_min_f32_e32 v5, 0x42a00000, v5
	v_mul_f32_e32 v5, 0x3fb8aa3b, v5
	v_exp_f32_e32 v5, v5
	s_addc_u32 s1, s19, s10
	s_lshl_b64 s[0:1], s[0:1], 9
	s_nop 0
	v_lshlrev_b32_e32 v6, 16, v6
	v_mul_f32_e32 v5, v5, v6
	v_bfe_u32 v7, v5, 16, 1
	v_add3_u32 v5, v5, v7, s66
	ds_write_b16_d16_hi v42, v5 offset:2560
	v_sub_f32_e32 v5, v2, v29
	v_min_f32_e32 v5, 0x42a00000, v5
	v_mul_f32_e32 v5, 0x3fb8aa3b, v5
	v_exp_f32_e32 v5, v5
	s_nop 0
	v_mul_f32_e32 v5, v47, v5
	v_bfe_u32 v7, v5, 16, 1
	v_add3_u32 v5, v5, v7, s66
	ds_write_b16_d16_hi v42, v5 offset:11776
	v_sub_f32_e32 v5, v3, v29
	v_min_f32_e32 v5, 0x42a00000, v5
	v_mul_f32_e32 v5, 0x3fb8aa3b, v5
	v_exp_f32_e32 v5, v5
	s_nop 0
	v_mul_f32_e32 v5, v47, v5
	v_bfe_u32 v7, v5, 16, 1
	v_add3_u32 v5, v5, v7, s66
	ds_write_b16_d16_hi v37, v5 offset:21002
	s_nop 0
	ds_write_b16 v37, v4 offset:30218
	v_min_f32_e32 v4, 0x42a00000, v29
	v_mul_f32_e32 v4, 0x3fb8aa3b, v4
	v_exp_f32_e32 v4, v4
	s_nop 0
	v_mul_f32_e32 v4, v4, v6
	v_bfe_u32 v5, v4, 16, 1
	v_add3_u32 v6, v4, v5, s66
	v_lshl_add_u64 v[4:5], v[12:13], 0, s[0:1]
	global_store_short_d16_hi v[4:5], v6, off
	v_mov_b32_e32 v4, v98
	v_sub_f32_e32 v6, v16, v2
	v_mov_b32_e32 v5, v106
	v_min_f32_e32 v6, 0x42a00000, v6
	v_mul_f32_e32 v6, 0x3fb8aa3b, v6
	v_exp_f32_e32 v6, v6
	s_add_u32 s0, s18, s11
	s_addc_u32 s1, s19, s12
	s_lshl_b64 s[0:1], s[0:1], 9
	s_nop 0
	v_lshlrev_b32_e32 v4, 16, v4
	v_mul_f32_e32 v6, v6, v4
	v_bfe_u32 v7, v6, 16, 1
	v_add3_u32 v6, v6, v7, s66
	ds_write_b16_d16_hi v43, v6 offset:2560
	v_sub_f32_e32 v6, v2, v16
	v_min_f32_e32 v6, 0x42a00000, v6
	v_mul_f32_e32 v6, 0x3fb8aa3b, v6
	v_exp_f32_e32 v6, v6
	s_nop 0
	v_mul_f32_e32 v6, v17, v6
	v_bfe_u32 v7, v6, 16, 1
	v_add3_u32 v6, v6, v7, s66
	ds_write_b16_d16_hi v43, v6 offset:11776
	v_sub_f32_e32 v6, v3, v16
	v_min_f32_e32 v6, 0x42a00000, v6
	v_mul_f32_e32 v6, 0x3fb8aa3b, v6
	v_exp_f32_e32 v6, v6
	s_nop 0
	v_mul_f32_e32 v6, v17, v6
	v_bfe_u32 v7, v6, 16, 1
	v_add3_u32 v6, v6, v7, s66
	ds_write_b16_d16_hi v37, v6 offset:21004
	s_nop 0
	ds_write_b16 v37, v5 offset:30220
	v_min_f32_e32 v5, 0x42a00000, v16
	v_mul_f32_e32 v5, 0x3fb8aa3b, v5
	v_exp_f32_e32 v5, v5
	s_nop 0
	v_mul_f32_e32 v4, v5, v4
	v_bfe_u32 v5, v4, 16, 1
	v_add3_u32 v6, v4, v5, s66
	v_lshl_add_u64 v[4:5], v[12:13], 0, s[0:1]
	global_store_short_d16_hi v[4:5], v6, off
	v_mov_b32_e32 v4, v99
	v_sub_f32_e32 v6, v14, v2
	v_mov_b32_e32 v5, v107
	v_min_f32_e32 v6, 0x42a00000, v6
	v_mul_f32_e32 v6, 0x3fb8aa3b, v6
	v_sub_f32_e32 v2, v2, v14
	v_exp_f32_e32 v6, v6
	v_min_f32_e32 v2, 0x42a00000, v2
	v_mul_f32_e32 v2, 0x3fb8aa3b, v2
	v_exp_f32_e32 v2, v2
	s_add_u32 s0, s18, s13
	s_addc_u32 s1, s19, s14
	s_lshl_b64 s[0:1], s[0:1], 9
	v_mul_f32_e32 v2, v15, v2
	s_andn2_b64 vcc, exec, s[54:55]
	s_nop 0
	v_lshlrev_b32_e32 v4, 16, v4
	v_mul_f32_e32 v6, v6, v4
	v_bfe_u32 v7, v6, 16, 1
	v_add3_u32 v6, v6, v7, s66
	ds_write_b16_d16_hi v44, v6 offset:2560
	v_bfe_u32 v6, v2, 16, 1
	v_add3_u32 v2, v2, v6, s66
	ds_write_b16_d16_hi v44, v2 offset:11776
	v_sub_f32_e32 v2, v3, v14
	v_min_f32_e32 v2, 0x42a00000, v2
	v_mul_f32_e32 v2, 0x3fb8aa3b, v2
	v_exp_f32_e32 v2, v2
	s_nop 0
	v_mul_f32_e32 v2, v15, v2
	v_bfe_u32 v6, v2, 16, 1
	v_add3_u32 v2, v2, v6, s66
	ds_write_b16_d16_hi v37, v2 offset:21006
	s_nop 0
	ds_write_b16 v37, v5 offset:30222
	v_max_f32_e32 v2, v14, v14
	v_min_f32_e32 v2, 0x42a00000, v2
	v_mul_f32_e32 v2, 0x3fb8aa3b, v2
	v_exp_f32_e32 v2, v2
	s_nop 0
	v_mul_f32_e32 v2, v2, v4
	v_bfe_u32 v4, v2, 16, 1
	v_add3_u32 v2, v2, v4, s66
	v_lshl_add_u64 v[4:5], v[12:13], 0, s[0:1]
	global_store_short_d16_hi v[4:5], v2, off
	s_cbranch_vccnz .LBB0_556
	v_max_f32_e32 v2, v3, v3
	v_min_f32_e32 v2, 0x42a00000, v2
	v_mul_f32_e32 v2, 0x3fb8aa3b, v2
	v_exp_f32_e32 v4, v2
	s_lshl_b64 s[0:1], s[46:47], 8
	v_lshl_add_u64 v[2:3], v[24:25], 0, s[0:1]
	global_store_dword v[2:3], v4, off

; __device__ __forceinline__ void pass3(const bf16* ZB, const float* hg_norm, const Bufs& B, bf16* YCB, int G, int tid) {
;     ...
;     for (int it = (int)blockIdx.x * (MK_THREADS / 64) + wave; it < NUNIT * 2; it += G * (MK_THREADS / 64)) { const int u = it >> 1, ti = it & 1, n = u % NCH, bh = u / NCH, h = bh % HGH, b = bh / HGH;
;         const size_t row0 = (size_t)b * SEQ + 64 * n + 32 * ti; const bf16* sp = B.SST + (size_t)u * 4096; f32x16 acc[2]; acc[0] = f32x16{}; acc[1] = f32x16{};
; #pragma unroll
;         for (int ks = 0; ks < 4; ++ks) { const bf16x8 av = *(const bf16x8*)(B.QE + (row0 + r32) * 256 + 64 * h + 16 * ks + 8 * hh);
; #pragma unroll
;             for (int vi = 0; vi < 2; ++vi) { const bf16* s8 = sp + (size_t)(16 * ks + 8 * hh) * 64 + 32 * vi + r32; u32x4_t pk;
;                 pk.x = (unsigned)s8[0] | ((unsigned)s8[64] << 16); pk.y = (unsigned)s8[128] | ((unsigned)s8[192] << 16); pk.z = (unsigned)s8[256] | ((unsigned)s8[320] << 16); pk.w = (unsigned)s8[384] | ((unsigned)s8[448] << 16);
;                 acc[vi] = __builtin_amdgcn_mfma_f32_32x32x16_bf16(av, __builtin_bit_cast(bf16x8, pk), acc[vi], 0, 0, 0); } }
.LBB0_1059:
	s_ashr_i32 s1, s2, 31
	s_ashr_i32 s0, s2, 1
	s_lshr_b32 s6, s1, 26
	s_add_i32 s6, s0, s6
	s_ashr_i32 s7, s6, 6
	s_and_b32 s6, s6, 0x3ffffc0
	s_sub_i32 s8, s0, s6
	s_lshr_b32 s6, s7, 30
	s_add_i32 s6, s7, s6
	s_lshr_b32 s1, s1, 24
	s_and_b32 s6, s6, 0x3fffffc
	s_add_i32 s1, s0, s1
	s_sub_i32 s10, s7, s6
	s_ashr_i32 s6, s1, 8
	s_ashr_i32 s7, s6, 31
	s_lshl_b32 s1, s8, 6
	s_lshl_b64 s[6:7], s[6:7], 12
	s_ashr_i32 s8, s1, 31
	s_add_u32 s1, s6, s1
	s_addc_u32 s7, s7, s8
	s_and_b32 s6, s3, 32
	s_or_b32 s6, s1, s6
	s_ashr_i32 s1, s0, 31
	s_lshl_b64 s[8:9], s[0:1], 13
	v_mov_b32_e32 v3, s7
	v_or_b32_e32 v2, s6, v34
	s_lshl_b32 s0, s10, 6
	v_lshlrev_b64 v[2:3], 9, v[2:3]
	s_ashr_i32 s1, s0, 31
	v_lshl_add_u64 v[2:3], s[28:29], 0, v[2:3]
	s_lshl_b64 s[12:13], s[0:1], 1
	v_lshl_add_u64 v[2:3], v[2:3], 0, s[12:13]
	v_readlane_b32 s16, v251, 22
	v_readlane_b32 s17, v251, 23
	s_add_u32 s20, s64, s12
	s_addc_u32 s21, s65, s13
	s_add_u32 s16, s16, s12
	s_addc_u32 s17, s17, s13
	s_waitcnt vmcnt(1)
	v_lshl_add_u64 v[80:81], v[2:3], 0, v[214:215]
	v_lshl_add_u64 v[82:83], v[70:71], 0, s[8:9]
	global_load_dwordx4 v[84:87], v[80:81], off
	global_load_dwordx4 v[88:91], v[80:81], off offset:32
	global_load_dwordx4 v[92:95], v[80:81], off offset:64
	global_load_dwordx4 v[96:99], v[80:81], off offset:96
	v_add_co_u32_e32 v164, vcc, s88, v82
	s_nop 1
	v_addc_co_u32_e32 v165, vcc, 0, v83, vcc
	s_add_i32 s2, s2, s70
	s_add_i32 s3, s3, s11
	s_cmpk_lt_i32 s2, 0x800
	global_load_ushort v100, v[82:83], off
	global_load_ushort v132, v[82:83], off offset:128
	global_load_ushort v101, v[82:83], off offset:256
	global_load_ushort v133, v[82:83], off offset:384
	global_load_ushort v102, v[82:83], off offset:512
	global_load_ushort v134, v[82:83], off offset:640
	global_load_ushort v103, v[82:83], off offset:768
	global_load_ushort v135, v[82:83], off offset:896
	global_load_ushort v104, v[82:83], off offset:64
	global_load_ushort v136, v[82:83], off offset:192
	global_load_ushort v105, v[82:83], off offset:320
	global_load_ushort v137, v[82:83], off offset:448
	global_load_ushort v106, v[82:83], off offset:576
	global_load_ushort v138, v[82:83], off offset:704
	global_load_ushort v107, v[82:83], off offset:832
	global_load_ushort v139, v[82:83], off offset:960
	global_load_ushort v108, v[82:83], off offset:2048
	global_load_ushort v140, v[82:83], off offset:2176
	global_load_ushort v109, v[82:83], off offset:2304
	global_load_ushort v141, v[82:83], off offset:2432
	global_load_ushort v110, v[82:83], off offset:2560
	global_load_ushort v142, v[82:83], off offset:2688
	global_load_ushort v111, v[82:83], off offset:2816
	global_load_ushort v143, v[82:83], off offset:2944
	global_load_ushort v112, v[82:83], off offset:2112
	global_load_ushort v144, v[82:83], off offset:2240
	global_load_ushort v113, v[82:83], off offset:2368
	global_load_ushort v145, v[82:83], off offset:2496
	global_load_ushort v114, v[82:83], off offset:2624
	global_load_ushort v146, v[82:83], off offset:2752
	global_load_ushort v115, v[82:83], off offset:2880
	global_load_ushort v147, v[82:83], off offset:3008
	global_load_ushort v116, v[164:165], off
	global_load_ushort v148, v[164:165], off offset:128
	global_load_ushort v117, v[164:165], off offset:256
	global_load_ushort v149, v[164:165], off offset:384
	global_load_ushort v118, v[164:165], off offset:512
	global_load_ushort v150, v[164:165], off offset:640
	global_load_ushort v119, v[164:165], off offset:768
	global_load_ushort v151, v[164:165], off offset:896
	global_load_ushort v120, v[164:165], off offset:64
	global_load_ushort v152, v[164:165], off offset:192
	global_load_ushort v121, v[164:165], off offset:320
	global_load_ushort v153, v[164:165], off offset:448
	global_load_ushort v122, v[164:165], off offset:576
	global_load_ushort v154, v[164:165], off offset:704
	global_load_ushort v123, v[164:165], off offset:832
	global_load_ushort v155, v[164:165], off offset:960
	s_waitcnt vmcnt(32)
	v_lshl_or_b32 v100, v132, 16, v100
	v_lshl_or_b32 v101, v133, 16, v101
	v_lshl_or_b32 v102, v134, 16, v102
	v_lshl_or_b32 v103, v135, 16, v103
	v_lshl_or_b32 v104, v136, 16, v104
	v_lshl_or_b32 v105, v137, 16, v105
	v_lshl_or_b32 v106, v138, 16, v106
	v_lshl_or_b32 v107, v139, 16, v107
	s_nop 1
	v_mfma_f32_32x32x16_bf16 v[2:17], v[84:87], v[100:103], 0
	v_mfma_f32_32x32x16_bf16 v[18:33], v[84:87], v[104:107], 0
	global_load_ushort v124, v[164:165], off offset:2048
	global_load_ushort v156, v[164:165], off offset:2176
	global_load_ushort v125, v[164:165], off offset:2304
	global_load_ushort v157, v[164:165], off offset:2432
	global_load_ushort v126, v[164:165], off offset:2560
	global_load_ushort v158, v[164:165], off offset:2688
	global_load_ushort v127, v[164:165], off offset:2816
	global_load_ushort v159, v[164:165], off offset:2944
	global_load_ushort v128, v[164:165], off offset:2112
	global_load_ushort v160, v[164:165], off offset:2240
	global_load_ushort v129, v[164:165], off offset:2368
	global_load_ushort v161, v[164:165], off offset:2496
	global_load_ushort v130, v[164:165], off offset:2624
	global_load_ushort v162, v[164:165], off offset:2752
	global_load_ushort v131, v[164:165], off offset:2880
	global_load_ushort v163, v[164:165], off offset:3008
	s_waitcnt vmcnt(32)
	v_lshl_or_b32 v108, v140, 16, v108
	v_lshl_or_b32 v109, v141, 16, v109
	v_lshl_or_b32 v110, v142, 16, v110
	v_lshl_or_b32 v111, v143, 16, v111
	v_lshl_or_b32 v112, v144, 16, v112
	v_lshl_or_b32 v113, v145, 16, v113
	v_lshl_or_b32 v114, v146, 16, v114
	v_lshl_or_b32 v115, v147, 16, v115
	s_nop 1
	v_mfma_f32_32x32x16_bf16 v[2:17], v[88:91], v[108:111], v[2:17]
	v_mfma_f32_32x32x16_bf16 v[18:33], v[88:91], v[112:115], v[18:33]
	s_waitcnt vmcnt(16)
; __device__ __forceinline__ int crow(int r, int hi) { return (r & 3) + 8 * (r >> 2) + 4 * hi; }
; __device__ __forceinline__ int crow(int r, int hi) { return (r & 3) + 8 * (r >> 2) + 4 * hi; }
; __device__ __forceinline__ int crow(int r, int hi) { return (r & 3) + 8 * (r >> 2) + 4 * hi; }
; __device__ __forceinline__ int crow(int r, int hi) { return (r & 3) + 8 * (r >> 2) + 4 * hi; }
; __device__ __forceinline__ void pass3(const bf16* ZB, const float* hg_norm, const Bufs& B, bf16* YCB, int G, int tid) {
;     ...
;         for (int ks = 0; ks < 4; ++ks) { const bf16x8 av = *(const bf16x8*)(B.QE + (row0 + r32) * 256 + 64 * h + 16 * ks + 8 * hh);
; #pragma unroll
;             for (int vi = 0; vi < 2; ++vi) { const bf16* s8 = sp + (size_t)(16 * ks + 8 * hh) * 64 + 32 * vi + r32; u32x4_t pk;
;                 pk.x = (unsigned)s8[0] | ((unsigned)s8[64] << 16); pk.y = (unsigned)s8[128] | ((unsigned)s8[192] << 16); pk.z = (unsigned)s8[256] | ((unsigned)s8[320] << 16); pk.w = (unsigned)s8[384] | ((unsigned)s8[448] << 16);
;                 acc[vi] = __builtin_amdgcn_mfma_f32_32x32x16_bf16(av, __builtin_bit_cast(bf16x8, pk), acc[vi], 0, 0, 0); } }
;         const float hn0 = hg_norm[64 * h + r32], hn1 = hg_norm[64 * h + 32 + r32];
; #pragma unroll
;         for (int rg = 0; rg < 16; ++rg) { const size_t row = row0 + crow(rg, hh); const float o0 = acc[0][rg] + bf2f(B.INTRA[row * 256 + 64 * h + r32]), o1 = acc[1][rg] + bf2f(B.INTRA[row * 256 + 64 * h + 32 + r32]);
;             float ss = o0 * o0 + o1 * o1;
; #pragma unroll
;             for (int o = 1; o < 32; o <<= 1) ss += __shfl_xor(ss, o);
;             const float rinv = 1.0f / sqrtf(ss * (1.f / 64.f) + LN_EPS);
;             const float g0 = bf2f(ZB[row * ZLD + O_G + 64 * h + r32]), g1 = bf2f(ZB[row * ZLD + O_G + 64 * h + 32 + r32]);
	v_lshl_or_b32 v116, v148, 16, v116
	v_lshl_or_b32 v117, v149, 16, v117
	v_lshl_or_b32 v118, v150, 16, v118
	v_lshl_or_b32 v119, v151, 16, v119
	v_lshl_or_b32 v120, v152, 16, v120
	v_lshl_or_b32 v121, v153, 16, v121
	v_lshl_or_b32 v122, v154, 16, v122
	v_lshl_or_b32 v123, v155, 16, v123
	s_nop 1
	v_mfma_f32_32x32x16_bf16 v[2:17], v[92:95], v[116:119], v[2:17]
	v_mfma_f32_32x32x16_bf16 v[18:33], v[92:95], v[120:123], v[18:33]
	s_waitcnt vmcnt(0)
	v_lshl_or_b32 v124, v156, 16, v124
	v_lshl_or_b32 v125, v157, 16, v125
	v_lshl_or_b32 v126, v158, 16, v126
	v_lshl_or_b32 v127, v159, 16, v127
	v_lshl_or_b32 v128, v160, 16, v128
	v_lshl_or_b32 v129, v161, 16, v129
	v_lshl_or_b32 v130, v162, 16, v130
	v_lshl_or_b32 v131, v163, 16, v131
	s_nop 1
	v_mfma_f32_32x32x16_bf16 v[2:17], v[96:99], v[124:127], v[2:17]
	v_mfma_f32_32x32x16_bf16 v[18:33], v[96:99], v[128:131], v[18:33]
	v_or_b32_e32 v72, s0, v34
	v_ashrrev_i32_e32 v73, 31, v72
	v_lshl_add_u64 v[72:73], v[72:73], 2, s[38:39]
	global_load_dword v49, v[72:73], off
	global_load_dword v47, v[72:73], off offset:128
	v_lshlrev_b32_e32 v88, 1, v34
	v_or_b32_e32 v89, s6, v36
	v_lshl_or_b32 v90, v89, 9, v88
	v_lshl_or_b32 v91, v89, 11, v88
	global_load_ushort v132, v90, s[16:17]
	global_load_ushort v148, v90, s[16:17] offset:64
	global_load_ushort v166, v91, s[20:21] offset:1536
	global_load_ushort v182, v91, s[20:21] offset:1600
	v_or_b32_e32 v89, s6, v40
	v_lshl_or_b32 v90, v89, 9, v88
	v_lshl_or_b32 v91, v89, 11, v88
	global_load_ushort v133, v90, s[16:17]
	global_load_ushort v149, v90, s[16:17] offset:64
	global_load_ushort v167, v91, s[20:21] offset:1536
	global_load_ushort v183, v91, s[20:21] offset:1600
	v_or_b32_e32 v89, s6, v42
	v_lshl_or_b32 v90, v89, 9, v88
	v_lshl_or_b32 v91, v89, 11, v88
	global_load_ushort v134, v90, s[16:17]
	global_load_ushort v150, v90, s[16:17] offset:64
	global_load_ushort v168, v91, s[20:21] offset:1536
	global_load_ushort v184, v91, s[20:21] offset:1600
	v_or_b32_e32 v89, s6, v44
	v_lshl_or_b32 v90, v89, 9, v88
	v_lshl_or_b32 v91, v89, 11, v88
	global_load_ushort v135, v90, s[16:17]
	global_load_ushort v151, v90, s[16:17] offset:64
	global_load_ushort v169, v91, s[20:21] offset:1536
	global_load_ushort v185, v91, s[20:21] offset:1600
	v_or_b32_e32 v89, s6, v46
	v_lshl_or_b32 v90, v89, 9, v88
	v_lshl_or_b32 v91, v89, 11, v88
	global_load_ushort v136, v90, s[16:17]
	global_load_ushort v152, v90, s[16:17] offset:64
	global_load_ushort v170, v91, s[20:21] offset:1536
	global_load_ushort v186, v91, s[20:21] offset:1600
	v_or_b32_e32 v89, s6, v48
	v_lshl_or_b32 v90, v89, 9, v88
	v_lshl_or_b32 v91, v89, 11, v88
	global_load_ushort v137, v90, s[16:17]
	global_load_ushort v153, v90, s[16:17] offset:64
	global_load_ushort v171, v91, s[20:21] offset:1536
	global_load_ushort v187, v91, s[20:21] offset:1600
	v_or_b32_e32 v89, s6, v50
	v_lshl_or_b32 v90, v89, 9, v88
	v_lshl_or_b32 v91, v89, 11, v88
	global_load_ushort v138, v90, s[16:17]
	global_load_ushort v154, v90, s[16:17] offset:64
	global_load_ushort v172, v91, s[20:21] offset:1536
	global_load_ushort v188, v91, s[20:21] offset:1600
	v_or_b32_e32 v89, s6, v52
	v_lshl_or_b32 v90, v89, 9, v88
	v_lshl_or_b32 v91, v89, 11, v88
	global_load_ushort v139, v90, s[16:17]
	global_load_ushort v155, v90, s[16:17] offset:64
	global_load_ushort v173, v91, s[20:21] offset:1536
	global_load_ushort v189, v91, s[20:21] offset:1600
	s_waitcnt vmcnt(30)
	v_or_b32_e32 v89, s6, v54
	v_lshl_or_b32 v90, v89, 9, v88
	v_lshl_or_b32 v91, v89, 11, v88
	global_load_ushort v140, v90, s[16:17]
	global_load_ushort v156, v90, s[16:17] offset:64
	global_load_ushort v174, v91, s[20:21] offset:1536
	global_load_ushort v190, v91, s[20:21] offset:1600
	v_or_b32_e32 v89, s6, v56
	v_lshl_or_b32 v90, v89, 9, v88
	v_lshl_or_b32 v91, v89, 11, v88
	global_load_ushort v141, v90, s[16:17]
	global_load_ushort v157, v90, s[16:17] offset:64
	global_load_ushort v175, v91, s[20:21] offset:1536
	global_load_ushort v191, v91, s[20:21] offset:1600
	v_or_b32_e32 v89, s6, v58
	v_lshl_or_b32 v90, v89, 9, v88
	v_lshl_or_b32 v91, v89, 11, v88
	global_load_ushort v142, v90, s[16:17]
	global_load_ushort v158, v90, s[16:17] offset:64
	global_load_ushort v176, v91, s[20:21] offset:1536
	global_load_ushort v84, v91, s[20:21] offset:1600
	v_or_b32_e32 v89, s6, v60
	v_lshl_or_b32 v90, v89, 9, v88
	v_lshl_or_b32 v91, v89, 11, v88
	global_load_ushort v143, v90, s[16:17]
	global_load_ushort v159, v90, s[16:17] offset:64
	global_load_ushort v177, v91, s[20:21] offset:1536
	global_load_ushort v85, v91, s[20:21] offset:1600
	v_or_b32_e32 v89, s6, v62
	v_lshl_or_b32 v90, v89, 9, v88
	v_lshl_or_b32 v91, v89, 11, v88
	global_load_ushort v144, v90, s[16:17]
	global_load_ushort v160, v90, s[16:17] offset:64
	global_load_ushort v178, v91, s[20:21] offset:1536
	global_load_ushort v86, v91, s[20:21] offset:1600
	v_or_b32_e32 v89, s6, v64
	v_lshl_or_b32 v90, v89, 9, v88
	v_lshl_or_b32 v91, v89, 11, v88
	global_load_ushort v145, v90, s[16:17]
	global_load_ushort v161, v90, s[16:17] offset:64
	global_load_ushort v179, v91, s[20:21] offset:1536
	global_load_ushort v87, v91, s[20:21] offset:1600
	v_or_b32_e32 v89, s6, v66
	v_lshl_or_b32 v90, v89, 9, v88
	v_lshl_or_b32 v91, v89, 11, v88
	global_load_ushort v146, v90, s[16:17]
	global_load_ushort v162, v90, s[16:17] offset:64
	global_load_ushort v180, v91, s[20:21] offset:1536
	global_load_ushort v164, v91, s[20:21] offset:1600
	v_or_b32_e32 v89, s6, v68
	v_lshl_or_b32 v90, v89, 9, v88
	v_lshl_or_b32 v91, v89, 11, v88
	global_load_ushort v147, v90, s[16:17]
	global_load_ushort v163, v90, s[16:17] offset:64
	global_load_ushort v181, v91, s[20:21] offset:1536
	global_load_ushort v165, v91, s[20:21] offset:1600
	s_waitcnt vmcnt(0)
; __device__ __forceinline__ unsigned f2bf(float f) { unsigned u = __builtin_bit_cast(unsigned, f); return (u + 0x7fffu + ((u >> 16) & 1u)) >> 16; }
; __device__ __forceinline__ int crow(int r, int hi) { return (r & 3) + 8 * (r >> 2) + 4 * hi; }
; __device__ __forceinline__ int crow(int r, int hi) { return (r & 3) + 8 * (r >> 2) + 4 * hi; }
; __device__ __forceinline__ int crow(int r, int hi) { return (r & 3) + 8 * (r >> 2) + 4 * hi; }
; __device__ __forceinline__ int crow(int r, int hi) { return (r & 3) + 8 * (r >> 2) + 4 * hi; }
; __device__ __forceinline__ void pass3(const bf16* ZB, const float* hg_norm, const Bufs& B, bf16* YCB, int G, int tid) {
;     ...
;         const float hn0 = hg_norm[64 * h + r32], hn1 = hg_norm[64 * h + 32 + r32];
; #pragma unroll
;         for (int rg = 0; rg < 16; ++rg) { const size_t row = row0 + crow(rg, hh); const float o0 = acc[0][rg] + bf2f(B.INTRA[row * 256 + 64 * h + r32]), o1 = acc[1][rg] + bf2f(B.INTRA[row * 256 + 64 * h + 32 + r32]);
;             float ss = o0 * o0 + o1 * o1;
; #pragma unroll
;             for (int o = 1; o < 32; o <<= 1) ss += __shfl_xor(ss, o);
;             const float rinv = 1.0f / sqrtf(ss * (1.f / 64.f) + LN_EPS);
;             const float g0 = bf2f(ZB[row * ZLD + O_G + 64 * h + r32]), g1 = bf2f(ZB[row * ZLD + O_G + 64 * h + 32 + r32]);
;             YCB[row * 1024 + 256 + 64 * h + r32] = (bf16)f2bf(o0 * rinv * hn0 / (1.0f + __expf(-g0))); YCB[row * 1024 + 256 + 64 * h + 32 + r32] = (bf16)f2bf(o1 * rinv * hn1 / (1.0f + __expf(-g1))); }
	v_mov_b32_e32 v73, s7
	v_or_b32_e32 v72, s6, v36
	v_lshl_add_u64 v[74:75], v[38:39], 0, s[12:13]
	v_lshlrev_b64 v[76:77], 9, v[72:73]
	v_lshl_add_u64 v[76:77], v[74:75], 0, v[76:77]
	v_mov_b32_e32 v51, v132
	s_nop 0
	v_lshlrev_b32_e32 v51, 16, v51
	v_add_f32_e32 v51, v2, v51
	v_mov_b32_e32 v2, v148
	v_lshlrev_b64 v[76:77], 11, v[72:73]
	v_lshl_add_u64 v[72:73], s[64:65], 0, v[76:77]
	v_lshl_add_u64 v[78:79], v[72:73], 0, s[12:13]
	v_lshlrev_b32_e32 v72, 1, v34
	v_mov_b32_e32 v73, v215
	v_lshl_add_u64 v[78:79], v[78:79], 0, v[72:73]
	v_lshl_add_u64 v[76:77], s[26:27], 0, v[76:77]
	v_lshl_add_u64 v[76:77], v[76:77], 0, s[12:13]
	v_lshl_add_u64 v[76:77], v[76:77], 0, v[72:73]
	s_nop 0
	v_lshlrev_b32_e32 v2, 16, v2
	v_add_f32_e32 v2, v18, v2
	v_mul_f32_e32 v18, v2, v2
	v_fmac_f32_e32 v18, v51, v51
	ds_bpermute_b32 v53, v35, v18
	s_waitcnt lgkmcnt(0)
	v_add_f32_e32 v18, v18, v53
	ds_bpermute_b32 v53, v37, v18
	s_waitcnt lgkmcnt(0)
	v_add_f32_e32 v18, v18, v53
	ds_bpermute_b32 v53, v41, v18
	s_waitcnt lgkmcnt(0)
	v_add_f32_e32 v18, v18, v53
	ds_bpermute_b32 v53, v43, v18
	s_waitcnt lgkmcnt(0)
	v_add_f32_e32 v18, v18, v53
	ds_bpermute_b32 v53, v45, v18
	s_waitcnt lgkmcnt(0)
	v_add_f32_e32 v18, v18, v53
	v_fmamk_f32 v18, v18, 0x3c800000, v1
	v_cmp_gt_f32_e32 vcc, s14, v18
	v_mul_f32_e32 v53, 0x4f800000, v18
	s_nop 0
	v_cndmask_b32_e32 v18, v18, v53, vcc
	v_sqrt_f32_e32 v53, v18
	s_nop 0
	v_add_u32_e32 v55, -1, v53
	v_fma_f32 v57, -v55, v53, v18
	v_cmp_ge_f32_e64 s[0:1], 0, v57
	v_add_u32_e32 v57, 1, v53
	s_nop 0
	v_cndmask_b32_e64 v55, v53, v55, s[0:1]
	v_fma_f32 v53, -v57, v53, v18
	v_cmp_lt_f32_e64 s[0:1], 0, v53
	s_nop 1
	v_cndmask_b32_e64 v53, v55, v57, s[0:1]
	v_mul_f32_e32 v55, 0x37800000, v53
	v_cndmask_b32_e32 v53, v53, v55, vcc
	v_cmp_class_f32_e32 vcc, v18, v223
	s_nop 1
	v_cndmask_b32_e32 v18, v53, v18, vcc
	v_div_scale_f32 v53, s[0:1], v18, v18, 1.0
	v_rcp_f32_e32 v55, v53
	s_nop 0
	v_fma_f32 v57, -v53, v55, 1.0
	v_fmac_f32_e32 v55, v57, v55
	v_div_scale_f32 v57, vcc, 1.0, v18, 1.0
	v_mul_f32_e32 v59, v57, v55
	v_fma_f32 v61, -v53, v59, v57
	v_fmac_f32_e32 v59, v61, v55
	v_fma_f32 v53, -v53, v59, v57
	v_div_fmas_f32 v53, v53, v55, v59
	v_div_fixup_f32 v18, v53, v18, 1.0
	v_mov_b32_e32 v53, v166
	v_mov_b32_e32 v55, v182
	v_mul_f32_e32 v51, v51, v18
	v_mul_f32_e32 v51, v49, v51
	v_mul_f32_e32 v2, v2, v18
	v_mul_f32_e32 v2, v47, v2
	s_nop 0
	v_lshlrev_b32_e32 v53, 16, v53
	v_mul_f32_e32 v53, 0xbfb8aa3b, v53
	v_exp_f32_e32 v53, v53
	s_nop 0
	v_lshlrev_b32_e32 v55, 16, v55
	v_mul_f32_e32 v18, 0xbfb8aa3b, v55
	v_exp_f32_e32 v18, v18
	v_add_f32_e32 v53, 1.0, v53
	v_div_scale_f32 v57, s[0:1], v53, v53, v51
	v_rcp_f32_e32 v59, v57
	v_add_f32_e32 v18, 1.0, v18
	v_fma_f32 v61, -v57, v59, 1.0
	v_fmac_f32_e32 v59, v61, v59
	v_div_scale_f32 v61, vcc, v51, v53, v51
	v_mul_f32_e32 v63, v61, v59
	v_fma_f32 v65, -v57, v63, v61
	v_fmac_f32_e32 v63, v65, v59
	v_fma_f32 v57, -v57, v63, v61
	v_div_fmas_f32 v57, v57, v59, v63
	v_div_fixup_f32 v51, v57, v53, v51
	v_bfe_u32 v53, v51, 16, 1
	v_add3_u32 v51, v51, v53, s66
	global_store_short_d16_hi v[76:77], v51, off offset:512
	v_div_scale_f32 v51, s[0:1], v18, v18, v2
	v_rcp_f32_e32 v53, v51
	s_nop 0
	v_fma_f32 v55, -v51, v53, 1.0
	v_fmac_f32_e32 v53, v55, v53
	v_div_scale_f32 v55, vcc, v2, v18, v2
	v_mul_f32_e32 v57, v55, v53
	v_fma_f32 v59, -v51, v57, v55
	v_fmac_f32_e32 v57, v59, v53
	v_fma_f32 v51, -v51, v57, v55
	v_div_fmas_f32 v51, v51, v53, v57
	v_div_fixup_f32 v2, v51, v18, v2
	v_bfe_u32 v18, v2, 16, 1
	v_add3_u32 v2, v2, v18, s66
	global_store_short_d16_hi v[76:77], v2, off offset:576
	v_mov_b32_e32 v77, s7
	v_or_b32_e32 v76, s6, v40
	v_lshlrev_b64 v[78:79], 9, v[76:77]
	v_lshl_add_u64 v[78:79], v[74:75], 0, v[78:79]
	v_mov_b32_e32 v2, v133
	s_nop 0
	v_lshlrev_b32_e32 v2, 16, v2
	v_add_f32_e32 v51, v3, v2
	v_mov_b32_e32 v2, v149
	s_nop 0
	v_lshlrev_b32_e32 v2, 16, v2
	v_add_f32_e32 v53, v19, v2
	v_mul_f32_e32 v2, v53, v53
	v_fmac_f32_e32 v2, v51, v51
	ds_bpermute_b32 v3, v35, v2
	s_waitcnt lgkmcnt(0)
	v_add_f32_e32 v2, v2, v3
	ds_bpermute_b32 v3, v37, v2
	s_waitcnt lgkmcnt(0)
	v_add_f32_e32 v2, v2, v3
	ds_bpermute_b32 v3, v41, v2
	s_waitcnt lgkmcnt(0)
	v_add_f32_e32 v2, v2, v3
	ds_bpermute_b32 v3, v43, v2
	s_waitcnt lgkmcnt(0)
	v_add_f32_e32 v2, v2, v3
	ds_bpermute_b32 v3, v45, v2
	s_waitcnt lgkmcnt(0)
; __device__ __forceinline__ unsigned f2bf(float f) { unsigned u = __builtin_bit_cast(unsigned, f); return (u + 0x7fffu + ((u >> 16) & 1u)) >> 16; }
; __device__ __forceinline__ int crow(int r, int hi) { return (r & 3) + 8 * (r >> 2) + 4 * hi; }
; __device__ __forceinline__ int crow(int r, int hi) { return (r & 3) + 8 * (r >> 2) + 4 * hi; }
; __device__ __forceinline__ int crow(int r, int hi) { return (r & 3) + 8 * (r >> 2) + 4 * hi; }
; __device__ __forceinline__ int crow(int r, int hi) { return (r & 3) + 8 * (r >> 2) + 4 * hi; }
; __device__ __forceinline__ void pass3(const bf16* ZB, const float* hg_norm, const Bufs& B, bf16* YCB, int G, int tid) {
;     ...
;         const float hn0 = hg_norm[64 * h + r32], hn1 = hg_norm[64 * h + 32 + r32];
; #pragma unroll
;         for (int rg = 0; rg < 16; ++rg) { const size_t row = row0 + crow(rg, hh); const float o0 = acc[0][rg] + bf2f(B.INTRA[row * 256 + 64 * h + r32]), o1 = acc[1][rg] + bf2f(B.INTRA[row * 256 + 64 * h + 32 + r32]);
;             float ss = o0 * o0 + o1 * o1;
; #pragma unroll
;             for (int o = 1; o < 32; o <<= 1) ss += __shfl_xor(ss, o);
;             const float rinv = 1.0f / sqrtf(ss * (1.f / 64.f) + LN_EPS);
;             const float g0 = bf2f(ZB[row * ZLD + O_G + 64 * h + r32]), g1 = bf2f(ZB[row * ZLD + O_G + 64 * h + 32 + r32]);
;             YCB[row * 1024 + 256 + 64 * h + r32] = (bf16)f2bf(o0 * rinv * hn0 / (1.0f + __expf(-g0))); YCB[row * 1024 + 256 + 64 * h + 32 + r32] = (bf16)f2bf(o1 * rinv * hn1 / (1.0f + __expf(-g1))); }
	v_add_f32_e32 v2, v2, v3
	v_fmamk_f32 v2, v2, 0x3c800000, v1
	v_cmp_gt_f32_e32 vcc, s14, v2
	v_mul_f32_e32 v3, 0x4f800000, v2
	s_nop 0
	v_cndmask_b32_e32 v2, v2, v3, vcc
	v_sqrt_f32_e32 v3, v2
	s_nop 0
	v_add_u32_e32 v18, -1, v3
	v_fma_f32 v19, -v18, v3, v2
	v_cmp_ge_f32_e64 s[0:1], 0, v19
	v_add_u32_e32 v19, 1, v3
	s_nop 0
	v_cndmask_b32_e64 v18, v3, v18, s[0:1]
	v_fma_f32 v3, -v19, v3, v2
	v_cmp_lt_f32_e64 s[0:1], 0, v3
	s_nop 1
	v_cndmask_b32_e64 v3, v18, v19, s[0:1]
	v_mul_f32_e32 v18, 0x37800000, v3
	v_cndmask_b32_e32 v3, v3, v18, vcc
	v_cmp_class_f32_e32 vcc, v2, v223
	s_nop 1
	v_cndmask_b32_e32 v2, v3, v2, vcc
	v_div_scale_f32 v3, s[0:1], v2, v2, 1.0
	v_rcp_f32_e32 v18, v3
	s_nop 0
	v_fma_f32 v19, -v3, v18, 1.0
	v_fmac_f32_e32 v18, v19, v18
	v_div_scale_f32 v19, vcc, 1.0, v2, 1.0
	v_mul_f32_e32 v55, v19, v18
	v_fma_f32 v57, -v3, v55, v19
	v_fmac_f32_e32 v55, v57, v18
	v_fma_f32 v3, -v3, v55, v19
	v_div_fmas_f32 v3, v3, v18, v55
	v_div_fixup_f32 v55, v3, v2, 1.0
	v_lshlrev_b64 v[2:3], 11, v[76:77]
	v_lshl_add_u64 v[18:19], s[64:65], 0, v[2:3]
	v_lshl_add_u64 v[18:19], v[18:19], 0, s[12:13]
	v_lshl_add_u64 v[18:19], v[18:19], 0, v[72:73]
	v_mov_b32_e32 v57, v167
	v_lshl_add_u64 v[2:3], s[26:27], 0, v[2:3]
	v_mov_b32_e32 v18, v183
	v_mul_f32_e32 v19, v51, v55
	v_mul_f32_e32 v19, v49, v19
	v_lshl_add_u64 v[2:3], v[2:3], 0, s[12:13]
	v_lshl_add_u64 v[2:3], v[2:3], 0, v[72:73]
	s_nop 0
	v_lshlrev_b32_e32 v57, 16, v57
	v_mul_f32_e32 v51, 0xbfb8aa3b, v57
	v_exp_f32_e32 v51, v51
	s_nop 0
	v_lshlrev_b32_e32 v18, 16, v18
	v_mul_f32_e32 v18, 0xbfb8aa3b, v18
	v_exp_f32_e32 v18, v18
	v_add_f32_e32 v51, 1.0, v51
	v_div_scale_f32 v57, s[0:1], v51, v51, v19
	v_rcp_f32_e32 v59, v57
	v_add_f32_e32 v18, 1.0, v18
	v_fma_f32 v61, -v57, v59, 1.0
	v_fmac_f32_e32 v59, v61, v59
	v_div_scale_f32 v61, vcc, v19, v51, v19
	v_mul_f32_e32 v63, v61, v59
	v_fma_f32 v65, -v57, v63, v61
	v_fmac_f32_e32 v63, v65, v59
	v_fma_f32 v57, -v57, v63, v61
	v_div_fmas_f32 v57, v57, v59, v63
	v_div_fixup_f32 v19, v57, v51, v19
	v_bfe_u32 v51, v19, 16, 1
	v_add3_u32 v19, v19, v51, s66
	global_store_short_d16_hi v[2:3], v19, off offset:512
	v_mul_f32_e32 v19, v53, v55
	v_mul_f32_e32 v19, v47, v19
	v_div_scale_f32 v51, s[0:1], v18, v18, v19
	v_rcp_f32_e32 v53, v51
	s_nop 0
	v_fma_f32 v55, -v51, v53, 1.0
	v_fmac_f32_e32 v53, v55, v53
	v_div_scale_f32 v55, vcc, v19, v18, v19
	v_mul_f32_e32 v57, v55, v53
	v_fma_f32 v59, -v51, v57, v55
	v_fmac_f32_e32 v57, v59, v53
	v_fma_f32 v51, -v51, v57, v55
	v_div_fmas_f32 v51, v51, v53, v57
	v_div_fixup_f32 v18, v51, v18, v19
	v_bfe_u32 v19, v18, 16, 1
	v_add3_u32 v18, v18, v19, s66
	global_store_short_d16_hi v[2:3], v18, off offset:576
	v_mov_b32_e32 v3, s7
	v_or_b32_e32 v2, s6, v42
	v_lshlrev_b64 v[18:19], 9, v[2:3]
	v_lshl_add_u64 v[18:19], v[74:75], 0, v[18:19]
	v_mov_b32_e32 v51, v134
	v_lshlrev_b64 v[2:3], 11, v[2:3]
	v_mov_b32_e32 v18, v150
	s_nop 0
	v_lshlrev_b32_e32 v51, 16, v51
	v_add_f32_e32 v4, v4, v51
	s_nop 0
	v_lshlrev_b32_e32 v18, 16, v18
	v_add_f32_e32 v20, v20, v18
	v_mul_f32_e32 v18, v20, v20
	v_fmac_f32_e32 v18, v4, v4
	ds_bpermute_b32 v19, v35, v18
	s_waitcnt lgkmcnt(0)
	v_add_f32_e32 v18, v18, v19
	ds_bpermute_b32 v19, v37, v18
	s_waitcnt lgkmcnt(0)
	v_add_f32_e32 v18, v18, v19
	ds_bpermute_b32 v19, v41, v18
	s_waitcnt lgkmcnt(0)
	v_add_f32_e32 v18, v18, v19
	ds_bpermute_b32 v19, v43, v18
	s_waitcnt lgkmcnt(0)
	v_add_f32_e32 v18, v18, v19
	ds_bpermute_b32 v19, v45, v18
	s_waitcnt lgkmcnt(0)
	v_add_f32_e32 v18, v18, v19
	v_fmamk_f32 v18, v18, 0x3c800000, v1
	v_cmp_gt_f32_e32 vcc, s14, v18
	v_mul_f32_e32 v19, 0x4f800000, v18
	s_nop 0
	v_cndmask_b32_e32 v18, v18, v19, vcc
	v_sqrt_f32_e32 v19, v18
	s_nop 0
	v_add_u32_e32 v51, -1, v19
	v_fma_f32 v53, -v51, v19, v18
	v_cmp_ge_f32_e64 s[0:1], 0, v53
	v_add_u32_e32 v53, 1, v19
	s_nop 0
	v_cndmask_b32_e64 v51, v19, v51, s[0:1]
	v_fma_f32 v19, -v53, v19, v18
	v_cmp_lt_f32_e64 s[0:1], 0, v19
	s_nop 1
	v_cndmask_b32_e64 v19, v51, v53, s[0:1]
	v_mul_f32_e32 v51, 0x37800000, v19
	v_cndmask_b32_e32 v19, v19, v51, vcc
	v_cmp_class_f32_e32 vcc, v18, v223
	s_nop 1
	v_cndmask_b32_e32 v18, v19, v18, vcc
	v_div_scale_f32 v19, s[0:1], v18, v18, 1.0
	v_rcp_f32_e32 v51, v19
	s_nop 0
	v_fma_f32 v53, -v19, v51, 1.0
	v_fmac_f32_e32 v51, v53, v51
	v_div_scale_f32 v53, vcc, 1.0, v18, 1.0
	v_mul_f32_e32 v55, v53, v51
	v_fma_f32 v57, -v19, v55, v53
	v_fmac_f32_e32 v55, v57, v51
	v_fma_f32 v19, -v19, v55, v53
	v_div_fmas_f32 v19, v19, v51, v55
	v_div_fixup_f32 v51, v19, v18, 1.0
	v_lshl_add_u64 v[18:19], s[64:65], 0, v[2:3]
	v_lshl_add_u64 v[18:19], v[18:19], 0, s[12:13]
	v_lshl_add_u64 v[18:19], v[18:19], 0, v[72:73]
	v_mov_b32_e32 v53, v168
	v_mul_f32_e32 v4, v4, v51
	v_mov_b32_e32 v18, v184
	v_mul_f32_e32 v4, v49, v4
	v_lshl_add_u64 v[2:3], s[26:27], 0, v[2:3]
	v_lshl_add_u64 v[2:3], v[2:3], 0, s[12:13]
	v_lshl_add_u64 v[2:3], v[2:3], 0, v[72:73]
	s_nop 0
	v_lshlrev_b32_e32 v53, 16, v53
	v_mul_f32_e32 v19, 0xbfb8aa3b, v53
	v_exp_f32_e32 v19, v19
	s_nop 0
	v_lshlrev_b32_e32 v18, 16, v18
	v_mul_f32_e32 v18, 0xbfb8aa3b, v18
	v_exp_f32_e32 v18, v18
	v_add_f32_e32 v19, 1.0, v19
	v_div_scale_f32 v53, s[0:1], v19, v19, v4
	v_rcp_f32_e32 v55, v53
	v_add_f32_e32 v18, 1.0, v18
	v_fma_f32 v57, -v53, v55, 1.0
	v_fmac_f32_e32 v55, v57, v55
	v_div_scale_f32 v57, vcc, v4, v19, v4
	v_mul_f32_e32 v59, v57, v55
	v_fma_f32 v61, -v53, v59, v57
	v_fmac_f32_e32 v59, v61, v55
	v_fma_f32 v53, -v53, v59, v57
	v_div_fmas_f32 v53, v53, v55, v59
	v_div_fixup_f32 v4, v53, v19, v4
	v_bfe_u32 v19, v4, 16, 1
	v_add3_u32 v4, v4, v19, s66
	global_store_short_d16_hi v[2:3], v4, off offset:512
	v_mul_f32_e32 v4, v20, v51
	v_mul_f32_e32 v4, v47, v4
	v_div_scale_f32 v19, s[0:1], v18, v18, v4
	v_rcp_f32_e32 v20, v19
	s_nop 0
	v_fma_f32 v51, -v19, v20, 1.0
	v_fmac_f32_e32 v20, v51, v20
	v_div_scale_f32 v51, vcc, v4, v18, v4
	v_mul_f32_e32 v53, v51, v20
	v_fma_f32 v55, -v19, v53, v51
	v_fmac_f32_e32 v53, v55, v20
	v_fma_f32 v19, -v19, v53, v51
	v_div_fmas_f32 v19, v19, v20, v53
	v_div_fixup_f32 v4, v19, v18, v4
	v_bfe_u32 v18, v4, 16, 1
	v_add3_u32 v4, v4, v18, s66
	global_store_short_d16_hi v[2:3], v4, off offset:576
	v_mov_b32_e32 v3, s7
	v_or_b32_e32 v2, s6, v44
	v_lshlrev_b64 v[18:19], 9, v[2:3]
	v_lshl_add_u64 v[18:19], v[74:75], 0, v[18:19]
	v_mov_b32_e32 v4, v135
	v_lshlrev_b64 v[2:3], 11, v[2:3]
	s_nop 0
	v_lshlrev_b32_e32 v4, 16, v4
	v_add_f32_e32 v20, v5, v4
	v_mov_b32_e32 v4, v151
	s_nop 0
	v_lshlrev_b32_e32 v4, 16, v4
	v_add_f32_e32 v18, v21, v4
	v_mul_f32_e32 v4, v18, v18
	v_fmac_f32_e32 v4, v20, v20
	ds_bpermute_b32 v5, v35, v4
	s_waitcnt lgkmcnt(0)
; __device__ __forceinline__ unsigned f2bf(float f) { unsigned u = __builtin_bit_cast(unsigned, f); return (u + 0x7fffu + ((u >> 16) & 1u)) >> 16; }
; __device__ __forceinline__ int crow(int r, int hi) { return (r & 3) + 8 * (r >> 2) + 4 * hi; }
; __device__ __forceinline__ int crow(int r, int hi) { return (r & 3) + 8 * (r >> 2) + 4 * hi; }
; __device__ __forceinline__ int crow(int r, int hi) { return (r & 3) + 8 * (r >> 2) + 4 * hi; }
; __device__ __forceinline__ int crow(int r, int hi) { return (r & 3) + 8 * (r >> 2) + 4 * hi; }
; __device__ __forceinline__ void pass3(const bf16* ZB, const float* hg_norm, const Bufs& B, bf16* YCB, int G, int tid) {
;     ...
;         const float hn0 = hg_norm[64 * h + r32], hn1 = hg_norm[64 * h + 32 + r32];
; #pragma unroll
;         for (int rg = 0; rg < 16; ++rg) { const size_t row = row0 + crow(rg, hh); const float o0 = acc[0][rg] + bf2f(B.INTRA[row * 256 + 64 * h + r32]), o1 = acc[1][rg] + bf2f(B.INTRA[row * 256 + 64 * h + 32 + r32]);
;             float ss = o0 * o0 + o1 * o1;
; #pragma unroll
;             for (int o = 1; o < 32; o <<= 1) ss += __shfl_xor(ss, o);
;             const float rinv = 1.0f / sqrtf(ss * (1.f / 64.f) + LN_EPS);
;             const float g0 = bf2f(ZB[row * ZLD + O_G + 64 * h + r32]), g1 = bf2f(ZB[row * ZLD + O_G + 64 * h + 32 + r32]);
;             YCB[row * 1024 + 256 + 64 * h + r32] = (bf16)f2bf(o0 * rinv * hn0 / (1.0f + __expf(-g0))); YCB[row * 1024 + 256 + 64 * h + 32 + r32] = (bf16)f2bf(o1 * rinv * hn1 / (1.0f + __expf(-g1))); }
	v_add_f32_e32 v4, v4, v5
	ds_bpermute_b32 v5, v37, v4
	s_waitcnt lgkmcnt(0)
	v_add_f32_e32 v4, v4, v5
	ds_bpermute_b32 v5, v41, v4
	s_waitcnt lgkmcnt(0)
	v_add_f32_e32 v4, v4, v5
	ds_bpermute_b32 v5, v43, v4
	s_waitcnt lgkmcnt(0)
	v_add_f32_e32 v4, v4, v5
	ds_bpermute_b32 v5, v45, v4
	s_waitcnt lgkmcnt(0)
	v_add_f32_e32 v4, v4, v5
	v_fmamk_f32 v4, v4, 0x3c800000, v1
	v_cmp_gt_f32_e32 vcc, s14, v4
	v_mul_f32_e32 v5, 0x4f800000, v4
	s_nop 0
	v_cndmask_b32_e32 v4, v4, v5, vcc
	v_sqrt_f32_e32 v5, v4
	s_nop 0
	v_add_u32_e32 v19, -1, v5
	v_fma_f32 v21, -v19, v5, v4
	v_cmp_ge_f32_e64 s[0:1], 0, v21
	v_add_u32_e32 v21, 1, v5
	s_nop 0
	v_cndmask_b32_e64 v19, v5, v19, s[0:1]
	v_fma_f32 v5, -v21, v5, v4
	v_cmp_lt_f32_e64 s[0:1], 0, v5
	s_nop 1
	v_cndmask_b32_e64 v5, v19, v21, s[0:1]
	v_mul_f32_e32 v19, 0x37800000, v5
	v_cndmask_b32_e32 v5, v5, v19, vcc
	v_cmp_class_f32_e32 vcc, v4, v223
	s_nop 1
	v_cndmask_b32_e32 v4, v5, v4, vcc
	v_div_scale_f32 v5, s[0:1], v4, v4, 1.0
	v_rcp_f32_e32 v19, v5
	s_nop 0
	v_fma_f32 v21, -v5, v19, 1.0
	v_fmac_f32_e32 v19, v21, v19
	v_div_scale_f32 v21, vcc, 1.0, v4, 1.0
	v_mul_f32_e32 v51, v21, v19
	v_fma_f32 v53, -v5, v51, v21
	v_fmac_f32_e32 v51, v53, v19
	v_fma_f32 v5, -v5, v51, v21
	v_div_fmas_f32 v5, v5, v19, v51
	v_div_fixup_f32 v19, v5, v4, 1.0
	v_lshl_add_u64 v[4:5], s[64:65], 0, v[2:3]
	v_lshl_add_u64 v[4:5], v[4:5], 0, s[12:13]
	v_lshl_add_u64 v[4:5], v[4:5], 0, v[72:73]
	v_mov_b32_e32 v21, v169
	v_lshl_add_u64 v[2:3], s[26:27], 0, v[2:3]
	v_mov_b32_e32 v4, v185
	v_mul_f32_e32 v5, v20, v19
	v_mul_f32_e32 v5, v49, v5
	v_lshl_add_u64 v[2:3], v[2:3], 0, s[12:13]
	v_lshl_add_u64 v[2:3], v[2:3], 0, v[72:73]
	s_nop 0
	v_lshlrev_b32_e32 v21, 16, v21
	v_mul_f32_e32 v20, 0xbfb8aa3b, v21
	v_exp_f32_e32 v20, v20
	s_nop 0
	v_lshlrev_b32_e32 v4, 16, v4
	v_mul_f32_e32 v4, 0xbfb8aa3b, v4
	v_exp_f32_e32 v4, v4
	v_add_f32_e32 v20, 1.0, v20
	v_div_scale_f32 v21, s[0:1], v20, v20, v5
	v_rcp_f32_e32 v51, v21
	v_add_f32_e32 v4, 1.0, v4
	v_fma_f32 v53, -v21, v51, 1.0
	v_fmac_f32_e32 v51, v53, v51
	v_div_scale_f32 v53, vcc, v5, v20, v5
	v_mul_f32_e32 v55, v53, v51
	v_fma_f32 v57, -v21, v55, v53
	v_fmac_f32_e32 v55, v57, v51
	v_fma_f32 v21, -v21, v55, v53
	v_div_fmas_f32 v21, v21, v51, v55
	v_div_fixup_f32 v5, v21, v20, v5
	v_bfe_u32 v20, v5, 16, 1
	v_add3_u32 v5, v5, v20, s66
	global_store_short_d16_hi v[2:3], v5, off offset:512
	v_mul_f32_e32 v5, v18, v19
	v_mul_f32_e32 v5, v47, v5
	v_div_scale_f32 v18, s[0:1], v4, v4, v5
	v_rcp_f32_e32 v19, v18
	s_nop 0
	v_fma_f32 v20, -v18, v19, 1.0
	v_fmac_f32_e32 v19, v20, v19
	v_div_scale_f32 v20, vcc, v5, v4, v5
	v_mul_f32_e32 v21, v20, v19
	v_fma_f32 v51, -v18, v21, v20
	v_fmac_f32_e32 v21, v51, v19
	v_fma_f32 v18, -v18, v21, v20
	v_div_fmas_f32 v18, v18, v19, v21
	v_div_fixup_f32 v4, v18, v4, v5
	v_bfe_u32 v5, v4, 16, 1
	v_add3_u32 v4, v4, v5, s66
	global_store_short_d16_hi v[2:3], v4, off offset:576
	v_mov_b32_e32 v3, s7
	v_or_b32_e32 v2, s6, v46
	v_lshlrev_b64 v[4:5], 9, v[2:3]
	v_lshl_add_u64 v[4:5], v[74:75], 0, v[4:5]
	v_mov_b32_e32 v18, v136
	v_lshlrev_b64 v[2:3], 11, v[2:3]
	v_mov_b32_e32 v4, v152
	s_nop 0
	v_lshlrev_b32_e32 v18, 16, v18
	v_add_f32_e32 v6, v6, v18
	s_nop 0
	v_lshlrev_b32_e32 v4, 16, v4
	v_add_f32_e32 v18, v22, v4
	v_mul_f32_e32 v4, v18, v18
	v_fmac_f32_e32 v4, v6, v6
	ds_bpermute_b32 v5, v35, v4
	s_waitcnt lgkmcnt(0)
	v_add_f32_e32 v4, v4, v5
	ds_bpermute_b32 v5, v37, v4
	s_waitcnt lgkmcnt(0)
	v_add_f32_e32 v4, v4, v5
	ds_bpermute_b32 v5, v41, v4
	s_waitcnt lgkmcnt(0)
	v_add_f32_e32 v4, v4, v5
	ds_bpermute_b32 v5, v43, v4
	s_waitcnt lgkmcnt(0)
	v_add_f32_e32 v4, v4, v5
	ds_bpermute_b32 v5, v45, v4
	s_waitcnt lgkmcnt(0)
	v_add_f32_e32 v4, v4, v5
	v_fmamk_f32 v4, v4, 0x3c800000, v1
	v_cmp_gt_f32_e32 vcc, s14, v4
	v_mul_f32_e32 v5, 0x4f800000, v4
	s_nop 0
	v_cndmask_b32_e32 v4, v4, v5, vcc
	v_sqrt_f32_e32 v5, v4
	s_nop 0
	v_add_u32_e32 v19, -1, v5
	v_fma_f32 v20, -v19, v5, v4
	v_cmp_ge_f32_e64 s[0:1], 0, v20
	v_add_u32_e32 v20, 1, v5
	s_nop 0
	v_cndmask_b32_e64 v19, v5, v19, s[0:1]
	v_fma_f32 v5, -v20, v5, v4
	v_cmp_lt_f32_e64 s[0:1], 0, v5
	s_nop 1
	v_cndmask_b32_e64 v5, v19, v20, s[0:1]
	v_mul_f32_e32 v19, 0x37800000, v5
	v_cndmask_b32_e32 v5, v5, v19, vcc
	v_cmp_class_f32_e32 vcc, v4, v223
	s_nop 1
	v_cndmask_b32_e32 v4, v5, v4, vcc
	v_div_scale_f32 v5, s[0:1], v4, v4, 1.0
	v_rcp_f32_e32 v19, v5
	s_nop 0
	v_fma_f32 v20, -v5, v19, 1.0
	v_fmac_f32_e32 v19, v20, v19
	v_div_scale_f32 v20, vcc, 1.0, v4, 1.0
	v_mul_f32_e32 v21, v20, v19
	v_fma_f32 v22, -v5, v21, v20
	v_fmac_f32_e32 v21, v22, v19
	v_fma_f32 v5, -v5, v21, v20
	v_div_fmas_f32 v5, v5, v19, v21
	v_div_fixup_f32 v19, v5, v4, 1.0
	v_lshl_add_u64 v[4:5], s[64:65], 0, v[2:3]
	v_lshl_add_u64 v[4:5], v[4:5], 0, s[12:13]
	v_lshl_add_u64 v[4:5], v[4:5], 0, v[72:73]
	v_mov_b32_e32 v20, v170
	v_lshl_add_u64 v[2:3], s[26:27], 0, v[2:3]
	v_mov_b32_e32 v4, v186
	v_mul_f32_e32 v5, v6, v19
	v_mul_f32_e32 v5, v49, v5
	v_lshl_add_u64 v[2:3], v[2:3], 0, s[12:13]
	v_lshl_add_u64 v[2:3], v[2:3], 0, v[72:73]
	s_nop 0
	v_lshlrev_b32_e32 v20, 16, v20
	v_mul_f32_e32 v6, 0xbfb8aa3b, v20
	v_exp_f32_e32 v6, v6
	s_nop 0
	v_lshlrev_b32_e32 v4, 16, v4
	v_mul_f32_e32 v4, 0xbfb8aa3b, v4
	v_exp_f32_e32 v4, v4
	v_add_f32_e32 v6, 1.0, v6
	v_div_scale_f32 v20, s[0:1], v6, v6, v5
	v_rcp_f32_e32 v21, v20
	v_add_f32_e32 v4, 1.0, v4
	v_fma_f32 v22, -v20, v21, 1.0
	v_fmac_f32_e32 v21, v22, v21
	v_div_scale_f32 v22, vcc, v5, v6, v5
	v_mul_f32_e32 v51, v22, v21
	v_fma_f32 v53, -v20, v51, v22
	v_fmac_f32_e32 v51, v53, v21
	v_fma_f32 v20, -v20, v51, v22
	v_div_fmas_f32 v20, v20, v21, v51
	v_div_fixup_f32 v5, v20, v6, v5
	v_bfe_u32 v6, v5, 16, 1
	v_add3_u32 v5, v5, v6, s66
	global_store_short_d16_hi v[2:3], v5, off offset:512
	v_mul_f32_e32 v5, v18, v19
	v_mul_f32_e32 v5, v47, v5
	v_div_scale_f32 v6, s[0:1], v4, v4, v5
	v_rcp_f32_e32 v18, v6
	s_nop 0
	v_fma_f32 v19, -v6, v18, 1.0
	v_fmac_f32_e32 v18, v19, v18
	v_div_scale_f32 v19, vcc, v5, v4, v5
	v_mul_f32_e32 v20, v19, v18
	v_fma_f32 v21, -v6, v20, v19
	v_fmac_f32_e32 v20, v21, v18
	v_fma_f32 v6, -v6, v20, v19
	v_div_fmas_f32 v6, v6, v18, v20
	v_div_fixup_f32 v4, v6, v4, v5
	v_bfe_u32 v5, v4, 16, 1
	v_add3_u32 v4, v4, v5, s66
	global_store_short_d16_hi v[2:3], v4, off offset:576
	v_mov_b32_e32 v3, s7
	v_or_b32_e32 v2, s6, v48
	v_lshlrev_b64 v[4:5], 9, v[2:3]
	v_lshl_add_u64 v[4:5], v[74:75], 0, v[4:5]
	v_mov_b32_e32 v6, v137
	v_lshlrev_b64 v[2:3], 11, v[2:3]
	v_mov_b32_e32 v4, v153
	s_nop 0
	v_lshlrev_b32_e32 v6, 16, v6
	v_add_f32_e32 v6, v7, v6
	s_nop 0
	v_lshlrev_b32_e32 v4, 16, v4
	v_add_f32_e32 v7, v23, v4
	v_mul_f32_e32 v4, v7, v7
	v_fmac_f32_e32 v4, v6, v6
	ds_bpermute_b32 v5, v35, v4
	s_waitcnt lgkmcnt(0)
; __device__ __forceinline__ unsigned f2bf(float f) { unsigned u = __builtin_bit_cast(unsigned, f); return (u + 0x7fffu + ((u >> 16) & 1u)) >> 16; }
; __device__ __forceinline__ int crow(int r, int hi) { return (r & 3) + 8 * (r >> 2) + 4 * hi; }
; __device__ __forceinline__ int crow(int r, int hi) { return (r & 3) + 8 * (r >> 2) + 4 * hi; }
; __device__ __forceinline__ int crow(int r, int hi) { return (r & 3) + 8 * (r >> 2) + 4 * hi; }
; __device__ __forceinline__ int crow(int r, int hi) { return (r & 3) + 8 * (r >> 2) + 4 * hi; }
; __device__ __forceinline__ void pass3(const bf16* ZB, const float* hg_norm, const Bufs& B, bf16* YCB, int G, int tid) {
;     ...
;         const float hn0 = hg_norm[64 * h + r32], hn1 = hg_norm[64 * h + 32 + r32];
; #pragma unroll
;         for (int rg = 0; rg < 16; ++rg) { const size_t row = row0 + crow(rg, hh); const float o0 = acc[0][rg] + bf2f(B.INTRA[row * 256 + 64 * h + r32]), o1 = acc[1][rg] + bf2f(B.INTRA[row * 256 + 64 * h + 32 + r32]);
;             float ss = o0 * o0 + o1 * o1;
; #pragma unroll
;             for (int o = 1; o < 32; o <<= 1) ss += __shfl_xor(ss, o);
;             const float rinv = 1.0f / sqrtf(ss * (1.f / 64.f) + LN_EPS);
;             const float g0 = bf2f(ZB[row * ZLD + O_G + 64 * h + r32]), g1 = bf2f(ZB[row * ZLD + O_G + 64 * h + 32 + r32]);
;             YCB[row * 1024 + 256 + 64 * h + r32] = (bf16)f2bf(o0 * rinv * hn0 / (1.0f + __expf(-g0))); YCB[row * 1024 + 256 + 64 * h + 32 + r32] = (bf16)f2bf(o1 * rinv * hn1 / (1.0f + __expf(-g1))); }
	v_add_f32_e32 v4, v4, v5
	ds_bpermute_b32 v5, v37, v4
	s_waitcnt lgkmcnt(0)
	v_add_f32_e32 v4, v4, v5
	ds_bpermute_b32 v5, v41, v4
	s_waitcnt lgkmcnt(0)
	v_add_f32_e32 v4, v4, v5
	ds_bpermute_b32 v5, v43, v4
	s_waitcnt lgkmcnt(0)
	v_add_f32_e32 v4, v4, v5
	ds_bpermute_b32 v5, v45, v4
	s_waitcnt lgkmcnt(0)
	v_add_f32_e32 v4, v4, v5
	v_fmamk_f32 v4, v4, 0x3c800000, v1
	v_cmp_gt_f32_e32 vcc, s14, v4
	v_mul_f32_e32 v5, 0x4f800000, v4
	s_nop 0
	v_cndmask_b32_e32 v4, v4, v5, vcc
	v_sqrt_f32_e32 v5, v4
	s_nop 0
	v_add_u32_e32 v18, -1, v5
	v_fma_f32 v19, -v18, v5, v4
	v_cmp_ge_f32_e64 s[0:1], 0, v19
	v_add_u32_e32 v19, 1, v5
	s_nop 0
	v_cndmask_b32_e64 v18, v5, v18, s[0:1]
	v_fma_f32 v5, -v19, v5, v4
	v_cmp_lt_f32_e64 s[0:1], 0, v5
	s_nop 1
	v_cndmask_b32_e64 v5, v18, v19, s[0:1]
	v_mul_f32_e32 v18, 0x37800000, v5
	v_cndmask_b32_e32 v5, v5, v18, vcc
	v_cmp_class_f32_e32 vcc, v4, v223
	s_nop 1
	v_cndmask_b32_e32 v4, v5, v4, vcc
	v_div_scale_f32 v5, s[0:1], v4, v4, 1.0
	v_rcp_f32_e32 v18, v5
	s_nop 0
	v_fma_f32 v19, -v5, v18, 1.0
	v_fmac_f32_e32 v18, v19, v18
	v_div_scale_f32 v19, vcc, 1.0, v4, 1.0
	v_mul_f32_e32 v20, v19, v18
	v_fma_f32 v21, -v5, v20, v19
	v_fmac_f32_e32 v20, v21, v18
	v_fma_f32 v5, -v5, v20, v19
	v_div_fmas_f32 v5, v5, v18, v20
	v_div_fixup_f32 v18, v5, v4, 1.0
	v_lshl_add_u64 v[4:5], s[64:65], 0, v[2:3]
	v_lshl_add_u64 v[4:5], v[4:5], 0, s[12:13]
	v_lshl_add_u64 v[4:5], v[4:5], 0, v[72:73]
	v_mov_b32_e32 v19, v171
	v_lshl_add_u64 v[2:3], s[26:27], 0, v[2:3]
	v_mov_b32_e32 v4, v187
	v_mul_f32_e32 v5, v6, v18
	v_mul_f32_e32 v5, v49, v5
	v_lshl_add_u64 v[2:3], v[2:3], 0, s[12:13]
	v_lshl_add_u64 v[2:3], v[2:3], 0, v[72:73]
	s_nop 0
	v_lshlrev_b32_e32 v19, 16, v19
	v_mul_f32_e32 v6, 0xbfb8aa3b, v19
	v_exp_f32_e32 v6, v6
	s_nop 0
	v_lshlrev_b32_e32 v4, 16, v4
	v_mul_f32_e32 v4, 0xbfb8aa3b, v4
	v_exp_f32_e32 v4, v4
	v_add_f32_e32 v6, 1.0, v6
	v_div_scale_f32 v19, s[0:1], v6, v6, v5
	v_rcp_f32_e32 v20, v19
	v_add_f32_e32 v4, 1.0, v4
	v_fma_f32 v21, -v19, v20, 1.0
	v_fmac_f32_e32 v20, v21, v20
	v_div_scale_f32 v21, vcc, v5, v6, v5
	v_mul_f32_e32 v22, v21, v20
	v_fma_f32 v23, -v19, v22, v21
	v_fmac_f32_e32 v22, v23, v20
	v_fma_f32 v19, -v19, v22, v21
	v_div_fmas_f32 v19, v19, v20, v22
	v_div_fixup_f32 v5, v19, v6, v5
	v_bfe_u32 v6, v5, 16, 1
	v_add3_u32 v5, v5, v6, s66
	global_store_short_d16_hi v[2:3], v5, off offset:512
	v_mul_f32_e32 v5, v7, v18
	v_mul_f32_e32 v5, v47, v5
	v_div_scale_f32 v6, s[0:1], v4, v4, v5
	v_rcp_f32_e32 v7, v6
	s_nop 0
	v_fma_f32 v18, -v6, v7, 1.0
	v_fmac_f32_e32 v7, v18, v7
	v_div_scale_f32 v18, vcc, v5, v4, v5
	v_mul_f32_e32 v19, v18, v7
	v_fma_f32 v20, -v6, v19, v18
	v_fmac_f32_e32 v19, v20, v7
	v_fma_f32 v6, -v6, v19, v18
	v_div_fmas_f32 v6, v6, v7, v19
	v_div_fixup_f32 v4, v6, v4, v5
	v_bfe_u32 v5, v4, 16, 1
	v_add3_u32 v4, v4, v5, s66
	global_store_short_d16_hi v[2:3], v4, off offset:576
	v_mov_b32_e32 v3, s7
	v_or_b32_e32 v2, s6, v50
	v_lshlrev_b64 v[4:5], 9, v[2:3]
	v_lshl_add_u64 v[4:5], v[74:75], 0, v[4:5]
	v_mov_b32_e32 v6, v138
	v_lshlrev_b64 v[2:3], 11, v[2:3]
	v_mov_b32_e32 v4, v154
	s_nop 0
	v_lshlrev_b32_e32 v6, 16, v6
	v_add_f32_e32 v6, v8, v6
	s_nop 0
	v_lshlrev_b32_e32 v4, 16, v4
	v_add_f32_e32 v7, v24, v4
	v_mul_f32_e32 v4, v7, v7
	v_fmac_f32_e32 v4, v6, v6
	ds_bpermute_b32 v5, v35, v4
	s_waitcnt lgkmcnt(0)
	v_add_f32_e32 v4, v4, v5
	ds_bpermute_b32 v5, v37, v4
	s_waitcnt lgkmcnt(0)
	v_add_f32_e32 v4, v4, v5
	ds_bpermute_b32 v5, v41, v4
	s_waitcnt lgkmcnt(0)
	v_add_f32_e32 v4, v4, v5
	ds_bpermute_b32 v5, v43, v4
	s_waitcnt lgkmcnt(0)
	v_add_f32_e32 v4, v4, v5
	ds_bpermute_b32 v5, v45, v4
	s_waitcnt lgkmcnt(0)
	v_add_f32_e32 v4, v4, v5
	v_fmamk_f32 v4, v4, 0x3c800000, v1
	v_cmp_gt_f32_e32 vcc, s14, v4
	v_mul_f32_e32 v5, 0x4f800000, v4
	s_nop 0
	v_cndmask_b32_e32 v4, v4, v5, vcc
	v_sqrt_f32_e32 v5, v4
	s_nop 0
	v_add_u32_e32 v8, -1, v5
	v_fma_f32 v18, -v8, v5, v4
	v_cmp_ge_f32_e64 s[0:1], 0, v18
	v_add_u32_e32 v18, 1, v5
	s_nop 0
	v_cndmask_b32_e64 v8, v5, v8, s[0:1]
	v_fma_f32 v5, -v18, v5, v4
	v_cmp_lt_f32_e64 s[0:1], 0, v5
	s_nop 1
	v_cndmask_b32_e64 v5, v8, v18, s[0:1]
	v_mul_f32_e32 v8, 0x37800000, v5
	v_cndmask_b32_e32 v5, v5, v8, vcc
	v_cmp_class_f32_e32 vcc, v4, v223
	s_nop 1
	v_cndmask_b32_e32 v4, v5, v4, vcc
	v_div_scale_f32 v5, s[0:1], v4, v4, 1.0
	v_rcp_f32_e32 v8, v5
	s_nop 0
	v_fma_f32 v18, -v5, v8, 1.0
	v_fmac_f32_e32 v8, v18, v8
	v_div_scale_f32 v18, vcc, 1.0, v4, 1.0
	v_mul_f32_e32 v19, v18, v8
	v_fma_f32 v20, -v5, v19, v18
	v_fmac_f32_e32 v19, v20, v8
	v_fma_f32 v5, -v5, v19, v18
	v_div_fmas_f32 v5, v5, v8, v19
	v_div_fixup_f32 v8, v5, v4, 1.0
	v_lshl_add_u64 v[4:5], s[64:65], 0, v[2:3]
	v_lshl_add_u64 v[4:5], v[4:5], 0, s[12:13]
	v_lshl_add_u64 v[4:5], v[4:5], 0, v[72:73]
	v_mov_b32_e32 v18, v172
	v_lshl_add_u64 v[2:3], s[26:27], 0, v[2:3]
	v_mov_b32_e32 v4, v188
	v_mul_f32_e32 v5, v6, v8
	v_mul_f32_e32 v5, v49, v5
	v_lshl_add_u64 v[2:3], v[2:3], 0, s[12:13]
	v_lshl_add_u64 v[2:3], v[2:3], 0, v[72:73]
	s_nop 0
	v_lshlrev_b32_e32 v18, 16, v18
	v_mul_f32_e32 v6, 0xbfb8aa3b, v18
	v_exp_f32_e32 v6, v6
	s_nop 0
	v_lshlrev_b32_e32 v4, 16, v4
	v_mul_f32_e32 v4, 0xbfb8aa3b, v4
	v_exp_f32_e32 v4, v4
	v_add_f32_e32 v6, 1.0, v6
	v_div_scale_f32 v18, s[0:1], v6, v6, v5
	v_rcp_f32_e32 v19, v18
	v_add_f32_e32 v4, 1.0, v4
	v_fma_f32 v20, -v18, v19, 1.0
	v_fmac_f32_e32 v19, v20, v19
	v_div_scale_f32 v20, vcc, v5, v6, v5
	v_mul_f32_e32 v21, v20, v19
	v_fma_f32 v22, -v18, v21, v20
	v_fmac_f32_e32 v21, v22, v19
	v_fma_f32 v18, -v18, v21, v20
	v_div_fmas_f32 v18, v18, v19, v21
	v_div_fixup_f32 v5, v18, v6, v5
	v_bfe_u32 v6, v5, 16, 1
	v_add3_u32 v5, v5, v6, s66
	global_store_short_d16_hi v[2:3], v5, off offset:512
	v_mul_f32_e32 v5, v7, v8
	v_mul_f32_e32 v5, v47, v5
	v_div_scale_f32 v6, s[0:1], v4, v4, v5
	v_rcp_f32_e32 v7, v6
	s_nop 0
	v_fma_f32 v8, -v6, v7, 1.0
	v_fmac_f32_e32 v7, v8, v7
	v_div_scale_f32 v8, vcc, v5, v4, v5
	v_mul_f32_e32 v18, v8, v7
	v_fma_f32 v19, -v6, v18, v8
	v_fmac_f32_e32 v18, v19, v7
	v_fma_f32 v6, -v6, v18, v8
	v_div_fmas_f32 v6, v6, v7, v18
	v_div_fixup_f32 v4, v6, v4, v5
	v_bfe_u32 v5, v4, 16, 1
	v_add3_u32 v4, v4, v5, s66
	global_store_short_d16_hi v[2:3], v4, off offset:576
	v_mov_b32_e32 v3, s7
	v_or_b32_e32 v2, s6, v52
	v_lshlrev_b64 v[4:5], 9, v[2:3]
	v_lshl_add_u64 v[4:5], v[74:75], 0, v[4:5]
	v_mov_b32_e32 v6, v139
	v_lshlrev_b64 v[2:3], 11, v[2:3]
	v_mov_b32_e32 v4, v155
	s_nop 0
	v_lshlrev_b32_e32 v6, 16, v6
	v_add_f32_e32 v6, v9, v6
	s_nop 0
	v_lshlrev_b32_e32 v4, 16, v4
	v_add_f32_e32 v7, v25, v4
	v_mul_f32_e32 v4, v7, v7
	v_fmac_f32_e32 v4, v6, v6
	ds_bpermute_b32 v5, v35, v4
	s_waitcnt lgkmcnt(0)
; __device__ __forceinline__ unsigned f2bf(float f) { unsigned u = __builtin_bit_cast(unsigned, f); return (u + 0x7fffu + ((u >> 16) & 1u)) >> 16; }
; __device__ __forceinline__ int crow(int r, int hi) { return (r & 3) + 8 * (r >> 2) + 4 * hi; }
; __device__ __forceinline__ int crow(int r, int hi) { return (r & 3) + 8 * (r >> 2) + 4 * hi; }
; __device__ __forceinline__ int crow(int r, int hi) { return (r & 3) + 8 * (r >> 2) + 4 * hi; }
; __device__ __forceinline__ int crow(int r, int hi) { return (r & 3) + 8 * (r >> 2) + 4 * hi; }
; __device__ __forceinline__ void pass3(const bf16* ZB, const float* hg_norm, const Bufs& B, bf16* YCB, int G, int tid) {
;     ...
;         const float hn0 = hg_norm[64 * h + r32], hn1 = hg_norm[64 * h + 32 + r32];
; #pragma unroll
;         for (int rg = 0; rg < 16; ++rg) { const size_t row = row0 + crow(rg, hh); const float o0 = acc[0][rg] + bf2f(B.INTRA[row * 256 + 64 * h + r32]), o1 = acc[1][rg] + bf2f(B.INTRA[row * 256 + 64 * h + 32 + r32]);
;             float ss = o0 * o0 + o1 * o1;
; #pragma unroll
;             for (int o = 1; o < 32; o <<= 1) ss += __shfl_xor(ss, o);
;             const float rinv = 1.0f / sqrtf(ss * (1.f / 64.f) + LN_EPS);
;             const float g0 = bf2f(ZB[row * ZLD + O_G + 64 * h + r32]), g1 = bf2f(ZB[row * ZLD + O_G + 64 * h + 32 + r32]);
;             YCB[row * 1024 + 256 + 64 * h + r32] = (bf16)f2bf(o0 * rinv * hn0 / (1.0f + __expf(-g0))); YCB[row * 1024 + 256 + 64 * h + 32 + r32] = (bf16)f2bf(o1 * rinv * hn1 / (1.0f + __expf(-g1))); }
	v_add_f32_e32 v4, v4, v5
	ds_bpermute_b32 v5, v37, v4
	s_waitcnt lgkmcnt(0)
	v_add_f32_e32 v4, v4, v5
	ds_bpermute_b32 v5, v41, v4
	s_waitcnt lgkmcnt(0)
	v_add_f32_e32 v4, v4, v5
	ds_bpermute_b32 v5, v43, v4
	s_waitcnt lgkmcnt(0)
	v_add_f32_e32 v4, v4, v5
	ds_bpermute_b32 v5, v45, v4
	s_waitcnt lgkmcnt(0)
	v_add_f32_e32 v4, v4, v5
	v_fmamk_f32 v4, v4, 0x3c800000, v1
	v_cmp_gt_f32_e32 vcc, s14, v4
	v_mul_f32_e32 v5, 0x4f800000, v4
	s_nop 0
	v_cndmask_b32_e32 v4, v4, v5, vcc
	v_sqrt_f32_e32 v5, v4
	s_nop 0
	v_add_u32_e32 v8, -1, v5
	v_fma_f32 v9, -v8, v5, v4
	v_cmp_ge_f32_e64 s[0:1], 0, v9
	v_add_u32_e32 v9, 1, v5
	s_nop 0
	v_cndmask_b32_e64 v8, v5, v8, s[0:1]
	v_fma_f32 v5, -v9, v5, v4
	v_cmp_lt_f32_e64 s[0:1], 0, v5
	s_nop 1
	v_cndmask_b32_e64 v5, v8, v9, s[0:1]
	v_mul_f32_e32 v8, 0x37800000, v5
	v_cndmask_b32_e32 v5, v5, v8, vcc
	v_cmp_class_f32_e32 vcc, v4, v223
	s_nop 1
	v_cndmask_b32_e32 v4, v5, v4, vcc
	v_div_scale_f32 v5, s[0:1], v4, v4, 1.0
	v_rcp_f32_e32 v8, v5
	s_nop 0
	v_fma_f32 v9, -v5, v8, 1.0
	v_fmac_f32_e32 v8, v9, v8
	v_div_scale_f32 v9, vcc, 1.0, v4, 1.0
	v_mul_f32_e32 v18, v9, v8
	v_fma_f32 v19, -v5, v18, v9
	v_fmac_f32_e32 v18, v19, v8
	v_fma_f32 v5, -v5, v18, v9
	v_div_fmas_f32 v5, v5, v8, v18
	v_div_fixup_f32 v8, v5, v4, 1.0
	v_lshl_add_u64 v[4:5], s[64:65], 0, v[2:3]
	v_lshl_add_u64 v[4:5], v[4:5], 0, s[12:13]
	v_lshl_add_u64 v[4:5], v[4:5], 0, v[72:73]
	v_mov_b32_e32 v9, v173
	v_lshl_add_u64 v[2:3], s[26:27], 0, v[2:3]
	v_mov_b32_e32 v4, v189
	v_mul_f32_e32 v5, v6, v8
	v_mul_f32_e32 v5, v49, v5
	v_lshl_add_u64 v[2:3], v[2:3], 0, s[12:13]
	v_lshl_add_u64 v[2:3], v[2:3], 0, v[72:73]
	s_nop 0
	v_lshlrev_b32_e32 v9, 16, v9
	v_mul_f32_e32 v6, 0xbfb8aa3b, v9
	v_exp_f32_e32 v6, v6
	s_nop 0
	v_lshlrev_b32_e32 v4, 16, v4
	v_mul_f32_e32 v4, 0xbfb8aa3b, v4
	v_exp_f32_e32 v4, v4
	v_add_f32_e32 v6, 1.0, v6
	v_div_scale_f32 v9, s[0:1], v6, v6, v5
	v_rcp_f32_e32 v18, v9
	v_add_f32_e32 v4, 1.0, v4
	v_fma_f32 v19, -v9, v18, 1.0
	v_fmac_f32_e32 v18, v19, v18
	v_div_scale_f32 v19, vcc, v5, v6, v5
	v_mul_f32_e32 v20, v19, v18
	v_fma_f32 v21, -v9, v20, v19
	v_fmac_f32_e32 v20, v21, v18
	v_fma_f32 v9, -v9, v20, v19
	v_div_fmas_f32 v9, v9, v18, v20
	v_div_fixup_f32 v5, v9, v6, v5
	v_bfe_u32 v6, v5, 16, 1
	v_add3_u32 v5, v5, v6, s66
	global_store_short_d16_hi v[2:3], v5, off offset:512
	v_mul_f32_e32 v5, v7, v8
	v_mul_f32_e32 v5, v47, v5
	v_div_scale_f32 v6, s[0:1], v4, v4, v5
	v_rcp_f32_e32 v7, v6
	s_nop 0
	v_fma_f32 v8, -v6, v7, 1.0
	v_fmac_f32_e32 v7, v8, v7
	v_div_scale_f32 v8, vcc, v5, v4, v5
	v_mul_f32_e32 v9, v8, v7
	v_fma_f32 v18, -v6, v9, v8
	v_fmac_f32_e32 v9, v18, v7
	v_fma_f32 v6, -v6, v9, v8
	v_div_fmas_f32 v6, v6, v7, v9
	v_div_fixup_f32 v4, v6, v4, v5
	v_bfe_u32 v5, v4, 16, 1
	v_add3_u32 v4, v4, v5, s66
	global_store_short_d16_hi v[2:3], v4, off offset:576
	v_mov_b32_e32 v3, s7
	v_or_b32_e32 v2, s6, v54
	v_lshlrev_b64 v[4:5], 9, v[2:3]
	v_lshl_add_u64 v[4:5], v[74:75], 0, v[4:5]
	v_mov_b32_e32 v6, v140
	v_lshlrev_b64 v[2:3], 11, v[2:3]
	v_mov_b32_e32 v4, v156
	s_nop 0
	v_lshlrev_b32_e32 v6, 16, v6
	v_add_f32_e32 v6, v10, v6
	s_nop 0
	v_lshlrev_b32_e32 v4, 16, v4
	v_add_f32_e32 v7, v26, v4
	v_mul_f32_e32 v4, v7, v7
	v_fmac_f32_e32 v4, v6, v6
	ds_bpermute_b32 v5, v35, v4
	s_waitcnt lgkmcnt(0)
	v_add_f32_e32 v4, v4, v5
	ds_bpermute_b32 v5, v37, v4
	s_waitcnt lgkmcnt(0)
	v_add_f32_e32 v4, v4, v5
	ds_bpermute_b32 v5, v41, v4
	s_waitcnt lgkmcnt(0)
	v_add_f32_e32 v4, v4, v5
	ds_bpermute_b32 v5, v43, v4
	s_waitcnt lgkmcnt(0)
	v_add_f32_e32 v4, v4, v5
	ds_bpermute_b32 v5, v45, v4
	s_waitcnt lgkmcnt(0)
	v_add_f32_e32 v4, v4, v5
	v_fmamk_f32 v4, v4, 0x3c800000, v1
	v_cmp_gt_f32_e32 vcc, s14, v4
	v_mul_f32_e32 v5, 0x4f800000, v4
	s_nop 0
	v_cndmask_b32_e32 v4, v4, v5, vcc
	v_sqrt_f32_e32 v5, v4
	s_nop 0
	v_add_u32_e32 v8, -1, v5
	v_fma_f32 v9, -v8, v5, v4
	v_cmp_ge_f32_e64 s[0:1], 0, v9
	v_add_u32_e32 v9, 1, v5
	s_nop 0
	v_cndmask_b32_e64 v8, v5, v8, s[0:1]
	v_fma_f32 v5, -v9, v5, v4
	v_cmp_lt_f32_e64 s[0:1], 0, v5
	s_nop 1
	v_cndmask_b32_e64 v5, v8, v9, s[0:1]
	v_mul_f32_e32 v8, 0x37800000, v5
	v_cndmask_b32_e32 v5, v5, v8, vcc
	v_cmp_class_f32_e32 vcc, v4, v223
	s_nop 1
	v_cndmask_b32_e32 v4, v5, v4, vcc
	v_div_scale_f32 v5, s[0:1], v4, v4, 1.0
	v_rcp_f32_e32 v8, v5
	s_nop 0
	v_fma_f32 v9, -v5, v8, 1.0
	v_fmac_f32_e32 v8, v9, v8
	v_div_scale_f32 v9, vcc, 1.0, v4, 1.0
	v_mul_f32_e32 v10, v9, v8
	v_fma_f32 v18, -v5, v10, v9
	v_fmac_f32_e32 v10, v18, v8
	v_fma_f32 v5, -v5, v10, v9
	v_div_fmas_f32 v5, v5, v8, v10
	v_div_fixup_f32 v8, v5, v4, 1.0
	v_lshl_add_u64 v[4:5], s[64:65], 0, v[2:3]
	v_lshl_add_u64 v[4:5], v[4:5], 0, s[12:13]
	v_lshl_add_u64 v[4:5], v[4:5], 0, v[72:73]
	v_mov_b32_e32 v9, v174
	v_lshl_add_u64 v[2:3], s[26:27], 0, v[2:3]
	v_mov_b32_e32 v4, v190
	v_mul_f32_e32 v5, v6, v8
	v_mul_f32_e32 v5, v49, v5
	v_lshl_add_u64 v[2:3], v[2:3], 0, s[12:13]
	v_lshl_add_u64 v[2:3], v[2:3], 0, v[72:73]
	s_nop 0
	v_lshlrev_b32_e32 v9, 16, v9
	v_mul_f32_e32 v6, 0xbfb8aa3b, v9
	v_exp_f32_e32 v6, v6
	s_nop 0
	v_lshlrev_b32_e32 v4, 16, v4
	v_mul_f32_e32 v4, 0xbfb8aa3b, v4
	v_exp_f32_e32 v4, v4
	v_add_f32_e32 v6, 1.0, v6
	v_div_scale_f32 v9, s[0:1], v6, v6, v5
	v_rcp_f32_e32 v10, v9
	v_add_f32_e32 v4, 1.0, v4
	v_fma_f32 v18, -v9, v10, 1.0
	v_fmac_f32_e32 v10, v18, v10
	v_div_scale_f32 v18, vcc, v5, v6, v5
	v_mul_f32_e32 v19, v18, v10
	v_fma_f32 v20, -v9, v19, v18
	v_fmac_f32_e32 v19, v20, v10
	v_fma_f32 v9, -v9, v19, v18
	v_div_fmas_f32 v9, v9, v10, v19
	v_div_fixup_f32 v5, v9, v6, v5
	v_bfe_u32 v6, v5, 16, 1
	v_add3_u32 v5, v5, v6, s66
	global_store_short_d16_hi v[2:3], v5, off offset:512
	v_mul_f32_e32 v5, v7, v8
	v_mul_f32_e32 v5, v47, v5
	v_div_scale_f32 v6, s[0:1], v4, v4, v5
	v_rcp_f32_e32 v7, v6
	s_nop 0
	v_fma_f32 v8, -v6, v7, 1.0
	v_fmac_f32_e32 v7, v8, v7
	v_div_scale_f32 v8, vcc, v5, v4, v5
	v_mul_f32_e32 v9, v8, v7
	v_fma_f32 v10, -v6, v9, v8
	v_fmac_f32_e32 v9, v10, v7
	v_fma_f32 v6, -v6, v9, v8
	v_div_fmas_f32 v6, v6, v7, v9
	v_div_fixup_f32 v4, v6, v4, v5
	v_bfe_u32 v5, v4, 16, 1
	v_add3_u32 v4, v4, v5, s66
	global_store_short_d16_hi v[2:3], v4, off offset:576
	v_mov_b32_e32 v3, s7
	v_or_b32_e32 v2, s6, v56
	v_lshlrev_b64 v[4:5], 9, v[2:3]
	v_lshl_add_u64 v[4:5], v[74:75], 0, v[4:5]
	v_mov_b32_e32 v6, v141
	v_lshlrev_b64 v[2:3], 11, v[2:3]
	v_mov_b32_e32 v4, v157
	s_nop 0
	v_lshlrev_b32_e32 v6, 16, v6
	v_add_f32_e32 v6, v11, v6
	s_nop 0
	v_lshlrev_b32_e32 v4, 16, v4
	v_add_f32_e32 v7, v27, v4
	v_mul_f32_e32 v4, v7, v7
	v_fmac_f32_e32 v4, v6, v6
	ds_bpermute_b32 v5, v35, v4
	s_waitcnt lgkmcnt(0)
; __device__ __forceinline__ unsigned f2bf(float f) { unsigned u = __builtin_bit_cast(unsigned, f); return (u + 0x7fffu + ((u >> 16) & 1u)) >> 16; }
; __device__ __forceinline__ int crow(int r, int hi) { return (r & 3) + 8 * (r >> 2) + 4 * hi; }
; __device__ __forceinline__ int crow(int r, int hi) { return (r & 3) + 8 * (r >> 2) + 4 * hi; }
; __device__ __forceinline__ int crow(int r, int hi) { return (r & 3) + 8 * (r >> 2) + 4 * hi; }
; __device__ __forceinline__ int crow(int r, int hi) { return (r & 3) + 8 * (r >> 2) + 4 * hi; }
; __device__ __forceinline__ void pass3(const bf16* ZB, const float* hg_norm, const Bufs& B, bf16* YCB, int G, int tid) {
;     ...
;         const float hn0 = hg_norm[64 * h + r32], hn1 = hg_norm[64 * h + 32 + r32];
; #pragma unroll
;         for (int rg = 0; rg < 16; ++rg) { const size_t row = row0 + crow(rg, hh); const float o0 = acc[0][rg] + bf2f(B.INTRA[row * 256 + 64 * h + r32]), o1 = acc[1][rg] + bf2f(B.INTRA[row * 256 + 64 * h + 32 + r32]);
;             float ss = o0 * o0 + o1 * o1;
; #pragma unroll
;             for (int o = 1; o < 32; o <<= 1) ss += __shfl_xor(ss, o);
;             const float rinv = 1.0f / sqrtf(ss * (1.f / 64.f) + LN_EPS);
;             const float g0 = bf2f(ZB[row * ZLD + O_G + 64 * h + r32]), g1 = bf2f(ZB[row * ZLD + O_G + 64 * h + 32 + r32]);
;             YCB[row * 1024 + 256 + 64 * h + r32] = (bf16)f2bf(o0 * rinv * hn0 / (1.0f + __expf(-g0))); YCB[row * 1024 + 256 + 64 * h + 32 + r32] = (bf16)f2bf(o1 * rinv * hn1 / (1.0f + __expf(-g1))); }
	v_add_f32_e32 v4, v4, v5
	ds_bpermute_b32 v5, v37, v4
	s_waitcnt lgkmcnt(0)
	v_add_f32_e32 v4, v4, v5
	ds_bpermute_b32 v5, v41, v4
	s_waitcnt lgkmcnt(0)
	v_add_f32_e32 v4, v4, v5
	ds_bpermute_b32 v5, v43, v4
	s_waitcnt lgkmcnt(0)
	v_add_f32_e32 v4, v4, v5
	ds_bpermute_b32 v5, v45, v4
	s_waitcnt lgkmcnt(0)
	v_add_f32_e32 v4, v4, v5
	v_fmamk_f32 v4, v4, 0x3c800000, v1
	v_cmp_gt_f32_e32 vcc, s14, v4
	v_mul_f32_e32 v5, 0x4f800000, v4
	s_nop 0
	v_cndmask_b32_e32 v4, v4, v5, vcc
	v_sqrt_f32_e32 v5, v4
	s_nop 0
	v_add_u32_e32 v8, -1, v5
	v_fma_f32 v9, -v8, v5, v4
	v_cmp_ge_f32_e64 s[0:1], 0, v9
	v_add_u32_e32 v9, 1, v5
	s_nop 0
	v_cndmask_b32_e64 v8, v5, v8, s[0:1]
	v_fma_f32 v5, -v9, v5, v4
	v_cmp_lt_f32_e64 s[0:1], 0, v5
	s_nop 1
	v_cndmask_b32_e64 v5, v8, v9, s[0:1]
	v_mul_f32_e32 v8, 0x37800000, v5
	v_cndmask_b32_e32 v5, v5, v8, vcc
	v_cmp_class_f32_e32 vcc, v4, v223
	s_nop 1
	v_cndmask_b32_e32 v4, v5, v4, vcc
	v_div_scale_f32 v5, s[0:1], v4, v4, 1.0
	v_rcp_f32_e32 v8, v5
	s_nop 0
	v_fma_f32 v9, -v5, v8, 1.0
	v_fmac_f32_e32 v8, v9, v8
	v_div_scale_f32 v9, vcc, 1.0, v4, 1.0
	v_mul_f32_e32 v10, v9, v8
	v_fma_f32 v11, -v5, v10, v9
	v_fmac_f32_e32 v10, v11, v8
	v_fma_f32 v5, -v5, v10, v9
	v_div_fmas_f32 v5, v5, v8, v10
	v_div_fixup_f32 v8, v5, v4, 1.0
	v_lshl_add_u64 v[4:5], s[64:65], 0, v[2:3]
	v_lshl_add_u64 v[4:5], v[4:5], 0, s[12:13]
	v_lshl_add_u64 v[4:5], v[4:5], 0, v[72:73]
	v_mov_b32_e32 v9, v175
	v_lshl_add_u64 v[2:3], s[26:27], 0, v[2:3]
	v_mov_b32_e32 v4, v191
	v_mul_f32_e32 v5, v6, v8
	v_mul_f32_e32 v5, v49, v5
	v_lshl_add_u64 v[2:3], v[2:3], 0, s[12:13]
	v_lshl_add_u64 v[2:3], v[2:3], 0, v[72:73]
	s_nop 0
	v_lshlrev_b32_e32 v9, 16, v9
	v_mul_f32_e32 v6, 0xbfb8aa3b, v9
	v_exp_f32_e32 v6, v6
	s_nop 0
	v_lshlrev_b32_e32 v4, 16, v4
	v_mul_f32_e32 v4, 0xbfb8aa3b, v4
	v_exp_f32_e32 v4, v4
	v_add_f32_e32 v6, 1.0, v6
	v_div_scale_f32 v9, s[0:1], v6, v6, v5
	v_rcp_f32_e32 v10, v9
	v_add_f32_e32 v4, 1.0, v4
	v_fma_f32 v11, -v9, v10, 1.0
	v_fmac_f32_e32 v10, v11, v10
	v_div_scale_f32 v11, vcc, v5, v6, v5
	v_mul_f32_e32 v18, v11, v10
	v_fma_f32 v19, -v9, v18, v11
	v_fmac_f32_e32 v18, v19, v10
	v_fma_f32 v9, -v9, v18, v11
	v_div_fmas_f32 v9, v9, v10, v18
	v_div_fixup_f32 v5, v9, v6, v5
	v_bfe_u32 v6, v5, 16, 1
	v_add3_u32 v5, v5, v6, s66
	global_store_short_d16_hi v[2:3], v5, off offset:512
	v_mul_f32_e32 v5, v7, v8
	v_mul_f32_e32 v5, v47, v5
	v_div_scale_f32 v6, s[0:1], v4, v4, v5
	v_rcp_f32_e32 v7, v6
	s_nop 0
	v_fma_f32 v8, -v6, v7, 1.0
	v_fmac_f32_e32 v7, v8, v7
	v_div_scale_f32 v8, vcc, v5, v4, v5
	v_mul_f32_e32 v9, v8, v7
	v_fma_f32 v10, -v6, v9, v8
	v_fmac_f32_e32 v9, v10, v7
	v_fma_f32 v6, -v6, v9, v8
	v_div_fmas_f32 v6, v6, v7, v9
	v_div_fixup_f32 v4, v6, v4, v5
	v_bfe_u32 v5, v4, 16, 1
	v_add3_u32 v4, v4, v5, s66
	global_store_short_d16_hi v[2:3], v4, off offset:576
	v_mov_b32_e32 v3, s7
	v_or_b32_e32 v2, s6, v58
	v_lshlrev_b64 v[4:5], 9, v[2:3]
	v_lshl_add_u64 v[4:5], v[74:75], 0, v[4:5]
	v_mov_b32_e32 v6, v142
	v_lshlrev_b64 v[2:3], 11, v[2:3]
	v_mov_b32_e32 v4, v158
	s_nop 0
	v_lshlrev_b32_e32 v6, 16, v6
	v_add_f32_e32 v6, v12, v6
	s_nop 0
	v_lshlrev_b32_e32 v4, 16, v4
	v_add_f32_e32 v7, v28, v4
	v_mul_f32_e32 v4, v7, v7
	v_fmac_f32_e32 v4, v6, v6
	ds_bpermute_b32 v5, v35, v4
	s_waitcnt lgkmcnt(0)
	v_add_f32_e32 v4, v4, v5
	ds_bpermute_b32 v5, v37, v4
	s_waitcnt lgkmcnt(0)
	v_add_f32_e32 v4, v4, v5
	ds_bpermute_b32 v5, v41, v4
	s_waitcnt lgkmcnt(0)
	v_add_f32_e32 v4, v4, v5
	ds_bpermute_b32 v5, v43, v4
	s_waitcnt lgkmcnt(0)
	v_add_f32_e32 v4, v4, v5
	ds_bpermute_b32 v5, v45, v4
	s_waitcnt lgkmcnt(0)
	v_add_f32_e32 v4, v4, v5
	v_fmamk_f32 v4, v4, 0x3c800000, v1
	v_cmp_gt_f32_e32 vcc, s14, v4
	v_mul_f32_e32 v5, 0x4f800000, v4
	s_nop 0
	v_cndmask_b32_e32 v4, v4, v5, vcc
	v_sqrt_f32_e32 v5, v4
	s_nop 0
	v_add_u32_e32 v8, -1, v5
	v_fma_f32 v9, -v8, v5, v4
	v_cmp_ge_f32_e64 s[0:1], 0, v9
	v_add_u32_e32 v9, 1, v5
	s_nop 0
	v_cndmask_b32_e64 v8, v5, v8, s[0:1]
	v_fma_f32 v5, -v9, v5, v4
	v_cmp_lt_f32_e64 s[0:1], 0, v5
	s_nop 1
	v_cndmask_b32_e64 v5, v8, v9, s[0:1]
	v_mul_f32_e32 v8, 0x37800000, v5
	v_cndmask_b32_e32 v5, v5, v8, vcc
	v_cmp_class_f32_e32 vcc, v4, v223
	s_nop 1
	v_cndmask_b32_e32 v4, v5, v4, vcc
	v_div_scale_f32 v5, s[0:1], v4, v4, 1.0
	v_rcp_f32_e32 v8, v5
	s_nop 0
	v_fma_f32 v9, -v5, v8, 1.0
	v_fmac_f32_e32 v8, v9, v8
	v_div_scale_f32 v9, vcc, 1.0, v4, 1.0
	v_mul_f32_e32 v10, v9, v8
	v_fma_f32 v11, -v5, v10, v9
	v_fmac_f32_e32 v10, v11, v8
	v_fma_f32 v5, -v5, v10, v9
	v_div_fmas_f32 v5, v5, v8, v10
	v_div_fixup_f32 v8, v5, v4, 1.0
	v_lshl_add_u64 v[4:5], s[64:65], 0, v[2:3]
	v_lshl_add_u64 v[4:5], v[4:5], 0, s[12:13]
	v_lshl_add_u64 v[4:5], v[4:5], 0, v[72:73]
	v_mov_b32_e32 v9, v176
	v_lshl_add_u64 v[2:3], s[26:27], 0, v[2:3]
	v_mov_b32_e32 v4, v84
	v_mul_f32_e32 v5, v6, v8
	v_mul_f32_e32 v5, v49, v5
	v_lshl_add_u64 v[2:3], v[2:3], 0, s[12:13]
	v_lshl_add_u64 v[2:3], v[2:3], 0, v[72:73]
	s_nop 0
	v_lshlrev_b32_e32 v9, 16, v9
	v_mul_f32_e32 v6, 0xbfb8aa3b, v9
	v_exp_f32_e32 v6, v6
	s_nop 0
	v_lshlrev_b32_e32 v4, 16, v4
	v_mul_f32_e32 v4, 0xbfb8aa3b, v4
	v_exp_f32_e32 v4, v4
	v_add_f32_e32 v6, 1.0, v6
	v_div_scale_f32 v9, s[0:1], v6, v6, v5
	v_rcp_f32_e32 v10, v9
	v_add_f32_e32 v4, 1.0, v4
	v_fma_f32 v11, -v9, v10, 1.0
	v_fmac_f32_e32 v10, v11, v10
	v_div_scale_f32 v11, vcc, v5, v6, v5
	v_mul_f32_e32 v12, v11, v10
	v_fma_f32 v18, -v9, v12, v11
	v_fmac_f32_e32 v12, v18, v10
	v_fma_f32 v9, -v9, v12, v11
	v_div_fmas_f32 v9, v9, v10, v12
	v_div_fixup_f32 v5, v9, v6, v5
	v_bfe_u32 v6, v5, 16, 1
	v_add3_u32 v5, v5, v6, s66
	global_store_short_d16_hi v[2:3], v5, off offset:512
	v_mul_f32_e32 v5, v7, v8
	v_mul_f32_e32 v5, v47, v5
	v_div_scale_f32 v6, s[0:1], v4, v4, v5
	v_rcp_f32_e32 v7, v6
	s_nop 0
	v_fma_f32 v8, -v6, v7, 1.0
	v_fmac_f32_e32 v7, v8, v7
	v_div_scale_f32 v8, vcc, v5, v4, v5
	v_mul_f32_e32 v9, v8, v7
	v_fma_f32 v10, -v6, v9, v8
	v_fmac_f32_e32 v9, v10, v7
	v_fma_f32 v6, -v6, v9, v8
	v_div_fmas_f32 v6, v6, v7, v9
	v_div_fixup_f32 v4, v6, v4, v5
	v_bfe_u32 v5, v4, 16, 1
	v_add3_u32 v4, v4, v5, s66
	global_store_short_d16_hi v[2:3], v4, off offset:576
	v_mov_b32_e32 v3, s7
	v_or_b32_e32 v2, s6, v60
	v_lshlrev_b64 v[4:5], 9, v[2:3]
	v_lshl_add_u64 v[4:5], v[74:75], 0, v[4:5]
	v_mov_b32_e32 v6, v143
	v_lshlrev_b64 v[2:3], 11, v[2:3]
	v_mov_b32_e32 v4, v159
	s_nop 0
	v_lshlrev_b32_e32 v6, 16, v6
	v_add_f32_e32 v6, v13, v6
	s_nop 0
	v_lshlrev_b32_e32 v4, 16, v4
	v_add_f32_e32 v7, v29, v4
	v_mul_f32_e32 v4, v7, v7
	v_fmac_f32_e32 v4, v6, v6
	ds_bpermute_b32 v5, v35, v4
	s_waitcnt lgkmcnt(0)
; __device__ __forceinline__ unsigned f2bf(float f) { unsigned u = __builtin_bit_cast(unsigned, f); return (u + 0x7fffu + ((u >> 16) & 1u)) >> 16; }
; __device__ __forceinline__ int crow(int r, int hi) { return (r & 3) + 8 * (r >> 2) + 4 * hi; }
; __device__ __forceinline__ int crow(int r, int hi) { return (r & 3) + 8 * (r >> 2) + 4 * hi; }
; __device__ __forceinline__ int crow(int r, int hi) { return (r & 3) + 8 * (r >> 2) + 4 * hi; }
; __device__ __forceinline__ int crow(int r, int hi) { return (r & 3) + 8 * (r >> 2) + 4 * hi; }
; __device__ __forceinline__ void pass3(const bf16* ZB, const float* hg_norm, const Bufs& B, bf16* YCB, int G, int tid) {
;     ...
;         const float hn0 = hg_norm[64 * h + r32], hn1 = hg_norm[64 * h + 32 + r32];
; #pragma unroll
;         for (int rg = 0; rg < 16; ++rg) { const size_t row = row0 + crow(rg, hh); const float o0 = acc[0][rg] + bf2f(B.INTRA[row * 256 + 64 * h + r32]), o1 = acc[1][rg] + bf2f(B.INTRA[row * 256 + 64 * h + 32 + r32]);
;             float ss = o0 * o0 + o1 * o1;
; #pragma unroll
;             for (int o = 1; o < 32; o <<= 1) ss += __shfl_xor(ss, o);
;             const float rinv = 1.0f / sqrtf(ss * (1.f / 64.f) + LN_EPS);
;             const float g0 = bf2f(ZB[row * ZLD + O_G + 64 * h + r32]), g1 = bf2f(ZB[row * ZLD + O_G + 64 * h + 32 + r32]);
;             YCB[row * 1024 + 256 + 64 * h + r32] = (bf16)f2bf(o0 * rinv * hn0 / (1.0f + __expf(-g0))); YCB[row * 1024 + 256 + 64 * h + 32 + r32] = (bf16)f2bf(o1 * rinv * hn1 / (1.0f + __expf(-g1))); }
	v_add_f32_e32 v4, v4, v5
	ds_bpermute_b32 v5, v37, v4
	s_waitcnt lgkmcnt(0)
	v_add_f32_e32 v4, v4, v5
	ds_bpermute_b32 v5, v41, v4
	s_waitcnt lgkmcnt(0)
	v_add_f32_e32 v4, v4, v5
	ds_bpermute_b32 v5, v43, v4
	s_waitcnt lgkmcnt(0)
	v_add_f32_e32 v4, v4, v5
	ds_bpermute_b32 v5, v45, v4
	s_waitcnt lgkmcnt(0)
	v_add_f32_e32 v4, v4, v5
	v_fmamk_f32 v4, v4, 0x3c800000, v1
	v_cmp_gt_f32_e32 vcc, s14, v4
	v_mul_f32_e32 v5, 0x4f800000, v4
	s_nop 0
	v_cndmask_b32_e32 v4, v4, v5, vcc
	v_sqrt_f32_e32 v5, v4
	s_nop 0
	v_add_u32_e32 v8, -1, v5
	v_fma_f32 v9, -v8, v5, v4
	v_cmp_ge_f32_e64 s[0:1], 0, v9
	v_add_u32_e32 v9, 1, v5
	s_nop 0
	v_cndmask_b32_e64 v8, v5, v8, s[0:1]
	v_fma_f32 v5, -v9, v5, v4
	v_cmp_lt_f32_e64 s[0:1], 0, v5
	s_nop 1
	v_cndmask_b32_e64 v5, v8, v9, s[0:1]
	v_mul_f32_e32 v8, 0x37800000, v5
	v_cndmask_b32_e32 v5, v5, v8, vcc
	v_cmp_class_f32_e32 vcc, v4, v223
	s_nop 1
	v_cndmask_b32_e32 v4, v5, v4, vcc
	v_div_scale_f32 v5, s[0:1], v4, v4, 1.0
	v_rcp_f32_e32 v8, v5
	s_nop 0
	v_fma_f32 v9, -v5, v8, 1.0
	v_fmac_f32_e32 v8, v9, v8
	v_div_scale_f32 v9, vcc, 1.0, v4, 1.0
	v_mul_f32_e32 v10, v9, v8
	v_fma_f32 v11, -v5, v10, v9
	v_fmac_f32_e32 v10, v11, v8
	v_fma_f32 v5, -v5, v10, v9
	v_div_fmas_f32 v5, v5, v8, v10
	v_div_fixup_f32 v8, v5, v4, 1.0
	v_lshl_add_u64 v[4:5], s[64:65], 0, v[2:3]
	v_lshl_add_u64 v[4:5], v[4:5], 0, s[12:13]
	v_lshl_add_u64 v[4:5], v[4:5], 0, v[72:73]
	v_mov_b32_e32 v9, v177
	v_lshl_add_u64 v[2:3], s[26:27], 0, v[2:3]
	v_mov_b32_e32 v4, v85
	v_mul_f32_e32 v5, v6, v8
	v_mul_f32_e32 v5, v49, v5
	v_lshl_add_u64 v[2:3], v[2:3], 0, s[12:13]
	v_lshl_add_u64 v[2:3], v[2:3], 0, v[72:73]
	s_nop 0
	v_lshlrev_b32_e32 v9, 16, v9
	v_mul_f32_e32 v6, 0xbfb8aa3b, v9
	v_exp_f32_e32 v6, v6
	s_nop 0
	v_lshlrev_b32_e32 v4, 16, v4
	v_mul_f32_e32 v4, 0xbfb8aa3b, v4
	v_exp_f32_e32 v4, v4
	v_add_f32_e32 v6, 1.0, v6
	v_div_scale_f32 v9, s[0:1], v6, v6, v5
	v_rcp_f32_e32 v10, v9
	v_add_f32_e32 v4, 1.0, v4
	v_fma_f32 v11, -v9, v10, 1.0
	v_fmac_f32_e32 v10, v11, v10
	v_div_scale_f32 v11, vcc, v5, v6, v5
	v_mul_f32_e32 v12, v11, v10
	v_fma_f32 v13, -v9, v12, v11
	v_fmac_f32_e32 v12, v13, v10
	v_fma_f32 v9, -v9, v12, v11
	v_div_fmas_f32 v9, v9, v10, v12
	v_div_fixup_f32 v5, v9, v6, v5
	v_bfe_u32 v6, v5, 16, 1
	v_add3_u32 v5, v5, v6, s66
	global_store_short_d16_hi v[2:3], v5, off offset:512
	v_mul_f32_e32 v5, v7, v8
	v_mul_f32_e32 v5, v47, v5
	v_div_scale_f32 v6, s[0:1], v4, v4, v5
	v_rcp_f32_e32 v7, v6
	s_nop 0
	v_fma_f32 v8, -v6, v7, 1.0
	v_fmac_f32_e32 v7, v8, v7
	v_div_scale_f32 v8, vcc, v5, v4, v5
	v_mul_f32_e32 v9, v8, v7
	v_fma_f32 v10, -v6, v9, v8
	v_fmac_f32_e32 v9, v10, v7
	v_fma_f32 v6, -v6, v9, v8
	v_div_fmas_f32 v6, v6, v7, v9
	v_div_fixup_f32 v4, v6, v4, v5
	v_bfe_u32 v5, v4, 16, 1
	v_add3_u32 v4, v4, v5, s66
	global_store_short_d16_hi v[2:3], v4, off offset:576
	v_mov_b32_e32 v3, s7
	v_or_b32_e32 v2, s6, v62
	v_lshlrev_b64 v[4:5], 9, v[2:3]
	v_lshl_add_u64 v[4:5], v[74:75], 0, v[4:5]
	v_mov_b32_e32 v6, v144
	v_lshlrev_b64 v[2:3], 11, v[2:3]
	v_mov_b32_e32 v4, v160
	s_nop 0
	v_lshlrev_b32_e32 v6, 16, v6
	v_add_f32_e32 v6, v14, v6
	s_nop 0
	v_lshlrev_b32_e32 v4, 16, v4
	v_add_f32_e32 v7, v30, v4
	v_mul_f32_e32 v4, v7, v7
	v_fmac_f32_e32 v4, v6, v6
	ds_bpermute_b32 v5, v35, v4
	s_waitcnt lgkmcnt(0)
	v_add_f32_e32 v4, v4, v5
	ds_bpermute_b32 v5, v37, v4
	s_waitcnt lgkmcnt(0)
	v_add_f32_e32 v4, v4, v5
	ds_bpermute_b32 v5, v41, v4
	s_waitcnt lgkmcnt(0)
	v_add_f32_e32 v4, v4, v5
	ds_bpermute_b32 v5, v43, v4
	s_waitcnt lgkmcnt(0)
	v_add_f32_e32 v4, v4, v5
	ds_bpermute_b32 v5, v45, v4
	s_waitcnt lgkmcnt(0)
	v_add_f32_e32 v4, v4, v5
	v_fmamk_f32 v4, v4, 0x3c800000, v1
	v_cmp_gt_f32_e32 vcc, s14, v4
	v_mul_f32_e32 v5, 0x4f800000, v4
	s_nop 0
	v_cndmask_b32_e32 v4, v4, v5, vcc
	v_sqrt_f32_e32 v5, v4
	s_nop 0
	v_add_u32_e32 v8, -1, v5
	v_fma_f32 v9, -v8, v5, v4
	v_cmp_ge_f32_e64 s[0:1], 0, v9
	v_add_u32_e32 v9, 1, v5
	s_nop 0
	v_cndmask_b32_e64 v8, v5, v8, s[0:1]
	v_fma_f32 v5, -v9, v5, v4
	v_cmp_lt_f32_e64 s[0:1], 0, v5
	s_nop 1
	v_cndmask_b32_e64 v5, v8, v9, s[0:1]
	v_mul_f32_e32 v8, 0x37800000, v5
	v_cndmask_b32_e32 v5, v5, v8, vcc
	v_cmp_class_f32_e32 vcc, v4, v223
	s_nop 1
	v_cndmask_b32_e32 v4, v5, v4, vcc
	v_div_scale_f32 v5, s[0:1], v4, v4, 1.0
	v_rcp_f32_e32 v8, v5
	s_nop 0
	v_fma_f32 v9, -v5, v8, 1.0
	v_fmac_f32_e32 v8, v9, v8
	v_div_scale_f32 v9, vcc, 1.0, v4, 1.0
	v_mul_f32_e32 v10, v9, v8
	v_fma_f32 v11, -v5, v10, v9
	v_fmac_f32_e32 v10, v11, v8
	v_fma_f32 v5, -v5, v10, v9
	v_div_fmas_f32 v5, v5, v8, v10
	v_div_fixup_f32 v8, v5, v4, 1.0
	v_lshl_add_u64 v[4:5], s[64:65], 0, v[2:3]
	v_lshl_add_u64 v[4:5], v[4:5], 0, s[12:13]
	v_lshl_add_u64 v[4:5], v[4:5], 0, v[72:73]
	v_mov_b32_e32 v9, v178
	v_lshl_add_u64 v[2:3], s[26:27], 0, v[2:3]
	v_mov_b32_e32 v4, v86
	v_mul_f32_e32 v5, v6, v8
	v_mul_f32_e32 v5, v49, v5
	v_lshl_add_u64 v[2:3], v[2:3], 0, s[12:13]
	v_lshl_add_u64 v[2:3], v[2:3], 0, v[72:73]
	s_nop 0
	v_lshlrev_b32_e32 v9, 16, v9
	v_mul_f32_e32 v6, 0xbfb8aa3b, v9
	v_exp_f32_e32 v6, v6
	s_nop 0
	v_lshlrev_b32_e32 v4, 16, v4
	v_mul_f32_e32 v4, 0xbfb8aa3b, v4
	v_exp_f32_e32 v4, v4
	v_add_f32_e32 v6, 1.0, v6
	v_div_scale_f32 v9, s[0:1], v6, v6, v5
	v_rcp_f32_e32 v10, v9
	v_add_f32_e32 v4, 1.0, v4
	v_fma_f32 v11, -v9, v10, 1.0
	v_fmac_f32_e32 v10, v11, v10
	v_div_scale_f32 v11, vcc, v5, v6, v5
	v_mul_f32_e32 v12, v11, v10
	v_fma_f32 v13, -v9, v12, v11
	v_fmac_f32_e32 v12, v13, v10
	v_fma_f32 v9, -v9, v12, v11
	v_div_fmas_f32 v9, v9, v10, v12
	v_div_fixup_f32 v5, v9, v6, v5
	v_bfe_u32 v6, v5, 16, 1
	v_add3_u32 v5, v5, v6, s66
	global_store_short_d16_hi v[2:3], v5, off offset:512
	v_mul_f32_e32 v5, v7, v8
	v_mul_f32_e32 v5, v47, v5
	v_div_scale_f32 v6, s[0:1], v4, v4, v5
	v_rcp_f32_e32 v7, v6
	s_nop 0
	v_fma_f32 v8, -v6, v7, 1.0
	v_fmac_f32_e32 v7, v8, v7
	v_div_scale_f32 v8, vcc, v5, v4, v5
	v_mul_f32_e32 v9, v8, v7
	v_fma_f32 v10, -v6, v9, v8
	v_fmac_f32_e32 v9, v10, v7
	v_fma_f32 v6, -v6, v9, v8
	v_div_fmas_f32 v6, v6, v7, v9
	v_div_fixup_f32 v4, v6, v4, v5
	v_bfe_u32 v5, v4, 16, 1
	v_add3_u32 v4, v4, v5, s66
	global_store_short_d16_hi v[2:3], v4, off offset:576
	v_mov_b32_e32 v3, s7
	v_or_b32_e32 v2, s6, v64
	v_lshlrev_b64 v[4:5], 9, v[2:3]
	v_lshl_add_u64 v[4:5], v[74:75], 0, v[4:5]
	v_mov_b32_e32 v6, v145
	v_lshlrev_b64 v[2:3], 11, v[2:3]
	v_mov_b32_e32 v4, v161
	s_nop 0
	v_lshlrev_b32_e32 v6, 16, v6
	v_add_f32_e32 v6, v15, v6
	s_nop 0
	v_lshlrev_b32_e32 v4, 16, v4
	v_add_f32_e32 v7, v31, v4
	v_mul_f32_e32 v4, v7, v7
	v_fmac_f32_e32 v4, v6, v6
	ds_bpermute_b32 v5, v35, v4
	s_waitcnt lgkmcnt(0)
; __device__ __forceinline__ unsigned f2bf(float f) { unsigned u = __builtin_bit_cast(unsigned, f); return (u + 0x7fffu + ((u >> 16) & 1u)) >> 16; }
; __device__ __forceinline__ int crow(int r, int hi) { return (r & 3) + 8 * (r >> 2) + 4 * hi; }
; __device__ __forceinline__ int crow(int r, int hi) { return (r & 3) + 8 * (r >> 2) + 4 * hi; }
; __device__ __forceinline__ int crow(int r, int hi) { return (r & 3) + 8 * (r >> 2) + 4 * hi; }
; __device__ __forceinline__ int crow(int r, int hi) { return (r & 3) + 8 * (r >> 2) + 4 * hi; }
; __device__ __forceinline__ void pass3(const bf16* ZB, const float* hg_norm, const Bufs& B, bf16* YCB, int G, int tid) {
;     ...
;         const float hn0 = hg_norm[64 * h + r32], hn1 = hg_norm[64 * h + 32 + r32];
; #pragma unroll
;         for (int rg = 0; rg < 16; ++rg) { const size_t row = row0 + crow(rg, hh); const float o0 = acc[0][rg] + bf2f(B.INTRA[row * 256 + 64 * h + r32]), o1 = acc[1][rg] + bf2f(B.INTRA[row * 256 + 64 * h + 32 + r32]);
;             float ss = o0 * o0 + o1 * o1;
; #pragma unroll
;             for (int o = 1; o < 32; o <<= 1) ss += __shfl_xor(ss, o);
;             const float rinv = 1.0f / sqrtf(ss * (1.f / 64.f) + LN_EPS);
;             const float g0 = bf2f(ZB[row * ZLD + O_G + 64 * h + r32]), g1 = bf2f(ZB[row * ZLD + O_G + 64 * h + 32 + r32]);
;             YCB[row * 1024 + 256 + 64 * h + r32] = (bf16)f2bf(o0 * rinv * hn0 / (1.0f + __expf(-g0))); YCB[row * 1024 + 256 + 64 * h + 32 + r32] = (bf16)f2bf(o1 * rinv * hn1 / (1.0f + __expf(-g1))); }
	v_add_f32_e32 v4, v4, v5
	ds_bpermute_b32 v5, v37, v4
	s_waitcnt lgkmcnt(0)
	v_add_f32_e32 v4, v4, v5
	ds_bpermute_b32 v5, v41, v4
	s_waitcnt lgkmcnt(0)
	v_add_f32_e32 v4, v4, v5
	ds_bpermute_b32 v5, v43, v4
	s_waitcnt lgkmcnt(0)
	v_add_f32_e32 v4, v4, v5
	ds_bpermute_b32 v5, v45, v4
	s_waitcnt lgkmcnt(0)
	v_add_f32_e32 v4, v4, v5
	v_fmamk_f32 v4, v4, 0x3c800000, v1
	v_cmp_gt_f32_e32 vcc, s14, v4
	v_mul_f32_e32 v5, 0x4f800000, v4
	s_nop 0
	v_cndmask_b32_e32 v4, v4, v5, vcc
	v_sqrt_f32_e32 v5, v4
	s_nop 0
	v_add_u32_e32 v8, -1, v5
	v_fma_f32 v9, -v8, v5, v4
	v_cmp_ge_f32_e64 s[0:1], 0, v9
	v_add_u32_e32 v9, 1, v5
	s_nop 0
	v_cndmask_b32_e64 v8, v5, v8, s[0:1]
	v_fma_f32 v5, -v9, v5, v4
	v_cmp_lt_f32_e64 s[0:1], 0, v5
	s_nop 1
	v_cndmask_b32_e64 v5, v8, v9, s[0:1]
	v_mul_f32_e32 v8, 0x37800000, v5
	v_cndmask_b32_e32 v5, v5, v8, vcc
	v_cmp_class_f32_e32 vcc, v4, v223
	s_nop 1
	v_cndmask_b32_e32 v4, v5, v4, vcc
	v_div_scale_f32 v5, s[0:1], v4, v4, 1.0
	v_rcp_f32_e32 v8, v5
	s_nop 0
	v_fma_f32 v9, -v5, v8, 1.0
	v_fmac_f32_e32 v8, v9, v8
	v_div_scale_f32 v9, vcc, 1.0, v4, 1.0
	v_mul_f32_e32 v10, v9, v8
	v_fma_f32 v11, -v5, v10, v9
	v_fmac_f32_e32 v10, v11, v8
	v_fma_f32 v5, -v5, v10, v9
	v_div_fmas_f32 v5, v5, v8, v10
	v_div_fixup_f32 v8, v5, v4, 1.0
	v_lshl_add_u64 v[4:5], s[64:65], 0, v[2:3]
	v_lshl_add_u64 v[4:5], v[4:5], 0, s[12:13]
	v_lshl_add_u64 v[4:5], v[4:5], 0, v[72:73]
	v_mov_b32_e32 v9, v179
	v_lshl_add_u64 v[2:3], s[26:27], 0, v[2:3]
	v_mov_b32_e32 v4, v87
	v_mul_f32_e32 v5, v6, v8
	v_mul_f32_e32 v5, v49, v5
	v_lshl_add_u64 v[2:3], v[2:3], 0, s[12:13]
	v_lshl_add_u64 v[2:3], v[2:3], 0, v[72:73]
	s_nop 0
	v_lshlrev_b32_e32 v9, 16, v9
	v_mul_f32_e32 v6, 0xbfb8aa3b, v9
	v_exp_f32_e32 v6, v6
	s_nop 0
	v_lshlrev_b32_e32 v4, 16, v4
	v_mul_f32_e32 v4, 0xbfb8aa3b, v4
	v_exp_f32_e32 v4, v4
	v_add_f32_e32 v6, 1.0, v6
	v_div_scale_f32 v9, s[0:1], v6, v6, v5
	v_rcp_f32_e32 v10, v9
	v_add_f32_e32 v4, 1.0, v4
	v_fma_f32 v11, -v9, v10, 1.0
	v_fmac_f32_e32 v10, v11, v10
	v_div_scale_f32 v11, vcc, v5, v6, v5
	v_mul_f32_e32 v12, v11, v10
	v_fma_f32 v13, -v9, v12, v11
	v_fmac_f32_e32 v12, v13, v10
	v_fma_f32 v9, -v9, v12, v11
	v_div_fmas_f32 v9, v9, v10, v12
	v_div_fixup_f32 v5, v9, v6, v5
	v_bfe_u32 v6, v5, 16, 1
	v_add3_u32 v5, v5, v6, s66
	global_store_short_d16_hi v[2:3], v5, off offset:512
	v_mul_f32_e32 v5, v7, v8
	v_mul_f32_e32 v5, v47, v5
	v_div_scale_f32 v6, s[0:1], v4, v4, v5
	v_rcp_f32_e32 v7, v6
	s_nop 0
	v_fma_f32 v8, -v6, v7, 1.0
	v_fmac_f32_e32 v7, v8, v7
	v_div_scale_f32 v8, vcc, v5, v4, v5
	v_mul_f32_e32 v9, v8, v7
	v_fma_f32 v10, -v6, v9, v8
	v_fmac_f32_e32 v9, v10, v7
	v_fma_f32 v6, -v6, v9, v8
	v_div_fmas_f32 v6, v6, v7, v9
	v_div_fixup_f32 v4, v6, v4, v5
	v_bfe_u32 v5, v4, 16, 1
	v_add3_u32 v4, v4, v5, s66
	global_store_short_d16_hi v[2:3], v4, off offset:576
	v_mov_b32_e32 v3, s7
	v_or_b32_e32 v2, s6, v66
	v_lshlrev_b64 v[4:5], 9, v[2:3]
	v_lshl_add_u64 v[4:5], v[74:75], 0, v[4:5]
	v_mov_b32_e32 v6, v146
	v_lshlrev_b64 v[2:3], 11, v[2:3]
	v_mov_b32_e32 v4, v162
	s_nop 0
	v_lshlrev_b32_e32 v6, 16, v6
	v_add_f32_e32 v6, v16, v6
	s_nop 0
	v_lshlrev_b32_e32 v4, 16, v4
	v_add_f32_e32 v7, v32, v4
	v_mul_f32_e32 v4, v7, v7
	v_fmac_f32_e32 v4, v6, v6
	ds_bpermute_b32 v5, v35, v4
	s_waitcnt lgkmcnt(0)
	v_add_f32_e32 v4, v4, v5
	ds_bpermute_b32 v5, v37, v4
	s_waitcnt lgkmcnt(0)
	v_add_f32_e32 v4, v4, v5
	ds_bpermute_b32 v5, v41, v4
	s_waitcnt lgkmcnt(0)
	v_add_f32_e32 v4, v4, v5
	ds_bpermute_b32 v5, v43, v4
	s_waitcnt lgkmcnt(0)
	v_add_f32_e32 v4, v4, v5
	ds_bpermute_b32 v5, v45, v4
	s_waitcnt lgkmcnt(0)
; __device__ __forceinline__ unsigned f2bf(float f) { unsigned u = __builtin_bit_cast(unsigned, f); return (u + 0x7fffu + ((u >> 16) & 1u)) >> 16; }
; __device__ __forceinline__ int crow(int r, int hi) { return (r & 3) + 8 * (r >> 2) + 4 * hi; }
; __device__ __forceinline__ int crow(int r, int hi) { return (r & 3) + 8 * (r >> 2) + 4 * hi; }
; __device__ __forceinline__ int crow(int r, int hi) { return (r & 3) + 8 * (r >> 2) + 4 * hi; }
; __device__ __forceinline__ int crow(int r, int hi) { return (r & 3) + 8 * (r >> 2) + 4 * hi; }
; __device__ __forceinline__ void pass3(const bf16* ZB, const float* hg_norm, const Bufs& B, bf16* YCB, int G, int tid) {
;     ...
;         const float hn0 = hg_norm[64 * h + r32], hn1 = hg_norm[64 * h + 32 + r32];
; #pragma unroll
;         for (int rg = 0; rg < 16; ++rg) { const size_t row = row0 + crow(rg, hh); const float o0 = acc[0][rg] + bf2f(B.INTRA[row * 256 + 64 * h + r32]), o1 = acc[1][rg] + bf2f(B.INTRA[row * 256 + 64 * h + 32 + r32]);
;             float ss = o0 * o0 + o1 * o1;
; #pragma unroll
;             for (int o = 1; o < 32; o <<= 1) ss += __shfl_xor(ss, o);
;             const float rinv = 1.0f / sqrtf(ss * (1.f / 64.f) + LN_EPS);
;             const float g0 = bf2f(ZB[row * ZLD + O_G + 64 * h + r32]), g1 = bf2f(ZB[row * ZLD + O_G + 64 * h + 32 + r32]);
;             YCB[row * 1024 + 256 + 64 * h + r32] = (bf16)f2bf(o0 * rinv * hn0 / (1.0f + __expf(-g0))); YCB[row * 1024 + 256 + 64 * h + 32 + r32] = (bf16)f2bf(o1 * rinv * hn1 / (1.0f + __expf(-g1))); }
	v_add_f32_e32 v4, v4, v5
	v_fmamk_f32 v4, v4, 0x3c800000, v1
	v_cmp_gt_f32_e32 vcc, s14, v4
	v_mul_f32_e32 v5, 0x4f800000, v4
	s_nop 0
	v_cndmask_b32_e32 v4, v4, v5, vcc
	v_sqrt_f32_e32 v5, v4
	s_nop 0
	v_add_u32_e32 v8, -1, v5
	v_fma_f32 v9, -v8, v5, v4
	v_cmp_ge_f32_e64 s[0:1], 0, v9
	v_add_u32_e32 v9, 1, v5
	s_nop 0
	v_cndmask_b32_e64 v8, v5, v8, s[0:1]
	v_fma_f32 v5, -v9, v5, v4
	v_cmp_lt_f32_e64 s[0:1], 0, v5
	s_nop 1
	v_cndmask_b32_e64 v5, v8, v9, s[0:1]
	v_mul_f32_e32 v8, 0x37800000, v5
	v_cndmask_b32_e32 v5, v5, v8, vcc
	v_cmp_class_f32_e32 vcc, v4, v223
	s_nop 1
	v_cndmask_b32_e32 v4, v5, v4, vcc
	v_div_scale_f32 v5, s[0:1], v4, v4, 1.0
	v_rcp_f32_e32 v8, v5
	s_nop 0
	v_fma_f32 v9, -v5, v8, 1.0
	v_fmac_f32_e32 v8, v9, v8
	v_div_scale_f32 v9, vcc, 1.0, v4, 1.0
	v_mul_f32_e32 v10, v9, v8
	v_fma_f32 v11, -v5, v10, v9
	v_fmac_f32_e32 v10, v11, v8
	v_fma_f32 v5, -v5, v10, v9
	v_div_fmas_f32 v5, v5, v8, v10
	v_div_fixup_f32 v8, v5, v4, 1.0
	v_lshl_add_u64 v[4:5], s[64:65], 0, v[2:3]
	v_lshl_add_u64 v[4:5], v[4:5], 0, s[12:13]
	v_lshl_add_u64 v[4:5], v[4:5], 0, v[72:73]
	v_mov_b32_e32 v9, v180
	v_lshl_add_u64 v[2:3], s[26:27], 0, v[2:3]
	v_mov_b32_e32 v4, v164
	v_mul_f32_e32 v5, v6, v8
	v_mul_f32_e32 v5, v49, v5
	v_lshl_add_u64 v[2:3], v[2:3], 0, s[12:13]
	v_lshl_add_u64 v[2:3], v[2:3], 0, v[72:73]
	s_nop 0
	v_lshlrev_b32_e32 v9, 16, v9
	v_mul_f32_e32 v6, 0xbfb8aa3b, v9
	v_exp_f32_e32 v6, v6
	s_nop 0
	v_lshlrev_b32_e32 v4, 16, v4
	v_mul_f32_e32 v4, 0xbfb8aa3b, v4
	v_exp_f32_e32 v4, v4
	v_add_f32_e32 v6, 1.0, v6
	v_div_scale_f32 v9, s[0:1], v6, v6, v5
	v_rcp_f32_e32 v10, v9
	v_add_f32_e32 v4, 1.0, v4
	v_fma_f32 v11, -v9, v10, 1.0
	v_fmac_f32_e32 v10, v11, v10
	v_div_scale_f32 v11, vcc, v5, v6, v5
	v_mul_f32_e32 v12, v11, v10
	v_fma_f32 v13, -v9, v12, v11
	v_fmac_f32_e32 v12, v13, v10
	v_fma_f32 v9, -v9, v12, v11
	v_div_fmas_f32 v9, v9, v10, v12
	v_div_fixup_f32 v5, v9, v6, v5
	v_bfe_u32 v6, v5, 16, 1
	v_add3_u32 v5, v5, v6, s66
	global_store_short_d16_hi v[2:3], v5, off offset:512
	v_mul_f32_e32 v5, v7, v8
	v_mul_f32_e32 v5, v47, v5
	v_div_scale_f32 v6, s[0:1], v4, v4, v5
	v_rcp_f32_e32 v7, v6
	s_nop 0
	v_fma_f32 v8, -v6, v7, 1.0
	v_fmac_f32_e32 v7, v8, v7
	v_div_scale_f32 v8, vcc, v5, v4, v5
	v_mul_f32_e32 v9, v8, v7
	v_fma_f32 v10, -v6, v9, v8
	v_fmac_f32_e32 v9, v10, v7
	v_fma_f32 v6, -v6, v9, v8
	v_div_fmas_f32 v6, v6, v7, v9
	v_div_fixup_f32 v4, v6, v4, v5
	v_bfe_u32 v5, v4, 16, 1
	v_add3_u32 v4, v4, v5, s66
	global_store_short_d16_hi v[2:3], v4, off offset:576
	v_mov_b32_e32 v3, s7
	v_or_b32_e32 v2, s6, v68
	v_lshlrev_b64 v[4:5], 9, v[2:3]
	v_lshl_add_u64 v[4:5], v[74:75], 0, v[4:5]
	v_mov_b32_e32 v6, v147
	v_lshlrev_b64 v[2:3], 11, v[2:3]
	v_mov_b32_e32 v4, v163
	s_nop 0
	v_lshlrev_b32_e32 v6, 16, v6
	v_add_f32_e32 v7, v17, v6
	s_nop 0
	v_lshlrev_b32_e32 v4, 16, v4
	v_add_f32_e32 v6, v33, v4
	v_mul_f32_e32 v4, v6, v6
	v_fmac_f32_e32 v4, v7, v7
	ds_bpermute_b32 v5, v35, v4
	s_waitcnt lgkmcnt(0)
	v_add_f32_e32 v4, v4, v5
	ds_bpermute_b32 v5, v37, v4
	s_waitcnt lgkmcnt(0)
	v_add_f32_e32 v4, v4, v5
	ds_bpermute_b32 v5, v41, v4
	s_waitcnt lgkmcnt(0)
	v_add_f32_e32 v4, v4, v5
	ds_bpermute_b32 v5, v43, v4
	s_waitcnt lgkmcnt(0)
	v_add_f32_e32 v4, v4, v5
	ds_bpermute_b32 v5, v45, v4
	s_waitcnt lgkmcnt(0)
	v_add_f32_e32 v4, v4, v5
	v_fmamk_f32 v4, v4, 0x3c800000, v1
	v_cmp_gt_f32_e32 vcc, s14, v4
	v_mul_f32_e32 v5, 0x4f800000, v4
	s_nop 0
	v_cndmask_b32_e32 v4, v4, v5, vcc
	v_sqrt_f32_e32 v5, v4
	s_nop 0
	v_add_u32_e32 v8, -1, v5
	v_fma_f32 v9, -v8, v5, v4
	v_cmp_ge_f32_e64 s[0:1], 0, v9
	v_add_u32_e32 v9, 1, v5
	s_nop 0
	v_cndmask_b32_e64 v8, v5, v8, s[0:1]
	v_fma_f32 v5, -v9, v5, v4
	v_cmp_lt_f32_e64 s[0:1], 0, v5
	s_nop 1
	v_cndmask_b32_e64 v5, v8, v9, s[0:1]
	v_mul_f32_e32 v8, 0x37800000, v5
	v_cndmask_b32_e32 v5, v5, v8, vcc
	v_cmp_class_f32_e32 vcc, v4, v223
	s_nop 1
	v_cndmask_b32_e32 v4, v5, v4, vcc
	v_div_scale_f32 v5, s[0:1], v4, v4, 1.0
	v_rcp_f32_e32 v8, v5
	s_nop 0
	v_fma_f32 v9, -v5, v8, 1.0
	v_fmac_f32_e32 v8, v9, v8
	v_div_scale_f32 v9, vcc, 1.0, v4, 1.0
	v_mul_f32_e32 v10, v9, v8
	v_fma_f32 v11, -v5, v10, v9
	v_fmac_f32_e32 v10, v11, v8
	v_fma_f32 v5, -v5, v10, v9
	v_div_fmas_f32 v5, v5, v8, v10
	v_div_fixup_f32 v8, v5, v4, 1.0
	v_lshl_add_u64 v[4:5], s[64:65], 0, v[2:3]
	v_lshl_add_u64 v[4:5], v[4:5], 0, s[12:13]
	v_lshl_add_u64 v[4:5], v[4:5], 0, v[72:73]
	v_mov_b32_e32 v9, v181
	v_lshl_add_u64 v[2:3], s[26:27], 0, v[2:3]
	v_mov_b32_e32 v4, v165
	v_mul_f32_e32 v5, v7, v8
	v_mul_f32_e32 v5, v49, v5
	v_lshl_add_u64 v[2:3], v[2:3], 0, s[12:13]
	v_lshl_add_u64 v[2:3], v[2:3], 0, v[72:73]
	s_nop 0
	v_lshlrev_b32_e32 v9, 16, v9
	v_mul_f32_e32 v7, 0xbfb8aa3b, v9
	v_exp_f32_e32 v7, v7
	s_nop 0
	v_lshlrev_b32_e32 v4, 16, v4
	v_mul_f32_e32 v4, 0xbfb8aa3b, v4
	v_exp_f32_e32 v4, v4
	v_add_f32_e32 v7, 1.0, v7
	v_div_scale_f32 v9, s[0:1], v7, v7, v5
	v_rcp_f32_e32 v10, v9
	v_add_f32_e32 v4, 1.0, v4
	v_fma_f32 v11, -v9, v10, 1.0
	v_fmac_f32_e32 v10, v11, v10
	v_div_scale_f32 v11, vcc, v5, v7, v5
	v_mul_f32_e32 v12, v11, v10
	v_fma_f32 v13, -v9, v12, v11
	v_fmac_f32_e32 v12, v13, v10
	v_fma_f32 v9, -v9, v12, v11
	v_div_fmas_f32 v9, v9, v10, v12
	v_div_fixup_f32 v5, v9, v7, v5
	v_bfe_u32 v7, v5, 16, 1
	v_add3_u32 v5, v5, v7, s66
	global_store_short_d16_hi v[2:3], v5, off offset:512
	v_mul_f32_e32 v5, v6, v8
	v_mul_f32_e32 v5, v47, v5
	v_div_scale_f32 v6, s[0:1], v4, v4, v5
	v_rcp_f32_e32 v7, v6
	s_nop 0
	v_fma_f32 v8, -v6, v7, 1.0
	v_fmac_f32_e32 v7, v8, v7
	v_div_scale_f32 v8, vcc, v5, v4, v5
	v_mul_f32_e32 v9, v8, v7
	v_fma_f32 v10, -v6, v9, v8
	v_fmac_f32_e32 v9, v10, v7
	v_fma_f32 v6, -v6, v9, v8
	v_div_fmas_f32 v6, v6, v7, v9
	v_div_fixup_f32 v4, v6, v4, v5
	v_bfe_u32 v5, v4, 16, 1
	v_add3_u32 v4, v4, v5, s66
	global_store_short_d16_hi v[2:3], v4, off offset:576
	s_cbranch_scc1 .LBB0_1059

; #define LAS __attribute__((address_space(3)))
; __device__ __forceinline__ void sdsa2_phase(const Grp& g, LAS unsigned char* shm, int G, int tid) {
;     ...
;         { const int n = tid >> 7, kg = (tid >> 4) & 7, d4 = tid & 15; const LAS float* p0 = P + (2 * n) * 256; const LAS float* p1 = p0 + 256; float4 a0 = make_float4(0.f, 0.f, 0.f, 0.f), a1 = a0;
; #pragma unroll 16
;           for (int jj = 0; jj < 32; ++jj) { const int j = kg * 32 + jj, jc = j < ns ? j : ns - 1; const int sr = sel[jc];
;               const float* vr = (sr & 0x40000000) ? g.AV + ((size_t)db * g.L + (sr & 0xffff)) * KVW : g.cache_v + (size_t)sr * KVW;
;               const float4 vv = *(const float4*)(vr + n * 64 + 4 * d4); const float w0 = p0[j], w1 = p1[j];
;               a0.x = fmaf(w0, vv.x, a0.x); a0.y = fmaf(w0, vv.y, a0.y); a0.z = fmaf(w0, vv.z, a0.z); a0.w = fmaf(w0, vv.w, a0.w); a1.x = fmaf(w1, vv.x, a1.x); a1.y = fmaf(w1, vv.y, a1.y); a1.z = fmaf(w1, vv.z, a1.z); a1.w = fmaf(w1, vv.w, a1.w); }
.LBB0_1221:
	v_add_u32_e32 v55, s2, v143
	v_mov_b32_e32 v51, s63
	v_mov_b32_e32 v52, s11
	v_mov_b32_e32 v53, s62
	v_mov_b32_e32 v54, s10
	v_mov_b32_e32 v88, v55
	v_min_i32_e32 v88, v88, v154
	v_lshl_add_u32 v88, v88, 2, 0
	ds_read_b32 v42, v88 offset:33024
	v_add_u32_e32 v88, 1, v55
	v_min_i32_e32 v88, v88, v154
	v_lshl_add_u32 v88, v88, 2, 0
	ds_read_b32 v43, v88 offset:33024
	v_add_u32_e32 v88, 2, v55
	v_min_i32_e32 v88, v88, v154
	v_lshl_add_u32 v88, v88, 2, 0
	ds_read_b32 v44, v88 offset:33024
	v_add_u32_e32 v88, 3, v55
	v_min_i32_e32 v88, v88, v154
	v_lshl_add_u32 v88, v88, 2, 0
	ds_read_b32 v45, v88 offset:33024
	v_add_u32_e32 v88, 4, v55
	v_min_i32_e32 v88, v88, v154
	v_lshl_add_u32 v88, v88, 2, 0
	ds_read_b32 v46, v88 offset:33024
	v_add_u32_e32 v88, 5, v55
	v_min_i32_e32 v88, v88, v154
	v_lshl_add_u32 v88, v88, 2, 0
	ds_read_b32 v47, v88 offset:33024
	v_add_u32_e32 v88, 6, v55
	v_min_i32_e32 v88, v88, v154
	v_lshl_add_u32 v88, v88, 2, 0
	ds_read_b32 v48, v88 offset:33024
	v_add_u32_e32 v88, 7, v55
	v_min_i32_e32 v88, v88, v154
	v_lshl_add_u32 v88, v88, 2, 0
	ds_read_b32 v49, v88 offset:33024
	ds_read_b128 v[22:25], v50
	ds_read_b128 v[26:29], v50 offset:16
	ds_read_b128 v[34:37], v50 offset:1024
	ds_read_b128 v[56:59], v50 offset:1040
	s_waitcnt lgkmcnt(4)
	v_and_b32_e32 v88, 2.0, v42
	v_cmp_eq_u32_e32 vcc, 0, v88
	v_and_b32_e32 v88, 0xffff, v42
	v_ashrrev_i32_e32 v91, 31, v42
	v_mov_b32_e32 v89, v215
	v_lshl_add_u64 v[88:89], s[0:1], 0, v[88:89]
	v_cndmask_b32_e32 v89, v89, v91, vcc
	v_cndmask_b32_e32 v88, v88, v42, vcc
	v_cndmask_b32_e32 v91, v51, v52, vcc
	v_cndmask_b32_e32 v90, v53, v54, vcc
	v_lshlrev_b64 v[88:89], 10, v[88:89]
	v_lshl_add_u64 v[88:89], v[90:91], 0, v[88:89]
	v_lshl_add_u64 v[88:89], v[88:89], 0, v[118:119]
	v_lshl_add_u64 v[88:89], v[88:89], 0, v[214:215]
	global_load_dwordx4 v[2:5], v[88:89], off
	v_and_b32_e32 v88, 2.0, v43
	v_cmp_eq_u32_e32 vcc, 0, v88
	v_and_b32_e32 v88, 0xffff, v43
	v_ashrrev_i32_e32 v91, 31, v43
	v_mov_b32_e32 v89, v215
	v_lshl_add_u64 v[88:89], s[0:1], 0, v[88:89]
	v_cndmask_b32_e32 v89, v89, v91, vcc
	v_cndmask_b32_e32 v88, v88, v43, vcc
	v_cndmask_b32_e32 v91, v51, v52, vcc
	v_cndmask_b32_e32 v90, v53, v54, vcc
	v_lshlrev_b64 v[88:89], 10, v[88:89]
	v_lshl_add_u64 v[88:89], v[90:91], 0, v[88:89]
	v_lshl_add_u64 v[88:89], v[88:89], 0, v[118:119]
	v_lshl_add_u64 v[88:89], v[88:89], 0, v[214:215]
	global_load_dwordx4 v[6:9], v[88:89], off
	v_and_b32_e32 v88, 2.0, v44
	v_cmp_eq_u32_e32 vcc, 0, v88
	v_and_b32_e32 v88, 0xffff, v44
	v_ashrrev_i32_e32 v91, 31, v44
	v_mov_b32_e32 v89, v215
	v_lshl_add_u64 v[88:89], s[0:1], 0, v[88:89]
	v_cndmask_b32_e32 v89, v89, v91, vcc
	v_cndmask_b32_e32 v88, v88, v44, vcc
	v_cndmask_b32_e32 v91, v51, v52, vcc
	v_cndmask_b32_e32 v90, v53, v54, vcc
	v_lshlrev_b64 v[88:89], 10, v[88:89]
	v_lshl_add_u64 v[88:89], v[90:91], 0, v[88:89]
	v_lshl_add_u64 v[88:89], v[88:89], 0, v[118:119]
	v_lshl_add_u64 v[88:89], v[88:89], 0, v[214:215]
	global_load_dwordx4 v[10:13], v[88:89], off
	v_and_b32_e32 v88, 2.0, v45
	v_cmp_eq_u32_e32 vcc, 0, v88
	v_and_b32_e32 v88, 0xffff, v45
	v_ashrrev_i32_e32 v91, 31, v45
	v_mov_b32_e32 v89, v215
	v_lshl_add_u64 v[88:89], s[0:1], 0, v[88:89]
	v_cndmask_b32_e32 v89, v89, v91, vcc
	v_cndmask_b32_e32 v88, v88, v45, vcc
	v_cndmask_b32_e32 v91, v51, v52, vcc
	v_cndmask_b32_e32 v90, v53, v54, vcc
	v_lshlrev_b64 v[88:89], 10, v[88:89]
	v_lshl_add_u64 v[88:89], v[90:91], 0, v[88:89]
	v_lshl_add_u64 v[88:89], v[88:89], 0, v[118:119]
	v_lshl_add_u64 v[88:89], v[88:89], 0, v[214:215]
	global_load_dwordx4 v[14:17], v[88:89], off
	v_and_b32_e32 v88, 2.0, v46
	v_cmp_eq_u32_e32 vcc, 0, v88
	v_and_b32_e32 v88, 0xffff, v46
	v_ashrrev_i32_e32 v91, 31, v46
	v_mov_b32_e32 v89, v215
	v_lshl_add_u64 v[88:89], s[0:1], 0, v[88:89]
	v_cndmask_b32_e32 v89, v89, v91, vcc
	v_cndmask_b32_e32 v88, v88, v46, vcc
	v_cndmask_b32_e32 v91, v51, v52, vcc
	v_cndmask_b32_e32 v90, v53, v54, vcc
	v_lshlrev_b64 v[88:89], 10, v[88:89]
	v_lshl_add_u64 v[88:89], v[90:91], 0, v[88:89]
	v_lshl_add_u64 v[88:89], v[88:89], 0, v[118:119]
	v_lshl_add_u64 v[88:89], v[88:89], 0, v[214:215]
	global_load_dwordx4 v[72:75], v[88:89], off
	v_and_b32_e32 v88, 2.0, v47
	v_cmp_eq_u32_e32 vcc, 0, v88
	v_and_b32_e32 v88, 0xffff, v47
	v_ashrrev_i32_e32 v91, 31, v47
	v_mov_b32_e32 v89, v215
	v_lshl_add_u64 v[88:89], s[0:1], 0, v[88:89]
	v_cndmask_b32_e32 v89, v89, v91, vcc
	v_cndmask_b32_e32 v88, v88, v47, vcc
	v_cndmask_b32_e32 v91, v51, v52, vcc
	v_cndmask_b32_e32 v90, v53, v54, vcc
	v_lshlrev_b64 v[88:89], 10, v[88:89]
	v_lshl_add_u64 v[88:89], v[90:91], 0, v[88:89]
	v_lshl_add_u64 v[88:89], v[88:89], 0, v[118:119]
	v_lshl_add_u64 v[88:89], v[88:89], 0, v[214:215]
	global_load_dwordx4 v[76:79], v[88:89], off
	v_and_b32_e32 v88, 2.0, v48
	v_cmp_eq_u32_e32 vcc, 0, v88
	v_and_b32_e32 v88, 0xffff, v48
	v_ashrrev_i32_e32 v91, 31, v48
	v_mov_b32_e32 v89, v215
	v_lshl_add_u64 v[88:89], s[0:1], 0, v[88:89]
	v_cndmask_b32_e32 v89, v89, v91, vcc
	v_cndmask_b32_e32 v88, v88, v48, vcc
	v_cndmask_b32_e32 v91, v51, v52, vcc
	v_cndmask_b32_e32 v90, v53, v54, vcc
	v_lshlrev_b64 v[88:89], 10, v[88:89]
	v_lshl_add_u64 v[88:89], v[90:91], 0, v[88:89]
	v_lshl_add_u64 v[88:89], v[88:89], 0, v[118:119]
	v_lshl_add_u64 v[88:89], v[88:89], 0, v[214:215]
	global_load_dwordx4 v[80:83], v[88:89], off
	v_and_b32_e32 v88, 2.0, v49
	v_cmp_eq_u32_e32 vcc, 0, v88
	v_and_b32_e32 v88, 0xffff, v49
	v_ashrrev_i32_e32 v91, 31, v49
	v_mov_b32_e32 v89, v215
	v_lshl_add_u64 v[88:89], s[0:1], 0, v[88:89]
	v_cndmask_b32_e32 v89, v89, v91, vcc
	v_cndmask_b32_e32 v88, v88, v49, vcc
	v_cndmask_b32_e32 v91, v51, v52, vcc
	v_cndmask_b32_e32 v90, v53, v54, vcc
	v_lshlrev_b64 v[88:89], 10, v[88:89]
	v_lshl_add_u64 v[88:89], v[90:91], 0, v[88:89]
	v_lshl_add_u64 v[88:89], v[88:89], 0, v[118:119]
	v_lshl_add_u64 v[88:89], v[88:89], 0, v[214:215]
	global_load_dwordx4 v[84:87], v[88:89], off
	s_waitcnt lgkmcnt(0)
; #define LAS __attribute__((address_space(3)))
; __device__ __forceinline__ void sdsa2_phase(const Grp& g, LAS unsigned char* shm, int G, int tid) {
;     ...
;         { const int n = tid >> 7, kg = (tid >> 4) & 7, d4 = tid & 15; const LAS float* p0 = P + (2 * n) * 256; const LAS float* p1 = p0 + 256; float4 a0 = make_float4(0.f, 0.f, 0.f, 0.f), a1 = a0;
; #pragma unroll 16
;           for (int jj = 0; jj < 32; ++jj) { const int j = kg * 32 + jj, jc = j < ns ? j : ns - 1; const int sr = sel[jc];
;               const float* vr = (sr & 0x40000000) ? g.AV + ((size_t)db * g.L + (sr & 0xffff)) * KVW : g.cache_v + (size_t)sr * KVW;
;               const float4 vv = *(const float4*)(vr + n * 64 + 4 * d4); const float w0 = p0[j], w1 = p1[j];
;               a0.x = fmaf(w0, vv.x, a0.x); a0.y = fmaf(w0, vv.y, a0.y); a0.z = fmaf(w0, vv.z, a0.z); a0.w = fmaf(w0, vv.w, a0.w); a1.x = fmaf(w1, vv.x, a1.x); a1.y = fmaf(w1, vv.y, a1.y); a1.z = fmaf(w1, vv.z, a1.z); a1.w = fmaf(w1, vv.w, a1.w); }
	s_waitcnt vmcnt(7)
	v_pk_fma_f32 v[30:31], v[22:23], v[2:3], v[30:31] op_sel_hi:[0,1,1]
	v_pk_fma_f32 v[32:33], v[22:23], v[4:5], v[32:33] op_sel_hi:[0,1,1]
	v_pk_fma_f32 v[38:39], v[34:35], v[2:3], v[38:39] op_sel_hi:[0,1,1]
	v_pk_fma_f32 v[40:41], v[34:35], v[4:5], v[40:41] op_sel_hi:[0,1,1]
	s_waitcnt vmcnt(6)
	v_pk_fma_f32 v[30:31], v[22:23], v[6:7], v[30:31] op_sel:[1,0,0]
	v_pk_fma_f32 v[32:33], v[22:23], v[8:9], v[32:33] op_sel:[1,0,0]
	v_pk_fma_f32 v[38:39], v[34:35], v[6:7], v[38:39] op_sel:[1,0,0]
	v_pk_fma_f32 v[40:41], v[34:35], v[8:9], v[40:41] op_sel:[1,0,0]
	s_waitcnt vmcnt(5)
	v_pk_fma_f32 v[30:31], v[24:25], v[10:11], v[30:31] op_sel_hi:[0,1,1]
	v_pk_fma_f32 v[32:33], v[24:25], v[12:13], v[32:33] op_sel_hi:[0,1,1]
	v_pk_fma_f32 v[38:39], v[36:37], v[10:11], v[38:39] op_sel_hi:[0,1,1]
	v_pk_fma_f32 v[40:41], v[36:37], v[12:13], v[40:41] op_sel_hi:[0,1,1]
	s_waitcnt vmcnt(4)
	v_pk_fma_f32 v[30:31], v[24:25], v[14:15], v[30:31] op_sel:[1,0,0]
	v_pk_fma_f32 v[32:33], v[24:25], v[16:17], v[32:33] op_sel:[1,0,0]
	v_pk_fma_f32 v[38:39], v[36:37], v[14:15], v[38:39] op_sel:[1,0,0]
	v_pk_fma_f32 v[40:41], v[36:37], v[16:17], v[40:41] op_sel:[1,0,0]
	s_waitcnt vmcnt(3)
	v_pk_fma_f32 v[30:31], v[26:27], v[72:73], v[30:31] op_sel_hi:[0,1,1]
	v_pk_fma_f32 v[32:33], v[26:27], v[74:75], v[32:33] op_sel_hi:[0,1,1]
	v_pk_fma_f32 v[38:39], v[56:57], v[72:73], v[38:39] op_sel_hi:[0,1,1]
	v_pk_fma_f32 v[40:41], v[56:57], v[74:75], v[40:41] op_sel_hi:[0,1,1]
	s_waitcnt vmcnt(2)
	v_pk_fma_f32 v[30:31], v[26:27], v[76:77], v[30:31] op_sel:[1,0,0]
	v_pk_fma_f32 v[32:33], v[26:27], v[78:79], v[32:33] op_sel:[1,0,0]
	v_pk_fma_f32 v[38:39], v[56:57], v[76:77], v[38:39] op_sel:[1,0,0]
	v_pk_fma_f32 v[40:41], v[56:57], v[78:79], v[40:41] op_sel:[1,0,0]
	s_waitcnt vmcnt(1)
	v_pk_fma_f32 v[30:31], v[28:29], v[80:81], v[30:31] op_sel_hi:[0,1,1]
	v_pk_fma_f32 v[32:33], v[28:29], v[82:83], v[32:33] op_sel_hi:[0,1,1]
	v_pk_fma_f32 v[38:39], v[58:59], v[80:81], v[38:39] op_sel_hi:[0,1,1]
	v_pk_fma_f32 v[40:41], v[58:59], v[82:83], v[40:41] op_sel_hi:[0,1,1]
	s_waitcnt vmcnt(0)
	v_pk_fma_f32 v[30:31], v[28:29], v[84:85], v[30:31] op_sel:[1,0,0]
	v_pk_fma_f32 v[32:33], v[28:29], v[86:87], v[32:33] op_sel:[1,0,0]
	v_pk_fma_f32 v[38:39], v[58:59], v[84:85], v[38:39] op_sel:[1,0,0]
	v_pk_fma_f32 v[40:41], v[58:59], v[86:87], v[40:41] op_sel:[1,0,0]
	v_add_u32_e32 v88, 8, v55
	v_min_i32_e32 v88, v88, v154
	v_lshl_add_u32 v88, v88, 2, 0
	ds_read_b32 v42, v88 offset:33024
	v_add_u32_e32 v88, 9, v55
	v_min_i32_e32 v88, v88, v154
	v_lshl_add_u32 v88, v88, 2, 0
	ds_read_b32 v43, v88 offset:33024
	v_add_u32_e32 v88, 10, v55
	v_min_i32_e32 v88, v88, v154
	v_lshl_add_u32 v88, v88, 2, 0
	ds_read_b32 v44, v88 offset:33024
	v_add_u32_e32 v88, 11, v55
	v_min_i32_e32 v88, v88, v154
	v_lshl_add_u32 v88, v88, 2, 0
	ds_read_b32 v45, v88 offset:33024
	v_add_u32_e32 v88, 12, v55
	v_min_i32_e32 v88, v88, v154
	v_lshl_add_u32 v88, v88, 2, 0
	ds_read_b32 v46, v88 offset:33024
	v_add_u32_e32 v88, 13, v55
	v_min_i32_e32 v88, v88, v154
	v_lshl_add_u32 v88, v88, 2, 0
	ds_read_b32 v47, v88 offset:33024
	v_add_u32_e32 v88, 14, v55
	v_min_i32_e32 v88, v88, v154
	v_lshl_add_u32 v88, v88, 2, 0
	ds_read_b32 v48, v88 offset:33024
	v_add_u32_e32 v88, 15, v55
	v_min_i32_e32 v88, v88, v154
	v_lshl_add_u32 v88, v88, 2, 0
	ds_read_b32 v49, v88 offset:33024
	ds_read_b128 v[22:25], v50 offset:32
	ds_read_b128 v[26:29], v50 offset:48
	ds_read_b128 v[34:37], v50 offset:1056
	ds_read_b128 v[56:59], v50 offset:1072
	s_waitcnt lgkmcnt(4)
	v_and_b32_e32 v88, 2.0, v42
	v_cmp_eq_u32_e32 vcc, 0, v88
	v_and_b32_e32 v88, 0xffff, v42
	v_ashrrev_i32_e32 v91, 31, v42
	v_mov_b32_e32 v89, v215
	v_lshl_add_u64 v[88:89], s[0:1], 0, v[88:89]
	v_cndmask_b32_e32 v89, v89, v91, vcc
	v_cndmask_b32_e32 v88, v88, v42, vcc
	v_cndmask_b32_e32 v91, v51, v52, vcc
	v_cndmask_b32_e32 v90, v53, v54, vcc
	v_lshlrev_b64 v[88:89], 10, v[88:89]
	v_lshl_add_u64 v[88:89], v[90:91], 0, v[88:89]
	v_lshl_add_u64 v[88:89], v[88:89], 0, v[118:119]
	v_lshl_add_u64 v[88:89], v[88:89], 0, v[214:215]
	global_load_dwordx4 v[2:5], v[88:89], off
	v_and_b32_e32 v88, 2.0, v43
	v_cmp_eq_u32_e32 vcc, 0, v88
	v_and_b32_e32 v88, 0xffff, v43
	v_ashrrev_i32_e32 v91, 31, v43
	v_mov_b32_e32 v89, v215
	v_lshl_add_u64 v[88:89], s[0:1], 0, v[88:89]
	v_cndmask_b32_e32 v89, v89, v91, vcc
	v_cndmask_b32_e32 v88, v88, v43, vcc
	v_cndmask_b32_e32 v91, v51, v52, vcc
	v_cndmask_b32_e32 v90, v53, v54, vcc
	v_lshlrev_b64 v[88:89], 10, v[88:89]
	v_lshl_add_u64 v[88:89], v[90:91], 0, v[88:89]
	v_lshl_add_u64 v[88:89], v[88:89], 0, v[118:119]
	v_lshl_add_u64 v[88:89], v[88:89], 0, v[214:215]
	global_load_dwordx4 v[6:9], v[88:89], off
	v_and_b32_e32 v88, 2.0, v44
	v_cmp_eq_u32_e32 vcc, 0, v88
	v_and_b32_e32 v88, 0xffff, v44
	v_ashrrev_i32_e32 v91, 31, v44
	v_mov_b32_e32 v89, v215
	v_lshl_add_u64 v[88:89], s[0:1], 0, v[88:89]
	v_cndmask_b32_e32 v89, v89, v91, vcc
	v_cndmask_b32_e32 v88, v88, v44, vcc
	v_cndmask_b32_e32 v91, v51, v52, vcc
	v_cndmask_b32_e32 v90, v53, v54, vcc
	v_lshlrev_b64 v[88:89], 10, v[88:89]
	v_lshl_add_u64 v[88:89], v[90:91], 0, v[88:89]
	v_lshl_add_u64 v[88:89], v[88:89], 0, v[118:119]
	v_lshl_add_u64 v[88:89], v[88:89], 0, v[214:215]
	global_load_dwordx4 v[10:13], v[88:89], off
	v_and_b32_e32 v88, 2.0, v45
	v_cmp_eq_u32_e32 vcc, 0, v88
	v_and_b32_e32 v88, 0xffff, v45
	v_ashrrev_i32_e32 v91, 31, v45
	v_mov_b32_e32 v89, v215
	v_lshl_add_u64 v[88:89], s[0:1], 0, v[88:89]
	v_cndmask_b32_e32 v89, v89, v91, vcc
	v_cndmask_b32_e32 v88, v88, v45, vcc
	v_cndmask_b32_e32 v91, v51, v52, vcc
	v_cndmask_b32_e32 v90, v53, v54, vcc
	v_lshlrev_b64 v[88:89], 10, v[88:89]
; #define LAS __attribute__((address_space(3)))
; __device__ __forceinline__ void sdsa2_phase(const Grp& g, LAS unsigned char* shm, int G, int tid) {
;     ...
;         { const int n = tid >> 7, kg = (tid >> 4) & 7, d4 = tid & 15; const LAS float* p0 = P + (2 * n) * 256; const LAS float* p1 = p0 + 256; float4 a0 = make_float4(0.f, 0.f, 0.f, 0.f), a1 = a0;
; #pragma unroll 16
;           for (int jj = 0; jj < 32; ++jj) { const int j = kg * 32 + jj, jc = j < ns ? j : ns - 1; const int sr = sel[jc];
;               const float* vr = (sr & 0x40000000) ? g.AV + ((size_t)db * g.L + (sr & 0xffff)) * KVW : g.cache_v + (size_t)sr * KVW;
;               const float4 vv = *(const float4*)(vr + n * 64 + 4 * d4); const float w0 = p0[j], w1 = p1[j];
;               a0.x = fmaf(w0, vv.x, a0.x); a0.y = fmaf(w0, vv.y, a0.y); a0.z = fmaf(w0, vv.z, a0.z); a0.w = fmaf(w0, vv.w, a0.w); a1.x = fmaf(w1, vv.x, a1.x); a1.y = fmaf(w1, vv.y, a1.y); a1.z = fmaf(w1, vv.z, a1.z); a1.w = fmaf(w1, vv.w, a1.w); }
;           *(LAS f32x4*)(red + (kg * 8 + 2 * n) * 64 + 4 * d4) = (f32x4){a0.x, a0.y, a0.z, a0.w}; *(LAS f32x4*)(red + (kg * 8 + 2 * n + 1) * 64 + 4 * d4) = (f32x4){a1.x, a1.y, a1.z, a1.w}; }
;         __syncthreads();
;         { float o = 0.f;
; #pragma unroll
;           for (int kg = 0; kg < 8; ++kg) o += red[kg * 512 + tid];
;           g.YCAT[(size_t)row * D + 512 + tid] = o; }
	v_lshl_add_u64 v[88:89], v[90:91], 0, v[88:89]
	v_lshl_add_u64 v[88:89], v[88:89], 0, v[118:119]
	v_lshl_add_u64 v[88:89], v[88:89], 0, v[214:215]
	global_load_dwordx4 v[14:17], v[88:89], off
	v_and_b32_e32 v88, 2.0, v46
	v_cmp_eq_u32_e32 vcc, 0, v88
	v_and_b32_e32 v88, 0xffff, v46
	v_ashrrev_i32_e32 v91, 31, v46
	v_mov_b32_e32 v89, v215
	v_lshl_add_u64 v[88:89], s[0:1], 0, v[88:89]
	v_cndmask_b32_e32 v89, v89, v91, vcc
	v_cndmask_b32_e32 v88, v88, v46, vcc
	v_cndmask_b32_e32 v91, v51, v52, vcc
	v_cndmask_b32_e32 v90, v53, v54, vcc
	v_lshlrev_b64 v[88:89], 10, v[88:89]
	v_lshl_add_u64 v[88:89], v[90:91], 0, v[88:89]
	v_lshl_add_u64 v[88:89], v[88:89], 0, v[118:119]
	v_lshl_add_u64 v[88:89], v[88:89], 0, v[214:215]
	global_load_dwordx4 v[72:75], v[88:89], off
	v_and_b32_e32 v88, 2.0, v47
	v_cmp_eq_u32_e32 vcc, 0, v88
	v_and_b32_e32 v88, 0xffff, v47
	v_ashrrev_i32_e32 v91, 31, v47
	v_mov_b32_e32 v89, v215
	v_lshl_add_u64 v[88:89], s[0:1], 0, v[88:89]
	v_cndmask_b32_e32 v89, v89, v91, vcc
	v_cndmask_b32_e32 v88, v88, v47, vcc
	v_cndmask_b32_e32 v91, v51, v52, vcc
	v_cndmask_b32_e32 v90, v53, v54, vcc
	v_lshlrev_b64 v[88:89], 10, v[88:89]
	v_lshl_add_u64 v[88:89], v[90:91], 0, v[88:89]
	v_lshl_add_u64 v[88:89], v[88:89], 0, v[118:119]
	v_lshl_add_u64 v[88:89], v[88:89], 0, v[214:215]
	global_load_dwordx4 v[76:79], v[88:89], off
	v_and_b32_e32 v88, 2.0, v48
	v_cmp_eq_u32_e32 vcc, 0, v88
	v_and_b32_e32 v88, 0xffff, v48
	v_ashrrev_i32_e32 v91, 31, v48
	v_mov_b32_e32 v89, v215
	v_lshl_add_u64 v[88:89], s[0:1], 0, v[88:89]
	v_cndmask_b32_e32 v89, v89, v91, vcc
	v_cndmask_b32_e32 v88, v88, v48, vcc
	v_cndmask_b32_e32 v91, v51, v52, vcc
	v_cndmask_b32_e32 v90, v53, v54, vcc
	v_lshlrev_b64 v[88:89], 10, v[88:89]
	v_lshl_add_u64 v[88:89], v[90:91], 0, v[88:89]
	v_lshl_add_u64 v[88:89], v[88:89], 0, v[118:119]
	v_lshl_add_u64 v[88:89], v[88:89], 0, v[214:215]
	global_load_dwordx4 v[80:83], v[88:89], off
	v_and_b32_e32 v88, 2.0, v49
	v_cmp_eq_u32_e32 vcc, 0, v88
	v_and_b32_e32 v88, 0xffff, v49
	v_ashrrev_i32_e32 v91, 31, v49
	v_mov_b32_e32 v89, v215
	v_lshl_add_u64 v[88:89], s[0:1], 0, v[88:89]
	v_cndmask_b32_e32 v89, v89, v91, vcc
	v_cndmask_b32_e32 v88, v88, v49, vcc
	v_cndmask_b32_e32 v91, v51, v52, vcc
	v_cndmask_b32_e32 v90, v53, v54, vcc
	v_lshlrev_b64 v[88:89], 10, v[88:89]
	v_lshl_add_u64 v[88:89], v[90:91], 0, v[88:89]
	v_lshl_add_u64 v[88:89], v[88:89], 0, v[118:119]
	v_lshl_add_u64 v[88:89], v[88:89], 0, v[214:215]
	global_load_dwordx4 v[84:87], v[88:89], off
	s_waitcnt lgkmcnt(0)
	s_waitcnt vmcnt(7)
	v_pk_fma_f32 v[30:31], v[22:23], v[2:3], v[30:31] op_sel_hi:[0,1,1]
	v_pk_fma_f32 v[32:33], v[22:23], v[4:5], v[32:33] op_sel_hi:[0,1,1]
	v_pk_fma_f32 v[38:39], v[34:35], v[2:3], v[38:39] op_sel_hi:[0,1,1]
	v_pk_fma_f32 v[40:41], v[34:35], v[4:5], v[40:41] op_sel_hi:[0,1,1]
	s_waitcnt vmcnt(6)
	v_pk_fma_f32 v[30:31], v[22:23], v[6:7], v[30:31] op_sel:[1,0,0]
	v_pk_fma_f32 v[32:33], v[22:23], v[8:9], v[32:33] op_sel:[1,0,0]
	v_pk_fma_f32 v[38:39], v[34:35], v[6:7], v[38:39] op_sel:[1,0,0]
	v_pk_fma_f32 v[40:41], v[34:35], v[8:9], v[40:41] op_sel:[1,0,0]
	s_waitcnt vmcnt(5)
	v_pk_fma_f32 v[30:31], v[24:25], v[10:11], v[30:31] op_sel_hi:[0,1,1]
	v_pk_fma_f32 v[32:33], v[24:25], v[12:13], v[32:33] op_sel_hi:[0,1,1]
	v_pk_fma_f32 v[38:39], v[36:37], v[10:11], v[38:39] op_sel_hi:[0,1,1]
	v_pk_fma_f32 v[40:41], v[36:37], v[12:13], v[40:41] op_sel_hi:[0,1,1]
	s_waitcnt vmcnt(4)
	v_pk_fma_f32 v[30:31], v[24:25], v[14:15], v[30:31] op_sel:[1,0,0]
	v_pk_fma_f32 v[32:33], v[24:25], v[16:17], v[32:33] op_sel:[1,0,0]
	v_pk_fma_f32 v[38:39], v[36:37], v[14:15], v[38:39] op_sel:[1,0,0]
	v_pk_fma_f32 v[40:41], v[36:37], v[16:17], v[40:41] op_sel:[1,0,0]
	s_waitcnt vmcnt(3)
	v_pk_fma_f32 v[30:31], v[26:27], v[72:73], v[30:31] op_sel_hi:[0,1,1]
	v_pk_fma_f32 v[32:33], v[26:27], v[74:75], v[32:33] op_sel_hi:[0,1,1]
	v_pk_fma_f32 v[38:39], v[56:57], v[72:73], v[38:39] op_sel_hi:[0,1,1]
	v_pk_fma_f32 v[40:41], v[56:57], v[74:75], v[40:41] op_sel_hi:[0,1,1]
	s_waitcnt vmcnt(2)
	v_pk_fma_f32 v[30:31], v[26:27], v[76:77], v[30:31] op_sel:[1,0,0]
	v_pk_fma_f32 v[32:33], v[26:27], v[78:79], v[32:33] op_sel:[1,0,0]
	v_pk_fma_f32 v[38:39], v[56:57], v[76:77], v[38:39] op_sel:[1,0,0]
	v_pk_fma_f32 v[40:41], v[56:57], v[78:79], v[40:41] op_sel:[1,0,0]
	s_waitcnt vmcnt(1)
	v_pk_fma_f32 v[30:31], v[28:29], v[80:81], v[30:31] op_sel_hi:[0,1,1]
	v_pk_fma_f32 v[32:33], v[28:29], v[82:83], v[32:33] op_sel_hi:[0,1,1]
	v_pk_fma_f32 v[38:39], v[58:59], v[80:81], v[38:39] op_sel_hi:[0,1,1]
	v_pk_fma_f32 v[40:41], v[58:59], v[82:83], v[40:41] op_sel_hi:[0,1,1]
	s_waitcnt vmcnt(0)
	v_pk_fma_f32 v[30:31], v[28:29], v[84:85], v[30:31] op_sel:[1,0,0]
	v_pk_fma_f32 v[32:33], v[28:29], v[86:87], v[32:33] op_sel:[1,0,0]
	v_pk_fma_f32 v[38:39], v[58:59], v[84:85], v[38:39] op_sel:[1,0,0]
	v_pk_fma_f32 v[40:41], v[58:59], v[86:87], v[40:41] op_sel:[1,0,0]
	v_add_u32_e32 v50, 64, v50
	s_add_i32 s2, s2, 16
	s_cmp_eq_u32 s2, 32
	s_cbranch_scc0 .LBB0_1221
	v_add_u32_e32 v28, 64, v120
	ds_write_b128 v144, v[30:33] offset:46400
	ds_write_b128 v144, v[38:41] offset:46656
	s_waitcnt lgkmcnt(0)
	s_barrier
	ds_read2st64_b32 v[22:23], v28 offset0:181 offset1:189
	ds_read2st64_b32 v[24:25], v28 offset0:197 offset1:205
	ds_read2st64_b32 v[26:27], v28 offset0:213 offset1:221
	v_readlane_b32 s52, v249, 4
	s_lshl_b64 s[0:1], s[6:7], 12
	s_waitcnt lgkmcnt(2)
	v_add_f32_e32 v22, 0, v22
	v_add_f32_e32 v29, v22, v23
	ds_read2st64_b32 v[22:23], v28 offset0:229 offset1:237
	s_waitcnt lgkmcnt(2)
	v_add_f32_e32 v24, v29, v24
	v_add_f32_e32 v24, v24, v25
	s_waitcnt lgkmcnt(1)
	v_add_f32_e32 v24, v24, v26
	v_readlane_b32 s54, v249, 6
	v_add_f32_e32 v24, v24, v27
	v_readlane_b32 s55, v249, 7
	s_add_u32 s0, s54, s0
	s_waitcnt lgkmcnt(0)
	v_add_f32_e32 v22, v24, v22
	s_addc_u32 s1, s55, s1
	v_add_f32_e32 v24, v22, v23
	v_lshl_add_u64 v[22:23], v[102:103], 2, s[0:1]
	v_add_co_u32_e32 v22, vcc, 0x5789d000, v22
	s_add_i32 s6, s6, s68
	s_nop 0
	v_addc_co_u32_e32 v23, vcc, 0, v23, vcc
	s_cmpk_gt_i32 s6, 0xff
	v_readlane_b32 s53, v249, 5
	global_store_dword v[22:23], v24, off offset:2048
	s_barrier
	s_cbranch_scc0 .LBB0_1090
	v_readlane_b32 s70, v250, 14
	v_readlane_b32 s76, v254, 15
	v_readlane_b32 s71, v250, 15
	v_readlane_b32 s72, v254, 23
	v_readlane_b32 s74, v254, 25
	v_readlane_b32 s78, v254, 27
	v_readlane_b32 s80, v254, 29
	v_readlane_b32 s82, v254, 31
	v_readlane_b32 s84, v254, 33
	v_readlane_b32 s94, v254, 35
	v_readlane_b32 s96, v254, 37
	v_readlane_b32 s44, v254, 11
	v_readlane_b32 s77, v254, 16
	v_readlane_b32 s71, v254, 22
	v_readlane_b32 s73, v254, 24
	v_readlane_b32 s75, v254, 26
	v_readlane_b32 s79, v254, 28
	v_readlane_b32 s81, v254, 30
	v_readlane_b32 s83, v254, 32
	v_readlane_b32 s85, v254, 34
	v_readlane_b32 s95, v254, 36
	v_readlane_b32 s97, v254, 38
	v_readlane_b32 s45, v254, 12
	v_readlane_b32 s46, v254, 13
	v_readlane_b32 s47, v254, 14
